# baseline (speedup 1.0000x reference)
.LBB0_347:
	s_or_b64 exec, exec, s[90:91]
	v_mov_b32_e32 v0, v180
	s_waitcnt lgkmcnt(0)
	s_barrier
	s_nop 0
	v_cmp_gt_i32_e32 vcc, s56, v0
	s_and_saveexec_b64 s[90:91], vcc
	s_cbranch_execz .LBB0_349
	v_ashrrev_i32_e32 v5, 31, v0
	v_add_u32_sdwa v5, v0, v5 dst_sel:DWORD dst_unused:UNUSED_PAD src0_sel:DWORD src1_sel:BYTE_3
	v_ashrrev_i32_e32 v5, 8, v5
	v_mul_i32_i24_e32 v7, 0x100, v5
	v_sub_u32_e32 v0, v0, v7
	v_mul_i32_i24_e32 v5, 0x1100, v5
	v_lshlrev_b32_e32 v5, 3, v5
	v_ashrrev_i32_e32 v13, 4, v0
	v_add_u32_e32 v7, 0, v5
	v_lshlrev_b32_e32 v11, 3, v0
	v_lshlrev_b32_e32 v13, 3, v13
	v_add3_u32 v7, v7, v11, v13
	ds_read_b64 v[26:27], v7 offset:6272
	ds_read_b64 v[28:29], v7 offset:8448
	ds_read_b64 v[82:83], v7 offset:10624
	ds_read_b64 v[96:97], v7 offset:12800
	ds_read_b64 v[106:107], v7 offset:14976
	ds_read_b64 v[108:109], v7 offset:17152
	ds_read_b64 v[110:111], v7 offset:19328
	ds_read_b64 v[114:115], v7 offset:21504
	ds_read_b64 v[116:117], v7 offset:23680
	ds_read_b64 v[118:119], v7 offset:25856
	ds_read_b64 v[120:121], v7 offset:28032
	ds_read_b64 v[122:123], v7 offset:30208
	ds_read_b64 v[124:125], v7 offset:32384
	ds_read_b64 v[126:127], v7 offset:34560
	ds_read_b64 v[128:129], v7 offset:36736
	ds_read_b64 v[130:131], v7 offset:38912
	s_waitcnt lgkmcnt(7)
	v_pk_add_f32 v[132:133], v[26:27], v[116:117]
	v_pk_add_f32 v[26:27], v[26:27], v[116:117] neg_lo:[0,1] neg_hi:[0,1]
	s_waitcnt lgkmcnt(3)
	v_pk_add_f32 v[116:117], v[106:107], v[124:125]
	v_pk_add_f32 v[106:107], v[106:107], v[124:125] neg_lo:[0,1] neg_hi:[0,1]
	s_mov_b32 s61, s34
	v_pk_add_f32 v[134:135], v[26:27], v[106:107] op_sel:[0,1] op_sel_hi:[1,0] neg_hi:[0,1]
	v_pk_add_f32 v[26:27], v[26:27], v[106:107] op_sel:[0,1] op_sel_hi:[1,0] neg_lo:[0,1]
	v_pk_add_f32 v[124:125], v[28:29], v[118:119]
	v_pk_add_f32 v[28:29], v[28:29], v[118:119] neg_lo:[0,1] neg_hi:[0,1]
	s_waitcnt lgkmcnt(2)
	v_pk_add_f32 v[118:119], v[108:109], v[126:127]
	v_pk_add_f32 v[108:109], v[108:109], v[126:127] neg_lo:[0,1] neg_hi:[0,1]
	v_pk_add_f32 v[106:107], v[132:133], v[116:117]
	v_xor_b32_e32 v127, 0x80000000, v108
	v_mov_b32_e32 v126, v109
	v_pk_add_f32 v[108:109], v[124:125], v[118:119]
	v_pk_add_f32 v[118:119], v[124:125], v[118:119] neg_lo:[0,1] neg_hi:[0,1]
	v_pk_add_f32 v[124:125], v[82:83], v[120:121]
	v_pk_add_f32 v[82:83], v[82:83], v[120:121] neg_lo:[0,1] neg_hi:[0,1]
	s_waitcnt lgkmcnt(1)
	v_pk_add_f32 v[120:121], v[110:111], v[128:129]
	v_pk_add_f32 v[110:111], v[110:111], v[128:129] neg_lo:[0,1] neg_hi:[0,1]
	v_pk_add_f32 v[116:117], v[132:133], v[116:117] neg_lo:[0,1] neg_hi:[0,1]
	v_pk_add_f32 v[132:133], v[28:29], v[126:127]
	v_pk_add_f32 v[28:29], v[28:29], v[126:127] neg_lo:[0,1] neg_hi:[0,1]
	v_xor_b32_e32 v127, 0x80000000, v110
	v_mov_b32_e32 v126, v111
	v_pk_add_f32 v[110:111], v[124:125], v[120:121]
	v_pk_add_f32 v[120:121], v[124:125], v[120:121] neg_lo:[0,1] neg_hi:[0,1]
	v_pk_add_f32 v[124:125], v[96:97], v[122:123]
	v_pk_add_f32 v[96:97], v[96:97], v[122:123] neg_lo:[0,1] neg_hi:[0,1]
	s_waitcnt lgkmcnt(0)
	v_pk_add_f32 v[122:123], v[114:115], v[130:131]
	v_pk_add_f32 v[114:115], v[114:115], v[130:131] neg_lo:[0,1] neg_hi:[0,1]
	v_pk_add_f32 v[128:129], v[82:83], v[126:127]
	v_pk_add_f32 v[82:83], v[82:83], v[126:127] neg_lo:[0,1] neg_hi:[0,1]
	v_xor_b32_e32 v127, 0x80000000, v114
	v_mov_b32_e32 v126, v115
	v_pk_add_f32 v[114:115], v[124:125], v[122:123]
	v_pk_add_f32 v[122:123], v[124:125], v[122:123] neg_lo:[0,1] neg_hi:[0,1]
	v_pk_mul_f32 v[124:125], v[132:133], s[24:25] op_sel_hi:[1,0]
	v_pk_add_f32 v[130:131], v[96:97], v[126:127]
	v_pk_add_f32 v[96:97], v[96:97], v[126:127] neg_lo:[0,1] neg_hi:[0,1]
	v_pk_fma_f32 v[126:127], v[132:133], s[26:27], v[124:125] op_sel:[0,0,1] op_sel_hi:[1,0,0] neg_hi:[0,0,1]
	s_mov_b32 s35, s24
	v_pk_mul_f32 v[124:125], v[118:119], s[28:29] op_sel_hi:[1,0]
	v_add_u32_e32 v5, s57, v5
	v_pk_fma_f32 v[132:133], v[118:119], s[28:29], v[124:125] op_sel:[0,0,1] op_sel_hi:[1,0,0] neg_hi:[0,0,1]
	v_pk_mul_f32 v[124:125], v[28:29], s[26:27] op_sel_hi:[1,0]
	v_pk_fma_f32 v[136:137], v[28:29], s[24:25], v[124:125] op_sel:[0,0,1] op_sel_hi:[1,0,0] neg_hi:[0,0,1]
	v_lshlrev_b32_e32 v0, 7, v0
	v_pk_mul_f32 v[28:29], v[128:129], s[28:29] op_sel_hi:[1,0]
	v_add3_u32 v0, v5, v0, v11
	v_pk_fma_f32 v[124:125], v[128:129], s[28:29], v[28:29] op_sel:[0,0,1] op_sel_hi:[1,0,0] neg_hi:[0,0,1]
	s_nop 0
	v_pk_fma_f32 v[28:29], v[120:121], 0, v[120:121] op_sel:[0,0,1] op_sel_hi:[1,0,0] neg_hi:[0,0,1]
	s_nop 0
	v_pk_mul_f32 v[120:121], v[82:83], s[30:31] op_sel_hi:[1,0]
	s_nop 0
	v_pk_fma_f32 v[128:129], v[82:83], s[30:31], v[120:121] op_sel:[0,0,1] op_sel_hi:[1,0,0] neg_lo:[0,0,1]
	v_pk_mul_f32 v[120:121], v[130:131], s[26:27] op_sel_hi:[1,0]
	v_pk_fma_f32 v[138:139], v[130:131], s[24:25], v[120:121] op_sel:[0,0,1] op_sel_hi:[1,0,0] neg_hi:[0,0,1]
	v_pk_add_f32 v[82:83], v[26:27], v[128:129]
	v_pk_mul_f32 v[120:121], v[122:123], s[30:31] op_sel_hi:[1,0]
	v_pk_add_f32 v[26:27], v[26:27], v[128:129] neg_lo:[0,1] neg_hi:[0,1]
	v_pk_fma_f32 v[130:131], v[122:123], s[30:31], v[120:121] op_sel:[0,0,1] op_sel_hi:[1,0,0] neg_lo:[0,0,1]
	s_nop 0
	v_pk_mul_f32 v[120:121], v[96:97], s[60:61] op_sel:[1,0]
	v_pk_add_f32 v[118:119], v[132:133], v[130:131] neg_lo:[0,1] neg_hi:[0,1]
	v_pk_fma_f32 v[96:97], v[96:97], s[34:35], v[120:121] op_sel_hi:[0,1,1]
	v_pk_add_f32 v[120:121], v[106:107], v[110:111]
	v_pk_add_f32 v[106:107], v[106:107], v[110:111] neg_lo:[0,1] neg_hi:[0,1]
	v_pk_add_f32 v[110:111], v[108:109], v[114:115]
	v_pk_add_f32 v[108:109], v[108:109], v[114:115] neg_lo:[0,1] neg_hi:[0,1]
	s_nop 0
	v_xor_b32_e32 v115, 0x80000000, v108
	v_mov_b32_e32 v114, v109
	v_pk_add_f32 v[108:109], v[120:121], v[110:111]
	v_pk_add_f32 v[122:123], v[106:107], v[114:115]
	v_pk_add_f32 v[110:111], v[120:121], v[110:111] neg_lo:[0,1] neg_hi:[0,1]
	v_pk_add_f32 v[106:107], v[106:107], v[114:115] neg_lo:[0,1] neg_hi:[0,1]
	v_pk_add_f32 v[114:115], v[134:135], v[124:125]
	v_pk_add_f32 v[120:121], v[134:135], v[124:125] neg_lo:[0,1] neg_hi:[0,1]
	v_pk_add_f32 v[124:125], v[126:127], v[138:139]
	v_pk_add_f32 v[126:127], v[126:127], v[138:139] neg_lo:[0,1] neg_hi:[0,1]
	s_nop 0
	v_xor_b32_e32 v135, 0x80000000, v126
	v_mov_b32_e32 v134, v127
	v_pk_add_f32 v[126:127], v[114:115], v[124:125]
	v_pk_add_f32 v[114:115], v[114:115], v[124:125] neg_lo:[0,1] neg_hi:[0,1]
	v_pk_add_f32 v[124:125], v[116:117], v[28:29]
	v_pk_add_f32 v[28:29], v[116:117], v[28:29] neg_lo:[0,1] neg_hi:[0,1]
	v_pk_add_f32 v[116:117], v[132:133], v[130:131]
	v_xor_b32_e32 v131, 0x80000000, v118
	v_mov_b32_e32 v130, v119
	v_pk_add_f32 v[118:119], v[124:125], v[116:117]
	v_pk_add_f32 v[116:117], v[124:125], v[116:117] neg_lo:[0,1] neg_hi:[0,1]
	v_pk_add_f32 v[124:125], v[136:137], v[96:97]
	v_pk_add_f32 v[96:97], v[136:137], v[96:97] neg_lo:[0,1] neg_hi:[0,1]
	v_pk_add_f32 v[138:139], v[120:121], v[134:135]
	v_xor_b32_e32 v129, 0x80000000, v96
	v_mov_b32_e32 v128, v97
	v_pk_add_f32 v[120:121], v[120:121], v[134:135] neg_lo:[0,1] neg_hi:[0,1]
	v_pk_add_f32 v[132:133], v[28:29], v[130:131]
	v_pk_add_f32 v[28:29], v[28:29], v[130:131] neg_lo:[0,1] neg_hi:[0,1]
	v_pk_add_f32 v[96:97], v[82:83], v[124:125]
	v_pk_add_f32 v[130:131], v[26:27], v[128:129]
	v_pk_add_f32 v[82:83], v[82:83], v[124:125] neg_lo:[0,1] neg_hi:[0,1]
	v_pk_add_f32 v[26:27], v[26:27], v[128:129] neg_lo:[0,1] neg_hi:[0,1]
	ds_write2_b64 v0, v[108:109], v[126:127] offset1:1
	ds_write2_b64 v0, v[118:119], v[96:97] offset0:2 offset1:3
	ds_write2_b64 v0, v[122:123], v[138:139] offset0:4 offset1:5
	ds_write2_b64 v0, v[132:133], v[130:131] offset0:6 offset1:7
	ds_write2_b64 v0, v[110:111], v[114:115] offset0:8 offset1:9
	ds_write2_b64 v0, v[116:117], v[82:83] offset0:10 offset1:11
	ds_write2_b64 v0, v[106:107], v[120:121] offset0:12 offset1:13
	ds_write2_b64 v0, v[28:29], v[26:27] offset0:14 offset1:15

.LBB0_351:
	s_or_b64 exec, exec, s[90:91]
	v_mov_b32_e32 v0, v180
	s_waitcnt lgkmcnt(0)
	s_barrier
	s_nop 0
	v_cmp_gt_i32_e32 vcc, s56, v0
	s_and_saveexec_b64 s[90:91], vcc
	s_cbranch_execz .LBB0_353
	v_ashrrev_i32_e32 v5, 31, v0
	v_add_u32_sdwa v5, v0, v5 dst_sel:DWORD dst_unused:UNUSED_PAD src0_sel:DWORD src1_sel:BYTE_3
	v_ashrrev_i32_e32 v5, 8, v5
	v_mul_i32_i24_e32 v7, 0x100, v5
	v_sub_u32_e32 v0, v0, v7
	v_mul_i32_i24_e32 v5, 0x1100, v5
	v_lshlrev_b32_e32 v7, 3, v0
	v_ashrrev_i32_e32 v0, 4, v0
	v_lshlrev_b32_e32 v5, 3, v5
	v_lshlrev_b32_e32 v0, 3, v0
	v_add_u32_e32 v11, 0, v7
	v_add3_u32 v13, v11, v5, v0
	ds_read_b64 v[26:27], v13 offset:6272
	ds_read_b64 v[28:29], v13 offset:8448
	ds_read_b64 v[82:83], v13 offset:10624
	ds_read_b64 v[96:97], v13 offset:12800
	ds_read_b64 v[106:107], v13 offset:14976
	ds_read_b64 v[108:109], v13 offset:17152
	ds_read_b64 v[110:111], v13 offset:19328
	ds_read_b64 v[114:115], v13 offset:21504
	ds_read_b64 v[116:117], v13 offset:34560
	ds_read_b64 v[118:119], v13 offset:36736
	ds_read_b64 v[120:121], v13 offset:38912
	ds_read_b64 v[122:123], v11
	ds_read_b64 v[124:125], v13 offset:23680
	ds_read_b64 v[126:127], v13 offset:25856
	ds_read_b64 v[128:129], v13 offset:28032
	ds_read_b64 v[130:131], v13 offset:30208
	ds_read_b64 v[132:133], v13 offset:32384
	s_waitcnt lgkmcnt(5)
	v_pk_mul_f32 v[134:135], v[28:29], v[122:123] op_sel:[1,1] op_sel_hi:[1,0]
	s_mov_b32 s61, s34
	v_pk_fma_f32 v[136:137], v[28:29], v[122:123], v[134:135] op_sel_hi:[0,1,1] neg_lo:[0,0,1]
	v_pk_mul_f32 v[28:29], v[122:123], v[122:123] op_sel:[1,1] op_sel_hi:[1,0]
	s_mov_b32 s35, s24
	v_pk_fma_f32 v[134:135], v[122:123], v[122:123], v[28:29] op_sel_hi:[1,0,1] neg_lo:[0,0,1] neg_hi:[0,0,1]
	v_pk_fma_f32 v[28:29], v[122:123], v[122:123], v[28:29] op_sel_hi:[1,0,1]
	v_mov_b32_e32 v138, v134
	v_mov_b32_e32 v139, v29
	v_pk_mul_f32 v[28:29], v[82:83], v[28:29] op_sel:[1,1] op_sel_hi:[0,1]
	v_pk_fma_f32 v[140:141], v[82:83], v[134:135], v[28:29] op_sel_hi:[1,0,1] neg_lo:[0,0,1]
	v_pk_mul_f32 v[82:83], v[122:123], v[138:139] op_sel:[1,0] op_sel_hi:[0,1]
	v_pk_mul_f32 v[28:29], v[122:123], v[138:139]
	v_pk_add_f32 v[82:83], v[82:83], v[82:83] op_sel:[0,1] op_sel_hi:[0,1]
	v_pk_mul_f32 v[134:135], v[96:97], v[82:83]
	v_pk_add_f32 v[28:29], v[28:29], v[28:29] op_sel:[0,1] op_sel_hi:[0,1] neg_lo:[0,1] neg_hi:[0,1]
	v_pk_fma_f32 v[138:139], v[96:97], v[28:29], v[134:135] op_sel:[0,0,1] op_sel_hi:[1,1,0] neg_lo:[0,0,1]
	v_pk_mul_f32 v[82:83], v[122:123], v[82:83]
	v_pk_fma_f32 v[96:97], v[122:123], v[28:29], v[82:83] op_sel:[0,0,1] op_sel_hi:[1,1,0] neg_lo:[0,0,1] neg_hi:[0,0,1]
	v_pk_fma_f32 v[28:29], v[122:123], v[28:29], v[82:83] op_sel:[0,0,1] op_sel_hi:[1,1,0]
	v_mov_b32_e32 v82, v96
	v_mov_b32_e32 v83, v29
	v_pk_mul_f32 v[28:29], v[106:107], v[28:29] op_sel:[1,1] op_sel_hi:[0,1]
	v_pk_fma_f32 v[134:135], v[106:107], v[96:97], v[28:29] op_sel_hi:[1,0,1] neg_lo:[0,0,1]
	v_add_u32_e32 v5, s57, v5
	v_pk_mul_f32 v[28:29], v[122:123], v[82:83]
	v_pk_mul_f32 v[82:83], v[122:123], v[82:83] op_sel:[1,0] op_sel_hi:[0,1]
	v_pk_add_f32 v[82:83], v[82:83], v[82:83] op_sel:[0,1] op_sel_hi:[0,1]
	v_pk_mul_f32 v[96:97], v[108:109], v[82:83]
	v_pk_add_f32 v[28:29], v[28:29], v[28:29] op_sel:[0,1] op_sel_hi:[0,1] neg_lo:[0,1] neg_hi:[0,1]
	v_pk_fma_f32 v[106:107], v[108:109], v[28:29], v[96:97] op_sel:[0,0,1] op_sel_hi:[1,1,0] neg_lo:[0,0,1]
	v_pk_mul_f32 v[82:83], v[122:123], v[82:83]
	v_pk_fma_f32 v[96:97], v[122:123], v[28:29], v[82:83] op_sel:[0,0,1] op_sel_hi:[1,1,0] neg_lo:[0,0,1] neg_hi:[0,0,1]
	v_pk_fma_f32 v[28:29], v[122:123], v[28:29], v[82:83] op_sel:[0,0,1] op_sel_hi:[1,1,0]
	v_mov_b32_e32 v82, v96
	v_mov_b32_e32 v83, v29
	v_pk_mul_f32 v[28:29], v[110:111], v[28:29] op_sel:[1,1] op_sel_hi:[0,1]
	v_pk_fma_f32 v[108:109], v[110:111], v[96:97], v[28:29] op_sel_hi:[1,0,1] neg_lo:[0,0,1]
	v_add3_u32 v0, v5, v7, v0
	v_pk_mul_f32 v[28:29], v[122:123], v[82:83]
	v_pk_mul_f32 v[82:83], v[122:123], v[82:83] op_sel:[1,0] op_sel_hi:[0,1]
	v_pk_add_f32 v[82:83], v[82:83], v[82:83] op_sel:[0,1] op_sel_hi:[0,1]
	v_pk_mul_f32 v[96:97], v[114:115], v[82:83]
	v_pk_add_f32 v[28:29], v[28:29], v[28:29] op_sel:[0,1] op_sel_hi:[0,1] neg_lo:[0,1] neg_hi:[0,1]
	v_pk_fma_f32 v[110:111], v[114:115], v[28:29], v[96:97] op_sel:[0,0,1] op_sel_hi:[1,1,0] neg_lo:[0,0,1]
	v_pk_mul_f32 v[82:83], v[122:123], v[82:83]
	v_pk_fma_f32 v[96:97], v[122:123], v[28:29], v[82:83] op_sel:[0,0,1] op_sel_hi:[1,1,0] neg_lo:[0,0,1] neg_hi:[0,0,1]
	v_pk_fma_f32 v[28:29], v[122:123], v[28:29], v[82:83] op_sel:[0,0,1] op_sel_hi:[1,1,0]
	v_mov_b32_e32 v82, v96
	v_mov_b32_e32 v83, v29
	s_waitcnt lgkmcnt(4)
	v_pk_mul_f32 v[28:29], v[124:125], v[28:29] op_sel:[1,1] op_sel_hi:[0,1]
	v_pk_fma_f32 v[114:115], v[124:125], v[96:97], v[28:29] op_sel_hi:[1,0,1] neg_lo:[0,0,1]
	s_nop 0
	v_pk_mul_f32 v[28:29], v[122:123], v[82:83]
	v_pk_mul_f32 v[82:83], v[122:123], v[82:83] op_sel:[1,0] op_sel_hi:[0,1]
	v_pk_add_f32 v[82:83], v[82:83], v[82:83] op_sel:[0,1] op_sel_hi:[0,1]
	s_waitcnt lgkmcnt(3)
	v_pk_mul_f32 v[96:97], v[126:127], v[82:83]
	v_pk_add_f32 v[28:29], v[28:29], v[28:29] op_sel:[0,1] op_sel_hi:[0,1] neg_lo:[0,1] neg_hi:[0,1]
	v_pk_fma_f32 v[124:125], v[126:127], v[28:29], v[96:97] op_sel:[0,0,1] op_sel_hi:[1,1,0] neg_lo:[0,0,1]
	v_pk_mul_f32 v[82:83], v[122:123], v[82:83]
	v_pk_fma_f32 v[96:97], v[122:123], v[28:29], v[82:83] op_sel:[0,0,1] op_sel_hi:[1,1,0] neg_lo:[0,0,1] neg_hi:[0,0,1]
	v_pk_fma_f32 v[28:29], v[122:123], v[28:29], v[82:83] op_sel:[0,0,1] op_sel_hi:[1,1,0]
	v_mov_b32_e32 v82, v96
	v_mov_b32_e32 v83, v29
	s_waitcnt lgkmcnt(2)
	v_pk_mul_f32 v[28:29], v[128:129], v[28:29] op_sel:[1,1] op_sel_hi:[0,1]
	v_pk_fma_f32 v[126:127], v[128:129], v[96:97], v[28:29] op_sel_hi:[1,0,1] neg_lo:[0,0,1]
	s_nop 0
	v_pk_mul_f32 v[28:29], v[122:123], v[82:83]
	v_pk_mul_f32 v[82:83], v[122:123], v[82:83] op_sel:[1,0] op_sel_hi:[0,1]
	v_pk_add_f32 v[82:83], v[82:83], v[82:83] op_sel:[0,1] op_sel_hi:[0,1]
	s_waitcnt lgkmcnt(1)
	v_pk_mul_f32 v[96:97], v[130:131], v[82:83]
	v_pk_add_f32 v[28:29], v[28:29], v[28:29] op_sel:[0,1] op_sel_hi:[0,1] neg_lo:[0,1] neg_hi:[0,1]
	v_pk_fma_f32 v[128:129], v[130:131], v[28:29], v[96:97] op_sel:[0,0,1] op_sel_hi:[1,1,0] neg_lo:[0,0,1]
	v_pk_mul_f32 v[82:83], v[122:123], v[82:83]
	v_pk_fma_f32 v[96:97], v[122:123], v[28:29], v[82:83] op_sel:[0,0,1] op_sel_hi:[1,1,0] neg_lo:[0,0,1] neg_hi:[0,0,1]
	v_pk_fma_f32 v[28:29], v[122:123], v[28:29], v[82:83] op_sel:[0,0,1] op_sel_hi:[1,1,0]
	v_mov_b32_e32 v82, v96
	v_mov_b32_e32 v83, v29
	s_waitcnt lgkmcnt(0)
	v_pk_mul_f32 v[28:29], v[132:133], v[28:29] op_sel:[1,1] op_sel_hi:[0,1]
	v_pk_fma_f32 v[130:131], v[132:133], v[96:97], v[28:29] op_sel_hi:[1,0,1] neg_lo:[0,0,1]
	s_nop 0
	v_pk_mul_f32 v[28:29], v[122:123], v[82:83]
	v_pk_mul_f32 v[82:83], v[122:123], v[82:83] op_sel:[1,0] op_sel_hi:[0,1]
	v_pk_add_f32 v[82:83], v[82:83], v[82:83] op_sel:[0,1] op_sel_hi:[0,1]
	v_pk_mul_f32 v[96:97], v[116:117], v[82:83]
	v_pk_add_f32 v[28:29], v[28:29], v[28:29] op_sel:[0,1] op_sel_hi:[0,1] neg_lo:[0,1] neg_hi:[0,1]
	v_pk_fma_f32 v[132:133], v[116:117], v[28:29], v[96:97] op_sel:[0,0,1] op_sel_hi:[1,1,0] neg_lo:[0,0,1]
	v_pk_mul_f32 v[28:29], v[122:123], v[28:29]
	v_pk_fma_f32 v[96:97], v[122:123], v[82:83], v[28:29] op_sel:[0,0,1] op_sel_hi:[1,1,0] neg_lo:[1,0,0] neg_hi:[1,0,0]
	v_pk_fma_f32 v[28:29], v[122:123], v[82:83], v[28:29] op_sel:[0,0,1] op_sel_hi:[1,1,0]
	v_mov_b32_e32 v83, v97
	v_mov_b32_e32 v82, v28
	v_pk_mul_f32 v[116:117], v[118:119], v[28:29] op_sel:[1,0] op_sel_hi:[0,0]
	v_pk_mov_b32 v[28:29], v[96:97], v[28:29] op_sel:[1,0]
	v_pk_mul_f32 v[82:83], v[122:123], v[82:83]
	v_pk_mul_f32 v[28:29], v[122:123], v[28:29]
	v_pk_add_f32 v[82:83], v[82:83], v[82:83] op_sel:[1,0] op_sel_hi:[1,0]
	v_pk_fma_f32 v[142:143], v[118:119], v[96:97], v[116:117] op_sel:[0,1,0] neg_lo:[0,0,1]
	v_pk_mul_f32 v[82:83], v[120:121], v[82:83] op_sel:[1,0] op_sel_hi:[0,1]
	v_pk_add_f32 v[28:29], v[28:29], v[28:29] op_sel:[0,1] op_sel_hi:[0,1] neg_lo:[0,1] neg_hi:[0,1]
	v_pk_fma_f32 v[96:97], v[120:121], v[28:29], v[82:83] neg_lo:[0,0,1]
	v_pk_add_f32 v[82:83], v[134:135], v[130:131]
	v_pk_add_f32 v[28:29], v[26:27], v[114:115]
	v_pk_add_f32 v[26:27], v[26:27], v[114:115] neg_lo:[0,1] neg_hi:[0,1]
	v_pk_add_f32 v[114:115], v[134:135], v[130:131] neg_lo:[0,1] neg_hi:[0,1]
	v_pk_add_f32 v[120:121], v[106:107], v[132:133]
	v_xor_b32_e32 v117, 0x80000000, v114
	v_mov_b32_e32 v116, v115
	v_pk_add_f32 v[106:107], v[106:107], v[132:133] neg_lo:[0,1] neg_hi:[0,1]
	v_pk_add_f32 v[114:115], v[28:29], v[82:83]
	v_pk_add_f32 v[118:119], v[26:27], v[116:117]
	v_pk_add_f32 v[28:29], v[28:29], v[82:83] neg_lo:[0,1] neg_hi:[0,1]
	v_pk_add_f32 v[26:27], v[26:27], v[116:117] neg_lo:[0,1] neg_hi:[0,1]
	v_pk_add_f32 v[82:83], v[136:137], v[124:125]
	v_pk_add_f32 v[116:117], v[136:137], v[124:125] neg_lo:[0,1] neg_hi:[0,1]
	v_xor_b32_e32 v123, 0x80000000, v106
	v_mov_b32_e32 v122, v107
	v_pk_add_f32 v[106:107], v[82:83], v[120:121]
	v_pk_add_f32 v[124:125], v[116:117], v[122:123]
	v_pk_add_f32 v[82:83], v[82:83], v[120:121] neg_lo:[0,1] neg_hi:[0,1]
	v_pk_add_f32 v[116:117], v[116:117], v[122:123] neg_lo:[0,1] neg_hi:[0,1]
	v_pk_add_f32 v[120:121], v[140:141], v[126:127]
	v_pk_add_f32 v[122:123], v[140:141], v[126:127] neg_lo:[0,1] neg_hi:[0,1]
	v_pk_add_f32 v[126:127], v[108:109], v[142:143]
	v_pk_add_f32 v[108:109], v[108:109], v[142:143] neg_lo:[0,1] neg_hi:[0,1]
	s_nop 0
	v_pk_add_f32 v[132:133], v[122:123], v[108:109] op_sel:[0,1] op_sel_hi:[1,0] neg_hi:[0,1]
	v_pk_add_f32 v[122:123], v[122:123], v[108:109] op_sel:[0,1] op_sel_hi:[1,0] neg_lo:[0,1]
	v_pk_add_f32 v[130:131], v[110:111], v[96:97]
	v_pk_add_f32 v[96:97], v[110:111], v[96:97] neg_lo:[0,1] neg_hi:[0,1]
	v_pk_add_f32 v[108:109], v[120:121], v[126:127]
	v_pk_add_f32 v[120:121], v[120:121], v[126:127] neg_lo:[0,1] neg_hi:[0,1]
	v_pk_add_f32 v[126:127], v[138:139], v[128:129]
	v_pk_add_f32 v[128:129], v[138:139], v[128:129] neg_lo:[0,1] neg_hi:[0,1]
	v_pk_add_f32 v[134:135], v[128:129], v[96:97] op_sel:[0,1] op_sel_hi:[1,0] neg_hi:[0,1]
	v_pk_add_f32 v[110:111], v[128:129], v[96:97] op_sel:[0,1] op_sel_hi:[1,0] neg_lo:[0,1]
	v_pk_mul_f32 v[128:129], v[124:125], s[24:25] op_sel_hi:[1,0]
	v_pk_add_f32 v[96:97], v[126:127], v[130:131]
	v_pk_add_f32 v[126:127], v[126:127], v[130:131] neg_lo:[0,1] neg_hi:[0,1]
	v_pk_fma_f32 v[130:131], v[124:125], s[26:27], v[128:129] op_sel:[0,0,1] op_sel_hi:[1,0,0] neg_hi:[0,0,1]
	s_nop 0
	v_pk_mul_f32 v[124:125], v[82:83], s[28:29] op_sel_hi:[1,0]
	s_nop 0
	v_pk_fma_f32 v[128:129], v[82:83], s[28:29], v[124:125] op_sel:[0,0,1] op_sel_hi:[1,0,0] neg_hi:[0,0,1]
	v_pk_mul_f32 v[124:125], v[116:117], s[26:27] op_sel_hi:[1,0]
	v_pk_fma_f32 v[136:137], v[116:117], s[24:25], v[124:125] op_sel:[0,0,1] op_sel_hi:[1,0,0] neg_hi:[0,0,1]
	s_nop 0
	v_pk_mul_f32 v[116:117], v[132:133], s[28:29] op_sel_hi:[1,0]
	s_nop 0
	v_pk_fma_f32 v[124:125], v[132:133], s[28:29], v[116:117] op_sel:[0,0,1] op_sel_hi:[1,0,0] neg_hi:[0,0,1]
	s_nop 0
	v_pk_fma_f32 v[116:117], v[120:121], 0, v[120:121] op_sel:[0,0,1] op_sel_hi:[1,0,0] neg_hi:[0,0,1]
	s_nop 0
	v_pk_mul_f32 v[120:121], v[122:123], s[30:31] op_sel_hi:[1,0]
	s_nop 0
	v_pk_fma_f32 v[132:133], v[122:123], s[30:31], v[120:121] op_sel:[0,0,1] op_sel_hi:[1,0,0] neg_lo:[0,0,1]
	v_pk_mul_f32 v[122:123], v[134:135], s[26:27] op_sel_hi:[1,0]
	v_pk_fma_f32 v[138:139], v[134:135], s[24:25], v[122:123] op_sel:[0,0,1] op_sel_hi:[1,0,0] neg_hi:[0,0,1]
	v_pk_add_f32 v[120:121], v[26:27], v[132:133]
	v_pk_mul_f32 v[122:123], v[126:127], s[30:31] op_sel_hi:[1,0]
	v_pk_add_f32 v[26:27], v[26:27], v[132:133] neg_lo:[0,1] neg_hi:[0,1]
	v_pk_fma_f32 v[134:135], v[126:127], s[30:31], v[122:123] op_sel:[0,0,1] op_sel_hi:[1,0,0] neg_lo:[0,0,1]
	s_nop 0
	v_pk_mul_f32 v[122:123], v[110:111], s[60:61] op_sel:[1,0]
	v_pk_add_f32 v[82:83], v[128:129], v[134:135]
	v_pk_fma_f32 v[110:111], v[110:111], s[34:35], v[122:123] op_sel_hi:[0,1,1]
	v_pk_add_f32 v[122:123], v[114:115], v[108:109]
	v_pk_add_f32 v[108:109], v[114:115], v[108:109] neg_lo:[0,1] neg_hi:[0,1]
	v_pk_add_f32 v[114:115], v[106:107], v[96:97]
	v_pk_add_f32 v[96:97], v[106:107], v[96:97] neg_lo:[0,1] neg_hi:[0,1]
	s_nop 0
	v_xor_b32_e32 v107, 0x80000000, v96
	v_mov_b32_e32 v106, v97
	v_pk_add_f32 v[96:97], v[122:123], v[114:115]
	v_pk_add_f32 v[126:127], v[108:109], v[106:107]
	v_pk_add_f32 v[114:115], v[122:123], v[114:115] neg_lo:[0,1] neg_hi:[0,1]
	v_pk_add_f32 v[106:107], v[108:109], v[106:107] neg_lo:[0,1] neg_hi:[0,1]
	v_pk_add_f32 v[108:109], v[118:119], v[124:125]
	v_pk_add_f32 v[118:119], v[118:119], v[124:125] neg_lo:[0,1] neg_hi:[0,1]
	v_pk_add_f32 v[122:123], v[130:131], v[138:139]
	v_pk_add_f32 v[124:125], v[130:131], v[138:139] neg_lo:[0,1] neg_hi:[0,1]
	s_nop 0
	v_xor_b32_e32 v131, 0x80000000, v124
	v_mov_b32_e32 v130, v125
	v_pk_add_f32 v[124:125], v[108:109], v[122:123]
	v_pk_add_f32 v[108:109], v[108:109], v[122:123] neg_lo:[0,1] neg_hi:[0,1]
	v_pk_add_f32 v[122:123], v[28:29], v[116:117]
	v_pk_add_f32 v[28:29], v[28:29], v[116:117] neg_lo:[0,1] neg_hi:[0,1]
	v_pk_add_f32 v[116:117], v[128:129], v[134:135] neg_lo:[0,1] neg_hi:[0,1]
	v_pk_add_f32 v[138:139], v[118:119], v[130:131]
	v_xor_b32_e32 v129, 0x80000000, v116
	v_mov_b32_e32 v128, v117
	v_pk_add_f32 v[116:117], v[122:123], v[82:83]
	v_pk_add_f32 v[82:83], v[122:123], v[82:83] neg_lo:[0,1] neg_hi:[0,1]
	v_pk_add_f32 v[122:123], v[136:137], v[110:111]
	v_pk_add_f32 v[110:111], v[136:137], v[110:111] neg_lo:[0,1] neg_hi:[0,1]
	v_pk_add_f32 v[118:119], v[118:119], v[130:131] neg_lo:[0,1] neg_hi:[0,1]
	v_pk_add_f32 v[130:131], v[28:29], v[128:129]
	v_pk_add_f32 v[28:29], v[28:29], v[128:129] neg_lo:[0,1] neg_hi:[0,1]
	v_xor_b32_e32 v129, 0x80000000, v110
	v_mov_b32_e32 v128, v111
	v_pk_add_f32 v[110:111], v[120:121], v[122:123]
	v_pk_add_f32 v[132:133], v[26:27], v[128:129]
	v_pk_add_f32 v[120:121], v[120:121], v[122:123] neg_lo:[0,1] neg_hi:[0,1]
	v_pk_add_f32 v[26:27], v[26:27], v[128:129] neg_lo:[0,1] neg_hi:[0,1]
	ds_write_b64 v0, v[96:97]
	ds_write_b64 v0, v[124:125] offset:2176
	ds_write_b64 v0, v[116:117] offset:4352
	ds_write_b64 v0, v[110:111] offset:6528
	ds_write_b64 v0, v[126:127] offset:8704
	ds_write_b64 v0, v[138:139] offset:10880
	ds_write_b64 v0, v[130:131] offset:13056
	ds_write_b64 v0, v[132:133] offset:15232
	ds_write_b64 v0, v[114:115] offset:17408
	ds_write_b64 v0, v[108:109] offset:19584
	ds_write_b64 v0, v[82:83] offset:21760
	ds_write_b64 v0, v[120:121] offset:23936
	ds_write_b64 v0, v[106:107] offset:26112
	ds_write_b64 v0, v[118:119] offset:28288
	ds_write_b64 v0, v[28:29] offset:30464
	ds_write_b64 v0, v[26:27] offset:32640

.LBB0_356:
	v_mov_b32_e32 v200, v197
	v_mov_b32_e32 v201, v193
	ds_write_b64 v0, v[200:201] offset:6272
	ds_write_b64 v232, v[240:241] offset:22656
	v_mov_b32_e32 v200, v196
	v_mov_b32_e32 v201, v192
	ds_write_b64 v0, v[200:201] offset:6280
	ds_write_b64 v232, v[240:241] offset:22664
	v_mov_b32_e32 v200, v198
	v_mov_b32_e32 v201, v194
	ds_write_b64 v0, v[200:201] offset:6288
	ds_write_b64 v232, v[240:241] offset:22672
	v_mov_b32_e32 v200, v199
	v_mov_b32_e32 v201, v195
	ds_write_b64 v0, v[200:201] offset:6296
	ds_write_b64 v232, v[240:241] offset:22680
	v_mov_b32_e32 v200, v189
	v_mov_b32_e32 v201, v185
	ds_write_b64 v0, v[200:201] offset:41088
	ds_write_b64 v232, v[240:241] offset:57472
	v_mov_b32_e32 v200, v188
	v_mov_b32_e32 v201, v184
	ds_write_b64 v0, v[200:201] offset:41096
	ds_write_b64 v232, v[240:241] offset:57480
	v_mov_b32_e32 v200, v190
	v_mov_b32_e32 v201, v186
	ds_write_b64 v0, v[200:201] offset:41104
	ds_write_b64 v232, v[240:241] offset:57488
	v_mov_b32_e32 v200, v191
	v_mov_b32_e32 v201, v187
	ds_write_b64 v0, v[200:201] offset:41112
	ds_write_b64 v232, v[240:241] offset:57496
	v_mov_b32_e32 v200, v180
	s_waitcnt lgkmcnt(0)
	s_barrier
	s_nop 0
	v_cmp_gt_i32_e32 vcc, s56, v200
	s_and_saveexec_b64 s[2:3], vcc
	s_cbranch_execz .LBB0_358
	v_ashrrev_i32_e32 v181, 31, v200
	v_add_u32_sdwa v181, v200, v181 dst_sel:DWORD dst_unused:UNUSED_PAD src0_sel:DWORD src1_sel:BYTE_3
	v_ashrrev_i32_e32 v181, 8, v181
	v_mul_i32_i24_e32 v201, 0x100, v181
	v_sub_u32_e32 v233, v200, v201
	v_mul_i32_i24_e32 v181, 0x1100, v181
	v_lshlrev_b32_e32 v181, 3, v181
	v_ashrrev_i32_e32 v201, 4, v233
	v_add_u32_e32 v200, 0, v181
	v_lshlrev_b32_e32 v244, 3, v233
	v_lshlrev_b32_e32 v201, 3, v201
	v_add3_u32 v230, v200, v244, v201
	ds_read_b64 v[200:201], v230 offset:6272
	ds_read_b64 v[202:203], v230 offset:8448
	ds_read_b64 v[204:205], v230 offset:10624
	ds_read_b64 v[206:207], v230 offset:12800
	ds_read_b64 v[208:209], v230 offset:14976
	ds_read_b64 v[210:211], v230 offset:17152
	ds_read_b64 v[212:213], v230 offset:19328
	ds_read_b64 v[214:215], v230 offset:21504
	ds_read_b64 v[216:217], v230 offset:23680
	ds_read_b64 v[218:219], v230 offset:25856
	ds_read_b64 v[220:221], v230 offset:28032
	ds_read_b64 v[222:223], v230 offset:30208
	ds_read_b64 v[224:225], v230 offset:32384
	ds_read_b64 v[226:227], v230 offset:34560
	ds_read_b64 v[228:229], v230 offset:36736
	ds_read_b64 v[230:231], v230 offset:38912
	s_waitcnt lgkmcnt(7)
	v_pk_add_f32 v[234:235], v[200:201], v[216:217]
	v_pk_add_f32 v[200:201], v[200:201], v[216:217] neg_lo:[0,1] neg_hi:[0,1]
	s_waitcnt lgkmcnt(3)
	v_pk_add_f32 v[216:217], v[208:209], v[224:225]
	v_pk_add_f32 v[208:209], v[208:209], v[224:225] neg_lo:[0,1] neg_hi:[0,1]
	s_mov_b32 s61, s34
	v_pk_add_f32 v[236:237], v[200:201], v[208:209] op_sel:[0,1] op_sel_hi:[1,0] neg_hi:[0,1]
	v_pk_add_f32 v[200:201], v[200:201], v[208:209] op_sel:[0,1] op_sel_hi:[1,0] neg_lo:[0,1]
	v_pk_add_f32 v[224:225], v[202:203], v[218:219]
	v_pk_add_f32 v[202:203], v[202:203], v[218:219] neg_lo:[0,1] neg_hi:[0,1]
	s_waitcnt lgkmcnt(2)
	v_pk_add_f32 v[218:219], v[210:211], v[226:227]
	v_pk_add_f32 v[210:211], v[210:211], v[226:227] neg_lo:[0,1] neg_hi:[0,1]
	v_pk_add_f32 v[208:209], v[234:235], v[216:217]
	v_xor_b32_e32 v227, 0x80000000, v210
	v_mov_b32_e32 v226, v211
	v_pk_add_f32 v[210:211], v[224:225], v[218:219]
	v_pk_add_f32 v[218:219], v[224:225], v[218:219] neg_lo:[0,1] neg_hi:[0,1]
	v_pk_add_f32 v[224:225], v[204:205], v[220:221]
	v_pk_add_f32 v[204:205], v[204:205], v[220:221] neg_lo:[0,1] neg_hi:[0,1]
	s_waitcnt lgkmcnt(1)
	v_pk_add_f32 v[220:221], v[212:213], v[228:229]
	v_pk_add_f32 v[212:213], v[212:213], v[228:229] neg_lo:[0,1] neg_hi:[0,1]
	v_pk_add_f32 v[216:217], v[234:235], v[216:217] neg_lo:[0,1] neg_hi:[0,1]
	v_pk_add_f32 v[234:235], v[202:203], v[226:227]
	v_pk_add_f32 v[202:203], v[202:203], v[226:227] neg_lo:[0,1] neg_hi:[0,1]
	v_xor_b32_e32 v227, 0x80000000, v212
	v_mov_b32_e32 v226, v213
	v_pk_add_f32 v[212:213], v[224:225], v[220:221]
	v_pk_add_f32 v[220:221], v[224:225], v[220:221] neg_lo:[0,1] neg_hi:[0,1]
	v_pk_add_f32 v[224:225], v[206:207], v[222:223]
	v_pk_add_f32 v[206:207], v[206:207], v[222:223] neg_lo:[0,1] neg_hi:[0,1]
	s_waitcnt lgkmcnt(0)
	v_pk_add_f32 v[222:223], v[214:215], v[230:231]
	v_pk_add_f32 v[214:215], v[214:215], v[230:231] neg_lo:[0,1] neg_hi:[0,1]
	v_pk_add_f32 v[228:229], v[204:205], v[226:227]
	v_pk_add_f32 v[204:205], v[204:205], v[226:227] neg_lo:[0,1] neg_hi:[0,1]
	v_xor_b32_e32 v227, 0x80000000, v214
	v_mov_b32_e32 v226, v215
	v_pk_add_f32 v[214:215], v[224:225], v[222:223]
	v_pk_add_f32 v[222:223], v[224:225], v[222:223] neg_lo:[0,1] neg_hi:[0,1]
	v_pk_mul_f32 v[224:225], v[234:235], s[24:25] op_sel_hi:[1,0]
	v_pk_add_f32 v[230:231], v[206:207], v[226:227]
	v_pk_add_f32 v[206:207], v[206:207], v[226:227] neg_lo:[0,1] neg_hi:[0,1]
	v_pk_fma_f32 v[226:227], v[234:235], s[26:27], v[224:225] op_sel:[0,0,1] op_sel_hi:[1,0,0] neg_hi:[0,0,1]
	s_mov_b32 s35, s24
	v_pk_mul_f32 v[224:225], v[218:219], s[28:29] op_sel_hi:[1,0]
	v_add_u32_e32 v181, s57, v181
	v_pk_fma_f32 v[234:235], v[218:219], s[28:29], v[224:225] op_sel:[0,0,1] op_sel_hi:[1,0,0] neg_hi:[0,0,1]
	v_pk_mul_f32 v[224:225], v[202:203], s[26:27] op_sel_hi:[1,0]
	v_pk_fma_f32 v[238:239], v[202:203], s[24:25], v[224:225] op_sel:[0,0,1] op_sel_hi:[1,0,0] neg_hi:[0,0,1]
	s_nop 0
	v_pk_mul_f32 v[202:203], v[228:229], s[28:29] op_sel_hi:[1,0]
	s_nop 0
	v_pk_fma_f32 v[224:225], v[228:229], s[28:29], v[202:203] op_sel:[0,0,1] op_sel_hi:[1,0,0] neg_hi:[0,0,1]
	s_nop 0
	v_pk_fma_f32 v[202:203], v[220:221], 0, v[220:221] op_sel:[0,0,1] op_sel_hi:[1,0,0] neg_hi:[0,0,1]
	s_nop 0
	v_pk_mul_f32 v[220:221], v[204:205], s[30:31] op_sel_hi:[1,0]
	s_nop 0
	v_pk_fma_f32 v[228:229], v[204:205], s[30:31], v[220:221] op_sel:[0,0,1] op_sel_hi:[1,0,0] neg_lo:[0,0,1]
	v_pk_mul_f32 v[220:221], v[230:231], s[26:27] op_sel_hi:[1,0]
	v_pk_fma_f32 v[242:243], v[230:231], s[24:25], v[220:221] op_sel:[0,0,1] op_sel_hi:[1,0,0] neg_hi:[0,0,1]
	v_pk_add_f32 v[204:205], v[200:201], v[228:229]
	v_pk_mul_f32 v[220:221], v[222:223], s[30:31] op_sel_hi:[1,0]
	v_pk_add_f32 v[200:201], v[200:201], v[228:229] neg_lo:[0,1] neg_hi:[0,1]
	v_pk_fma_f32 v[230:231], v[222:223], s[30:31], v[220:221] op_sel:[0,0,1] op_sel_hi:[1,0,0] neg_lo:[0,0,1]
	s_nop 0
	v_pk_mul_f32 v[220:221], v[206:207], s[60:61] op_sel:[1,0]
	v_pk_add_f32 v[218:219], v[234:235], v[230:231] neg_lo:[0,1] neg_hi:[0,1]
	v_pk_fma_f32 v[206:207], v[206:207], s[34:35], v[220:221] op_sel_hi:[0,1,1]
	v_pk_add_f32 v[220:221], v[208:209], v[212:213]
	v_pk_add_f32 v[208:209], v[208:209], v[212:213] neg_lo:[0,1] neg_hi:[0,1]
	v_pk_add_f32 v[212:213], v[210:211], v[214:215]
	v_pk_add_f32 v[210:211], v[210:211], v[214:215] neg_lo:[0,1] neg_hi:[0,1]
	s_nop 0
	v_xor_b32_e32 v215, 0x80000000, v210
	v_mov_b32_e32 v214, v211
	v_pk_add_f32 v[210:211], v[220:221], v[212:213]
	v_pk_add_f32 v[222:223], v[208:209], v[214:215]
	v_pk_add_f32 v[212:213], v[220:221], v[212:213] neg_lo:[0,1] neg_hi:[0,1]
	v_pk_add_f32 v[208:209], v[208:209], v[214:215] neg_lo:[0,1] neg_hi:[0,1]
	v_pk_add_f32 v[214:215], v[236:237], v[224:225]
	v_pk_add_f32 v[220:221], v[236:237], v[224:225] neg_lo:[0,1] neg_hi:[0,1]
	v_pk_add_f32 v[224:225], v[226:227], v[242:243]
	v_pk_add_f32 v[226:227], v[226:227], v[242:243] neg_lo:[0,1] neg_hi:[0,1]
	s_nop 0
	v_xor_b32_e32 v237, 0x80000000, v226
	v_mov_b32_e32 v236, v227
	v_pk_add_f32 v[226:227], v[214:215], v[224:225]
	v_pk_add_f32 v[214:215], v[214:215], v[224:225] neg_lo:[0,1] neg_hi:[0,1]
	v_pk_add_f32 v[224:225], v[216:217], v[202:203]
	v_pk_add_f32 v[202:203], v[216:217], v[202:203] neg_lo:[0,1] neg_hi:[0,1]
	v_pk_add_f32 v[216:217], v[234:235], v[230:231]
	v_xor_b32_e32 v231, 0x80000000, v218
	v_mov_b32_e32 v230, v219
	v_pk_add_f32 v[218:219], v[224:225], v[216:217]
	v_pk_add_f32 v[216:217], v[224:225], v[216:217] neg_lo:[0,1] neg_hi:[0,1]
	v_pk_add_f32 v[224:225], v[238:239], v[206:207]
	v_pk_add_f32 v[206:207], v[238:239], v[206:207] neg_lo:[0,1] neg_hi:[0,1]
	v_pk_add_f32 v[242:243], v[220:221], v[236:237]
	v_xor_b32_e32 v229, 0x80000000, v206
	v_mov_b32_e32 v228, v207
	v_pk_add_f32 v[206:207], v[204:205], v[224:225]
	v_pk_add_f32 v[204:205], v[204:205], v[224:225] neg_lo:[0,1] neg_hi:[0,1]
	v_lshlrev_b32_e32 v224, 7, v233
	v_add3_u32 v181, v181, v224, v244
	v_pk_add_f32 v[220:221], v[220:221], v[236:237] neg_lo:[0,1] neg_hi:[0,1]
	v_pk_add_f32 v[234:235], v[202:203], v[230:231]
	v_pk_add_f32 v[202:203], v[202:203], v[230:231] neg_lo:[0,1] neg_hi:[0,1]
	v_pk_add_f32 v[230:231], v[200:201], v[228:229]
	v_pk_add_f32 v[200:201], v[200:201], v[228:229] neg_lo:[0,1] neg_hi:[0,1]
	ds_write2_b64 v181, v[210:211], v[226:227] offset1:1
	ds_write2_b64 v181, v[218:219], v[206:207] offset0:2 offset1:3
	ds_write2_b64 v181, v[222:223], v[242:243] offset0:4 offset1:5
	ds_write2_b64 v181, v[234:235], v[230:231] offset0:6 offset1:7
	ds_write2_b64 v181, v[212:213], v[214:215] offset0:8 offset1:9
	ds_write2_b64 v181, v[216:217], v[204:205] offset0:10 offset1:11
	ds_write2_b64 v181, v[208:209], v[220:221] offset0:12 offset1:13
	ds_write2_b64 v181, v[202:203], v[200:201] offset0:14 offset1:15

.LBB0_360:
	s_or_b64 exec, exec, s[2:3]
	v_mov_b32_e32 v200, v180
	s_waitcnt lgkmcnt(0)
	s_barrier
	s_nop 0
	v_cmp_gt_i32_e32 vcc, s56, v200
	s_and_saveexec_b64 s[2:3], vcc
	s_cbranch_execz .LBB0_362
	v_ashrrev_i32_e32 v181, 31, v200
	v_add_u32_sdwa v181, v200, v181 dst_sel:DWORD dst_unused:UNUSED_PAD src0_sel:DWORD src1_sel:BYTE_3
	v_ashrrev_i32_e32 v181, 8, v181
	v_mul_i32_i24_e32 v201, 0x100, v181
	v_sub_u32_e32 v200, v200, v201
	v_mul_i32_i24_e32 v181, 0x1100, v181
	v_lshlrev_b32_e32 v233, 3, v200
	v_ashrrev_i32_e32 v200, 4, v200
	v_lshlrev_b32_e32 v181, 3, v181
	v_lshlrev_b32_e32 v248, 3, v200
	v_add_u32_e32 v222, 0, v233
	v_add3_u32 v234, v222, v181, v248
	ds_read_b64 v[200:201], v234 offset:6272
	ds_read_b64 v[202:203], v234 offset:8448
	ds_read_b64 v[204:205], v234 offset:10624
	ds_read_b64 v[206:207], v234 offset:12800
	ds_read_b64 v[208:209], v234 offset:14976
	ds_read_b64 v[210:211], v234 offset:17152
	ds_read_b64 v[212:213], v234 offset:19328
	ds_read_b64 v[214:215], v234 offset:21504
	ds_read_b64 v[216:217], v234 offset:34560
	ds_read_b64 v[218:219], v234 offset:36736
	ds_read_b64 v[220:221], v234 offset:38912
	ds_read_b64 v[222:223], v222
	ds_read_b64 v[224:225], v234 offset:23680
	ds_read_b64 v[226:227], v234 offset:25856
	ds_read_b64 v[228:229], v234 offset:28032
	ds_read_b64 v[230:231], v234 offset:30208
	ds_read_b64 v[234:235], v234 offset:32384
	s_waitcnt lgkmcnt(5)
	v_pk_mul_f32 v[236:237], v[202:203], v[222:223] op_sel:[1,1] op_sel_hi:[1,0]
	s_mov_b32 s61, s34
	v_pk_fma_f32 v[238:239], v[202:203], v[222:223], v[236:237] op_sel_hi:[0,1,1] neg_lo:[0,0,1]
	v_pk_mul_f32 v[202:203], v[222:223], v[222:223] op_sel:[1,1] op_sel_hi:[1,0]
	s_mov_b32 s35, s24
	v_pk_fma_f32 v[236:237], v[222:223], v[222:223], v[202:203] op_sel_hi:[1,0,1] neg_lo:[0,0,1] neg_hi:[0,0,1]
	v_pk_fma_f32 v[202:203], v[222:223], v[222:223], v[202:203] op_sel_hi:[1,0,1]
	v_mov_b32_e32 v242, v236
	v_mov_b32_e32 v243, v203
	v_pk_mul_f32 v[202:203], v[204:205], v[202:203] op_sel:[1,1] op_sel_hi:[0,1]
	v_pk_fma_f32 v[244:245], v[204:205], v[236:237], v[202:203] op_sel_hi:[1,0,1] neg_lo:[0,0,1]
	v_pk_mul_f32 v[204:205], v[222:223], v[242:243] op_sel:[1,0] op_sel_hi:[0,1]
	v_pk_mul_f32 v[202:203], v[222:223], v[242:243]
	v_pk_add_f32 v[204:205], v[204:205], v[204:205] op_sel:[0,1] op_sel_hi:[0,1]
	v_pk_mul_f32 v[236:237], v[206:207], v[204:205]
	v_pk_add_f32 v[202:203], v[202:203], v[202:203] op_sel:[0,1] op_sel_hi:[0,1] neg_lo:[0,1] neg_hi:[0,1]
	v_pk_fma_f32 v[242:243], v[206:207], v[202:203], v[236:237] op_sel:[0,0,1] op_sel_hi:[1,1,0] neg_lo:[0,0,1]
	v_pk_mul_f32 v[204:205], v[222:223], v[204:205]
	v_pk_fma_f32 v[206:207], v[222:223], v[202:203], v[204:205] op_sel:[0,0,1] op_sel_hi:[1,1,0] neg_lo:[0,0,1] neg_hi:[0,0,1]
	v_pk_fma_f32 v[202:203], v[222:223], v[202:203], v[204:205] op_sel:[0,0,1] op_sel_hi:[1,1,0]
	v_mov_b32_e32 v204, v206
	v_mov_b32_e32 v205, v203
	v_pk_mul_f32 v[202:203], v[208:209], v[202:203] op_sel:[1,1] op_sel_hi:[0,1]
	v_pk_fma_f32 v[236:237], v[208:209], v[206:207], v[202:203] op_sel_hi:[1,0,1] neg_lo:[0,0,1]
	v_add_u32_e32 v181, s57, v181
	v_pk_mul_f32 v[202:203], v[222:223], v[204:205]
	v_pk_mul_f32 v[204:205], v[222:223], v[204:205] op_sel:[1,0] op_sel_hi:[0,1]
	v_pk_add_f32 v[204:205], v[204:205], v[204:205] op_sel:[0,1] op_sel_hi:[0,1]
	v_pk_mul_f32 v[206:207], v[210:211], v[204:205]
	v_pk_add_f32 v[202:203], v[202:203], v[202:203] op_sel:[0,1] op_sel_hi:[0,1] neg_lo:[0,1] neg_hi:[0,1]
	v_pk_fma_f32 v[208:209], v[210:211], v[202:203], v[206:207] op_sel:[0,0,1] op_sel_hi:[1,1,0] neg_lo:[0,0,1]
	v_pk_mul_f32 v[204:205], v[222:223], v[204:205]
	v_pk_fma_f32 v[206:207], v[222:223], v[202:203], v[204:205] op_sel:[0,0,1] op_sel_hi:[1,1,0] neg_lo:[0,0,1] neg_hi:[0,0,1]
	v_pk_fma_f32 v[202:203], v[222:223], v[202:203], v[204:205] op_sel:[0,0,1] op_sel_hi:[1,1,0]
	v_mov_b32_e32 v204, v206
	v_mov_b32_e32 v205, v203
	v_pk_mul_f32 v[202:203], v[212:213], v[202:203] op_sel:[1,1] op_sel_hi:[0,1]
	v_pk_fma_f32 v[210:211], v[212:213], v[206:207], v[202:203] op_sel_hi:[1,0,1] neg_lo:[0,0,1]
	v_add3_u32 v181, v181, v233, v248
	v_pk_mul_f32 v[202:203], v[222:223], v[204:205]
	v_pk_mul_f32 v[204:205], v[222:223], v[204:205] op_sel:[1,0] op_sel_hi:[0,1]
	v_pk_add_f32 v[204:205], v[204:205], v[204:205] op_sel:[0,1] op_sel_hi:[0,1]
	v_pk_mul_f32 v[206:207], v[214:215], v[204:205]
	v_pk_add_f32 v[202:203], v[202:203], v[202:203] op_sel:[0,1] op_sel_hi:[0,1] neg_lo:[0,1] neg_hi:[0,1]
	v_pk_fma_f32 v[212:213], v[214:215], v[202:203], v[206:207] op_sel:[0,0,1] op_sel_hi:[1,1,0] neg_lo:[0,0,1]
	v_pk_mul_f32 v[204:205], v[222:223], v[204:205]
	v_pk_fma_f32 v[206:207], v[222:223], v[202:203], v[204:205] op_sel:[0,0,1] op_sel_hi:[1,1,0] neg_lo:[0,0,1] neg_hi:[0,0,1]
	v_pk_fma_f32 v[202:203], v[222:223], v[202:203], v[204:205] op_sel:[0,0,1] op_sel_hi:[1,1,0]
	v_mov_b32_e32 v204, v206
	v_mov_b32_e32 v205, v203
	s_waitcnt lgkmcnt(4)
	v_pk_mul_f32 v[202:203], v[224:225], v[202:203] op_sel:[1,1] op_sel_hi:[0,1]
	v_pk_fma_f32 v[214:215], v[224:225], v[206:207], v[202:203] op_sel_hi:[1,0,1] neg_lo:[0,0,1]
	s_nop 0
	v_pk_mul_f32 v[202:203], v[222:223], v[204:205]
	v_pk_mul_f32 v[204:205], v[222:223], v[204:205] op_sel:[1,0] op_sel_hi:[0,1]
	v_pk_add_f32 v[204:205], v[204:205], v[204:205] op_sel:[0,1] op_sel_hi:[0,1]
	s_waitcnt lgkmcnt(3)
	v_pk_mul_f32 v[206:207], v[226:227], v[204:205]
	v_pk_add_f32 v[202:203], v[202:203], v[202:203] op_sel:[0,1] op_sel_hi:[0,1] neg_lo:[0,1] neg_hi:[0,1]
	v_pk_fma_f32 v[224:225], v[226:227], v[202:203], v[206:207] op_sel:[0,0,1] op_sel_hi:[1,1,0] neg_lo:[0,0,1]
	v_pk_mul_f32 v[204:205], v[222:223], v[204:205]
	v_pk_fma_f32 v[206:207], v[222:223], v[202:203], v[204:205] op_sel:[0,0,1] op_sel_hi:[1,1,0] neg_lo:[0,0,1] neg_hi:[0,0,1]
	v_pk_fma_f32 v[202:203], v[222:223], v[202:203], v[204:205] op_sel:[0,0,1] op_sel_hi:[1,1,0]
	v_mov_b32_e32 v204, v206
	v_mov_b32_e32 v205, v203
	s_waitcnt lgkmcnt(2)
	v_pk_mul_f32 v[202:203], v[228:229], v[202:203] op_sel:[1,1] op_sel_hi:[0,1]
	v_pk_fma_f32 v[226:227], v[228:229], v[206:207], v[202:203] op_sel_hi:[1,0,1] neg_lo:[0,0,1]
	s_nop 0
	v_pk_mul_f32 v[202:203], v[222:223], v[204:205]
	v_pk_mul_f32 v[204:205], v[222:223], v[204:205] op_sel:[1,0] op_sel_hi:[0,1]
	v_pk_add_f32 v[204:205], v[204:205], v[204:205] op_sel:[0,1] op_sel_hi:[0,1]
	s_waitcnt lgkmcnt(1)
	v_pk_mul_f32 v[206:207], v[230:231], v[204:205]
	v_pk_add_f32 v[202:203], v[202:203], v[202:203] op_sel:[0,1] op_sel_hi:[0,1] neg_lo:[0,1] neg_hi:[0,1]
	v_pk_fma_f32 v[228:229], v[230:231], v[202:203], v[206:207] op_sel:[0,0,1] op_sel_hi:[1,1,0] neg_lo:[0,0,1]
	v_pk_mul_f32 v[204:205], v[222:223], v[204:205]
	v_pk_fma_f32 v[206:207], v[222:223], v[202:203], v[204:205] op_sel:[0,0,1] op_sel_hi:[1,1,0] neg_lo:[0,0,1] neg_hi:[0,0,1]
	v_pk_fma_f32 v[202:203], v[222:223], v[202:203], v[204:205] op_sel:[0,0,1] op_sel_hi:[1,1,0]
	v_mov_b32_e32 v204, v206
	v_mov_b32_e32 v205, v203
	s_waitcnt lgkmcnt(0)
	v_pk_mul_f32 v[202:203], v[234:235], v[202:203] op_sel:[1,1] op_sel_hi:[0,1]
	v_pk_fma_f32 v[230:231], v[234:235], v[206:207], v[202:203] op_sel_hi:[1,0,1] neg_lo:[0,0,1]
	s_nop 0
	v_pk_mul_f32 v[202:203], v[222:223], v[204:205]
	v_pk_mul_f32 v[204:205], v[222:223], v[204:205] op_sel:[1,0] op_sel_hi:[0,1]
	v_pk_add_f32 v[204:205], v[204:205], v[204:205] op_sel:[0,1] op_sel_hi:[0,1]
	v_pk_mul_f32 v[206:207], v[216:217], v[204:205]
	v_pk_add_f32 v[202:203], v[202:203], v[202:203] op_sel:[0,1] op_sel_hi:[0,1] neg_lo:[0,1] neg_hi:[0,1]
	v_pk_fma_f32 v[234:235], v[216:217], v[202:203], v[206:207] op_sel:[0,0,1] op_sel_hi:[1,1,0] neg_lo:[0,0,1]
	v_pk_mul_f32 v[202:203], v[222:223], v[202:203]
	v_pk_fma_f32 v[206:207], v[222:223], v[204:205], v[202:203] op_sel:[0,0,1] op_sel_hi:[1,1,0] neg_lo:[1,0,0] neg_hi:[1,0,0]
	v_pk_fma_f32 v[202:203], v[222:223], v[204:205], v[202:203] op_sel:[0,0,1] op_sel_hi:[1,1,0]
	v_mov_b32_e32 v205, v207
	v_mov_b32_e32 v204, v202
	v_pk_mul_f32 v[216:217], v[218:219], v[202:203] op_sel:[1,0] op_sel_hi:[0,0]
	v_pk_mov_b32 v[202:203], v[206:207], v[202:203] op_sel:[1,0]
	v_pk_mul_f32 v[204:205], v[222:223], v[204:205]
	v_pk_mul_f32 v[202:203], v[222:223], v[202:203]
	v_pk_add_f32 v[204:205], v[204:205], v[204:205] op_sel:[1,0] op_sel_hi:[1,0]
	v_pk_fma_f32 v[246:247], v[218:219], v[206:207], v[216:217] op_sel:[0,1,0] neg_lo:[0,0,1]
	v_pk_mul_f32 v[204:205], v[220:221], v[204:205] op_sel:[1,0] op_sel_hi:[0,1]
	v_pk_add_f32 v[202:203], v[202:203], v[202:203] op_sel:[0,1] op_sel_hi:[0,1] neg_lo:[0,1] neg_hi:[0,1]
	v_pk_fma_f32 v[206:207], v[220:221], v[202:203], v[204:205] neg_lo:[0,0,1]
	v_pk_add_f32 v[204:205], v[236:237], v[230:231]
	v_pk_add_f32 v[202:203], v[200:201], v[214:215]
	v_pk_add_f32 v[200:201], v[200:201], v[214:215] neg_lo:[0,1] neg_hi:[0,1]
	v_pk_add_f32 v[214:215], v[236:237], v[230:231] neg_lo:[0,1] neg_hi:[0,1]
	v_pk_add_f32 v[220:221], v[208:209], v[234:235]
	v_xor_b32_e32 v217, 0x80000000, v214
	v_mov_b32_e32 v216, v215
	v_pk_add_f32 v[208:209], v[208:209], v[234:235] neg_lo:[0,1] neg_hi:[0,1]
	v_pk_add_f32 v[214:215], v[202:203], v[204:205]
	v_pk_add_f32 v[218:219], v[200:201], v[216:217]
	v_pk_add_f32 v[202:203], v[202:203], v[204:205] neg_lo:[0,1] neg_hi:[0,1]
	v_pk_add_f32 v[200:201], v[200:201], v[216:217] neg_lo:[0,1] neg_hi:[0,1]
	v_pk_add_f32 v[204:205], v[238:239], v[224:225]
	v_pk_add_f32 v[216:217], v[238:239], v[224:225] neg_lo:[0,1] neg_hi:[0,1]
	v_xor_b32_e32 v223, 0x80000000, v208
	v_mov_b32_e32 v222, v209
	v_pk_add_f32 v[208:209], v[204:205], v[220:221]
	v_pk_add_f32 v[224:225], v[216:217], v[222:223]
	v_pk_add_f32 v[204:205], v[204:205], v[220:221] neg_lo:[0,1] neg_hi:[0,1]
	v_pk_add_f32 v[216:217], v[216:217], v[222:223] neg_lo:[0,1] neg_hi:[0,1]
	v_pk_add_f32 v[220:221], v[244:245], v[226:227]
	v_pk_add_f32 v[222:223], v[244:245], v[226:227] neg_lo:[0,1] neg_hi:[0,1]
	v_pk_add_f32 v[226:227], v[210:211], v[246:247]
	v_pk_add_f32 v[210:211], v[210:211], v[246:247] neg_lo:[0,1] neg_hi:[0,1]
	s_nop 0
	v_pk_add_f32 v[234:235], v[222:223], v[210:211] op_sel:[0,1] op_sel_hi:[1,0] neg_hi:[0,1]
	v_pk_add_f32 v[222:223], v[222:223], v[210:211] op_sel:[0,1] op_sel_hi:[1,0] neg_lo:[0,1]
	v_pk_add_f32 v[230:231], v[212:213], v[206:207]
	v_pk_add_f32 v[206:207], v[212:213], v[206:207] neg_lo:[0,1] neg_hi:[0,1]
	v_pk_add_f32 v[210:211], v[220:221], v[226:227]
	v_pk_add_f32 v[220:221], v[220:221], v[226:227] neg_lo:[0,1] neg_hi:[0,1]
	v_pk_add_f32 v[226:227], v[242:243], v[228:229]
	v_pk_add_f32 v[228:229], v[242:243], v[228:229] neg_lo:[0,1] neg_hi:[0,1]
	v_pk_add_f32 v[236:237], v[228:229], v[206:207] op_sel:[0,1] op_sel_hi:[1,0] neg_hi:[0,1]
	v_pk_add_f32 v[212:213], v[228:229], v[206:207] op_sel:[0,1] op_sel_hi:[1,0] neg_lo:[0,1]
	v_pk_mul_f32 v[228:229], v[224:225], s[24:25] op_sel_hi:[1,0]
	v_pk_add_f32 v[206:207], v[226:227], v[230:231]
	v_pk_add_f32 v[226:227], v[226:227], v[230:231] neg_lo:[0,1] neg_hi:[0,1]
	v_pk_fma_f32 v[230:231], v[224:225], s[26:27], v[228:229] op_sel:[0,0,1] op_sel_hi:[1,0,0] neg_hi:[0,0,1]
	s_nop 0
	v_pk_mul_f32 v[224:225], v[204:205], s[28:29] op_sel_hi:[1,0]
	s_nop 0
	v_pk_fma_f32 v[228:229], v[204:205], s[28:29], v[224:225] op_sel:[0,0,1] op_sel_hi:[1,0,0] neg_hi:[0,0,1]
	v_pk_mul_f32 v[224:225], v[216:217], s[26:27] op_sel_hi:[1,0]
	v_pk_fma_f32 v[238:239], v[216:217], s[24:25], v[224:225] op_sel:[0,0,1] op_sel_hi:[1,0,0] neg_hi:[0,0,1]
	s_nop 0
	v_pk_mul_f32 v[216:217], v[234:235], s[28:29] op_sel_hi:[1,0]
	s_nop 0
	v_pk_fma_f32 v[224:225], v[234:235], s[28:29], v[216:217] op_sel:[0,0,1] op_sel_hi:[1,0,0] neg_hi:[0,0,1]
	s_nop 0
	v_pk_fma_f32 v[216:217], v[220:221], 0, v[220:221] op_sel:[0,0,1] op_sel_hi:[1,0,0] neg_hi:[0,0,1]
	s_nop 0
	v_pk_mul_f32 v[220:221], v[222:223], s[30:31] op_sel_hi:[1,0]
	s_nop 0
	v_pk_fma_f32 v[234:235], v[222:223], s[30:31], v[220:221] op_sel:[0,0,1] op_sel_hi:[1,0,0] neg_lo:[0,0,1]
	v_pk_mul_f32 v[222:223], v[236:237], s[26:27] op_sel_hi:[1,0]
	v_pk_fma_f32 v[242:243], v[236:237], s[24:25], v[222:223] op_sel:[0,0,1] op_sel_hi:[1,0,0] neg_hi:[0,0,1]
	v_pk_add_f32 v[220:221], v[200:201], v[234:235]
	v_pk_mul_f32 v[222:223], v[226:227], s[30:31] op_sel_hi:[1,0]
	v_pk_add_f32 v[200:201], v[200:201], v[234:235] neg_lo:[0,1] neg_hi:[0,1]
	v_pk_fma_f32 v[236:237], v[226:227], s[30:31], v[222:223] op_sel:[0,0,1] op_sel_hi:[1,0,0] neg_lo:[0,0,1]
	s_nop 0
	v_pk_mul_f32 v[222:223], v[212:213], s[60:61] op_sel:[1,0]
	v_pk_add_f32 v[204:205], v[228:229], v[236:237]
	v_pk_fma_f32 v[212:213], v[212:213], s[34:35], v[222:223] op_sel_hi:[0,1,1]
	v_pk_add_f32 v[222:223], v[214:215], v[210:211]
	v_pk_add_f32 v[210:211], v[214:215], v[210:211] neg_lo:[0,1] neg_hi:[0,1]
	v_pk_add_f32 v[214:215], v[208:209], v[206:207]
	v_pk_add_f32 v[206:207], v[208:209], v[206:207] neg_lo:[0,1] neg_hi:[0,1]
	s_nop 0
	v_xor_b32_e32 v209, 0x80000000, v206
	v_mov_b32_e32 v208, v207
	v_pk_add_f32 v[206:207], v[222:223], v[214:215]
	v_pk_add_f32 v[226:227], v[210:211], v[208:209]
	v_pk_add_f32 v[214:215], v[222:223], v[214:215] neg_lo:[0,1] neg_hi:[0,1]
	v_pk_add_f32 v[208:209], v[210:211], v[208:209] neg_lo:[0,1] neg_hi:[0,1]
	v_pk_add_f32 v[210:211], v[218:219], v[224:225]
	v_pk_add_f32 v[218:219], v[218:219], v[224:225] neg_lo:[0,1] neg_hi:[0,1]
	v_pk_add_f32 v[222:223], v[230:231], v[242:243]
	v_pk_add_f32 v[224:225], v[230:231], v[242:243] neg_lo:[0,1] neg_hi:[0,1]
	s_nop 0
	v_xor_b32_e32 v231, 0x80000000, v224
	v_mov_b32_e32 v230, v225
	v_pk_add_f32 v[224:225], v[210:211], v[222:223]
	v_pk_add_f32 v[210:211], v[210:211], v[222:223] neg_lo:[0,1] neg_hi:[0,1]
	v_pk_add_f32 v[222:223], v[202:203], v[216:217]
	v_pk_add_f32 v[202:203], v[202:203], v[216:217] neg_lo:[0,1] neg_hi:[0,1]
	v_pk_add_f32 v[216:217], v[228:229], v[236:237] neg_lo:[0,1] neg_hi:[0,1]
	v_pk_add_f32 v[242:243], v[218:219], v[230:231]
	v_xor_b32_e32 v229, 0x80000000, v216
	v_mov_b32_e32 v228, v217
	v_pk_add_f32 v[216:217], v[222:223], v[204:205]
	v_pk_add_f32 v[204:205], v[222:223], v[204:205] neg_lo:[0,1] neg_hi:[0,1]
	v_pk_add_f32 v[222:223], v[238:239], v[212:213]
	v_pk_add_f32 v[212:213], v[238:239], v[212:213] neg_lo:[0,1] neg_hi:[0,1]
	v_pk_add_f32 v[218:219], v[218:219], v[230:231] neg_lo:[0,1] neg_hi:[0,1]
	v_pk_add_f32 v[230:231], v[202:203], v[228:229]
	v_pk_add_f32 v[202:203], v[202:203], v[228:229] neg_lo:[0,1] neg_hi:[0,1]
	v_xor_b32_e32 v229, 0x80000000, v212
	v_mov_b32_e32 v228, v213
	v_pk_add_f32 v[212:213], v[220:221], v[222:223]
	v_pk_add_f32 v[234:235], v[200:201], v[228:229]
	v_pk_add_f32 v[220:221], v[220:221], v[222:223] neg_lo:[0,1] neg_hi:[0,1]
	v_pk_add_f32 v[200:201], v[200:201], v[228:229] neg_lo:[0,1] neg_hi:[0,1]
	ds_write_b64 v181, v[206:207]
	ds_write_b64 v181, v[224:225] offset:2176
	ds_write_b64 v181, v[216:217] offset:4352
	ds_write_b64 v181, v[212:213] offset:6528
	ds_write_b64 v181, v[226:227] offset:8704
	ds_write_b64 v181, v[242:243] offset:10880
	ds_write_b64 v181, v[230:231] offset:13056
	ds_write_b64 v181, v[234:235] offset:15232
	ds_write_b64 v181, v[214:215] offset:17408
	ds_write_b64 v181, v[210:211] offset:19584
	ds_write_b64 v181, v[204:205] offset:21760
	ds_write_b64 v181, v[220:221] offset:23936
	ds_write_b64 v181, v[208:209] offset:26112
	ds_write_b64 v181, v[218:219] offset:28288
	ds_write_b64 v181, v[202:203] offset:30464
	ds_write_b64 v181, v[200:201] offset:32640
.LBB0_362:
	s_or_b64 exec, exec, s[2:3]
	v_mov_b32_e32 v200, v180
	s_waitcnt lgkmcnt(0)
	s_barrier
	s_nop 0
	v_cmp_gt_i32_e32 vcc, s56, v200
	s_and_saveexec_b64 s[2:3], vcc
	s_cbranch_execz .LBB0_364
	v_ashrrev_i32_e32 v181, 31, v200
	v_add_u32_sdwa v181, v200, v181 dst_sel:DWORD dst_unused:UNUSED_PAD src0_sel:DWORD src1_sel:BYTE_3
	v_ashrrev_i32_e32 v181, 8, v181
	v_mul_i32_i24_e32 v201, 0x100, v181
	v_sub_u32_e32 v233, v200, v201
	v_mul_i32_i24_e32 v181, 0x1100, v181
	v_lshlrev_b32_e32 v181, 3, v181
	v_ashrrev_i32_e32 v201, 4, v233
	v_add_u32_e32 v200, s57, v181
	v_lshlrev_b32_e32 v244, 3, v233
	v_lshlrev_b32_e32 v201, 3, v201
	v_add3_u32 v230, v200, v244, v201
	ds_read_b64 v[200:201], v230
	ds_read_b64 v[202:203], v230 offset:2176
	ds_read_b64 v[204:205], v230 offset:4352
	ds_read_b64 v[206:207], v230 offset:6528
	v_pk_mov_b32 v[208:209], v[42:43], v[42:43] op_sel:[1,0]
	v_pk_mov_b32 v[216:217], v[58:59], v[58:59] op_sel:[1,0]
	s_waitcnt lgkmcnt(3)
	v_pk_mul_f32 v[208:209], v[208:209], v[200:201] op_sel:[0,1]
	v_pk_mov_b32 v[224:225], v[74:75], v[74:75] op_sel:[1,0]
	v_pk_fma_f32 v[210:211], v[42:43], v[200:201], v[208:209] op_sel_hi:[1,0,1] neg_lo:[0,0,1]
	v_pk_mov_b32 v[234:235], v[92:93], v[92:93] op_sel:[1,0]
	v_pk_mov_b32 v[200:201], v[46:47], v[46:47] op_sel:[1,0]
	s_mov_b32 s35, s60
	s_waitcnt lgkmcnt(2)
	v_pk_mul_f32 v[200:201], v[200:201], v[202:203] op_sel:[0,1]
	v_add_u32_e32 v181, 0, v181
	v_pk_fma_f32 v[208:209], v[46:47], v[202:203], v[200:201] op_sel_hi:[1,0,1] neg_lo:[0,0,1]
	s_nop 0
	v_pk_mov_b32 v[200:201], v[50:51], v[50:51] op_sel:[1,0]
	s_waitcnt lgkmcnt(1)
	v_pk_mul_f32 v[200:201], v[200:201], v[204:205] op_sel:[0,1]
	s_nop 0
	v_pk_fma_f32 v[202:203], v[50:51], v[204:205], v[200:201] op_sel_hi:[1,0,1] neg_lo:[0,0,1]
	s_nop 0
	v_pk_mov_b32 v[200:201], v[54:55], v[54:55] op_sel:[1,0]
	s_waitcnt lgkmcnt(0)
	v_pk_mul_f32 v[200:201], v[200:201], v[206:207] op_sel:[0,1]
	s_nop 0
	v_pk_fma_f32 v[204:205], v[54:55], v[206:207], v[200:201] op_sel_hi:[1,0,1] neg_lo:[0,0,1]
	ds_read_b64 v[206:207], v230 offset:8704
	ds_read_b64 v[200:201], v230 offset:10880
	ds_read_b64 v[212:213], v230 offset:13056
	ds_read_b64 v[214:215], v230 offset:15232
	s_waitcnt lgkmcnt(3)
	v_pk_mul_f32 v[216:217], v[216:217], v[206:207] op_sel:[0,1]
	s_nop 0
	v_pk_fma_f32 v[218:219], v[58:59], v[206:207], v[216:217] op_sel_hi:[1,0,1] neg_lo:[0,0,1]
	s_nop 0
	v_pk_mov_b32 v[206:207], v[62:63], v[62:63] op_sel:[1,0]
	s_waitcnt lgkmcnt(2)
	v_pk_mul_f32 v[206:207], v[206:207], v[200:201] op_sel:[0,1]
	s_nop 0
	v_pk_fma_f32 v[216:217], v[62:63], v[200:201], v[206:207] op_sel_hi:[1,0,1] neg_lo:[0,0,1]
	s_nop 0
	v_pk_mov_b32 v[200:201], v[66:67], v[66:67] op_sel:[1,0]
	s_waitcnt lgkmcnt(1)
	v_pk_mul_f32 v[200:201], v[200:201], v[212:213] op_sel:[0,1]
	s_nop 0
	v_pk_fma_f32 v[206:207], v[66:67], v[212:213], v[200:201] op_sel_hi:[1,0,1] neg_lo:[0,0,1]
	s_nop 0
	v_pk_mov_b32 v[200:201], v[70:71], v[70:71] op_sel:[1,0]
	s_waitcnt lgkmcnt(0)
	v_pk_mul_f32 v[200:201], v[200:201], v[214:215] op_sel:[0,1]
	s_nop 0
	v_pk_fma_f32 v[212:213], v[70:71], v[214:215], v[200:201] op_sel_hi:[1,0,1] neg_lo:[0,0,1]
	ds_read_b64 v[214:215], v230 offset:17408
	ds_read_b64 v[200:201], v230 offset:19584
	ds_read_b64 v[220:221], v230 offset:21760
	ds_read_b64 v[222:223], v230 offset:23936
	s_waitcnt lgkmcnt(3)
	v_pk_mul_f32 v[224:225], v[224:225], v[214:215] op_sel:[0,1]
	s_nop 0
	v_pk_fma_f32 v[226:227], v[74:75], v[214:215], v[224:225] op_sel_hi:[1,0,1] neg_lo:[0,0,1]
	s_nop 0
	v_pk_mov_b32 v[214:215], v[78:79], v[78:79] op_sel:[1,0]
	s_waitcnt lgkmcnt(2)
	v_pk_mul_f32 v[214:215], v[214:215], v[200:201] op_sel:[0,1]
	s_nop 0
	v_pk_fma_f32 v[224:225], v[78:79], v[200:201], v[214:215] op_sel_hi:[1,0,1] neg_lo:[0,0,1]
	s_nop 0
	v_pk_mov_b32 v[200:201], v[84:85], v[84:85] op_sel:[1,0]
	s_waitcnt lgkmcnt(1)
	v_pk_mul_f32 v[200:201], v[200:201], v[220:221] op_sel:[0,1]
	s_nop 0
	v_pk_fma_f32 v[214:215], v[84:85], v[220:221], v[200:201] op_sel_hi:[1,0,1] neg_lo:[0,0,1]
	s_nop 0
	v_pk_mov_b32 v[200:201], v[88:89], v[88:89] op_sel:[1,0]
	s_waitcnt lgkmcnt(0)
	v_pk_mul_f32 v[200:201], v[200:201], v[222:223] op_sel:[0,1]
	s_nop 0
	v_pk_fma_f32 v[220:221], v[88:89], v[222:223], v[200:201] op_sel_hi:[1,0,1] neg_lo:[0,0,1]
	ds_read_b64 v[222:223], v230 offset:26112
	ds_read_b64 v[200:201], v230 offset:28288
	ds_read_b64 v[228:229], v230 offset:30464
	ds_read_b64 v[230:231], v230 offset:32640
	s_waitcnt lgkmcnt(3)
	v_pk_mul_f32 v[234:235], v[234:235], v[222:223] op_sel:[0,1]
	s_nop 0
	v_pk_fma_f32 v[236:237], v[92:93], v[222:223], v[234:235] op_sel_hi:[1,0,1] neg_lo:[0,0,1]
	s_nop 0
	v_pk_mov_b32 v[222:223], v[98:99], v[98:99] op_sel:[1,0]
	s_waitcnt lgkmcnt(2)
	v_pk_mul_f32 v[222:223], v[222:223], v[200:201] op_sel:[0,1]
	s_nop 0
	v_pk_fma_f32 v[234:235], v[98:99], v[200:201], v[222:223] op_sel_hi:[1,0,1] neg_lo:[0,0,1]
	s_nop 0
	v_pk_mov_b32 v[200:201], v[102:103], v[102:103] op_sel:[1,0]
	s_waitcnt lgkmcnt(1)
	v_pk_mul_f32 v[200:201], v[200:201], v[228:229] op_sel:[0,1]
	s_nop 0
	v_pk_fma_f32 v[222:223], v[102:103], v[228:229], v[200:201] op_sel_hi:[1,0,1] neg_lo:[0,0,1]
	s_nop 0
	v_pk_mov_b32 v[200:201], v[106:107], v[106:107] op_sel:[1,0]
	s_waitcnt lgkmcnt(0)
	v_pk_mul_f32 v[200:201], v[200:201], v[230:231] op_sel:[0,1]
	s_nop 0
	v_pk_fma_f32 v[228:229], v[106:107], v[230:231], v[200:201] op_sel_hi:[1,0,1] neg_lo:[0,0,1]
	s_nop 0
	v_pk_add_f32 v[200:201], v[210:211], v[226:227]
	v_pk_add_f32 v[210:211], v[210:211], v[226:227] neg_lo:[0,1] neg_hi:[0,1]
	v_pk_add_f32 v[226:227], v[218:219], v[236:237]
	v_pk_add_f32 v[218:219], v[218:219], v[236:237] neg_lo:[0,1] neg_hi:[0,1]
	s_nop 0
	v_xor_b32_e32 v230, 0x80000000, v219
	v_mov_b32_e32 v231, v218
	v_pk_add_f32 v[218:219], v[200:201], v[226:227]
	v_pk_add_f32 v[200:201], v[200:201], v[226:227] neg_lo:[0,1] neg_hi:[0,1]
	v_pk_add_f32 v[226:227], v[208:209], v[224:225]
	v_pk_add_f32 v[208:209], v[208:209], v[224:225] neg_lo:[0,1] neg_hi:[0,1]
	v_pk_add_f32 v[224:225], v[216:217], v[234:235]
	v_pk_add_f32 v[216:217], v[216:217], v[234:235] neg_lo:[0,1] neg_hi:[0,1]
	v_pk_add_f32 v[236:237], v[210:211], v[230:231]
	v_pk_add_f32 v[210:211], v[210:211], v[230:231] neg_lo:[0,1] neg_hi:[0,1]
	v_xor_b32_e32 v230, 0x80000000, v217
	v_mov_b32_e32 v231, v216
	v_pk_add_f32 v[216:217], v[226:227], v[224:225]
	v_pk_add_f32 v[224:225], v[226:227], v[224:225] neg_lo:[0,1] neg_hi:[0,1]
	v_pk_add_f32 v[226:227], v[202:203], v[214:215]
	v_pk_add_f32 v[202:203], v[202:203], v[214:215] neg_lo:[0,1] neg_hi:[0,1]
	v_pk_add_f32 v[214:215], v[206:207], v[222:223]
	v_pk_add_f32 v[206:207], v[206:207], v[222:223] neg_lo:[0,1] neg_hi:[0,1]
	v_pk_add_f32 v[234:235], v[208:209], v[230:231]
	v_pk_add_f32 v[208:209], v[208:209], v[230:231] neg_lo:[0,1] neg_hi:[0,1]
	v_pk_add_f32 v[230:231], v[202:203], v[206:207] op_sel:[0,1] op_sel_hi:[1,0] neg_lo:[0,1]
	v_pk_add_f32 v[202:203], v[202:203], v[206:207] op_sel:[0,1] op_sel_hi:[1,0] neg_hi:[0,1]
	v_pk_add_f32 v[222:223], v[204:205], v[220:221]
	v_pk_add_f32 v[204:205], v[204:205], v[220:221] neg_lo:[0,1] neg_hi:[0,1]
	v_pk_add_f32 v[220:221], v[212:213], v[228:229]
	v_pk_add_f32 v[212:213], v[212:213], v[228:229] neg_lo:[0,1] neg_hi:[0,1]
	v_pk_add_f32 v[206:207], v[226:227], v[214:215]
	v_pk_add_f32 v[214:215], v[226:227], v[214:215] neg_lo:[0,1] neg_hi:[0,1]
	v_xor_b32_e32 v226, 0x80000000, v213
	v_mov_b32_e32 v227, v212
	v_pk_add_f32 v[212:213], v[222:223], v[220:221]
	v_pk_add_f32 v[220:221], v[222:223], v[220:221] neg_lo:[0,1] neg_hi:[0,1]
	v_pk_mul_f32 v[222:223], v[234:235], s[24:25] op_sel_hi:[1,0]
	v_pk_add_f32 v[228:229], v[204:205], v[226:227]
	v_pk_add_f32 v[204:205], v[204:205], v[226:227] neg_lo:[0,1] neg_hi:[0,1]
	v_pk_fma_f32 v[226:227], v[234:235], s[26:27], v[222:223] op_sel:[0,0,1] op_sel_hi:[1,0,0] neg_lo:[0,0,1]
	s_nop 0
	v_pk_mul_f32 v[222:223], v[224:225], s[28:29] op_sel_hi:[1,0]
	s_nop 0
	v_pk_fma_f32 v[234:235], v[224:225], s[28:29], v[222:223] op_sel:[0,0,1] op_sel_hi:[1,0,0] neg_lo:[0,0,1]
	v_pk_mul_f32 v[224:225], v[208:209], s[26:27] op_sel_hi:[1,0]
	v_pk_fma_f32 v[238:239], v[208:209], s[24:25], v[224:225] op_sel:[0,0,1] op_sel_hi:[1,0,0] neg_lo:[0,0,1]
	s_nop 0
	v_pk_mul_f32 v[208:209], v[230:231], s[28:29] op_sel_hi:[1,0]
	s_nop 0
	v_pk_fma_f32 v[224:225], v[230:231], s[28:29], v[208:209] op_sel:[0,0,1] op_sel_hi:[1,0,0] neg_lo:[0,0,1]
	s_nop 0
	v_pk_fma_f32 v[208:209], v[214:215], 0, v[214:215] op_sel:[0,0,1] op_sel_hi:[1,0,0] neg_lo:[0,0,1]
	s_nop 0
	v_pk_mul_f32 v[214:215], v[202:203], s[30:31] op_sel_hi:[1,0]
	s_nop 0
	v_pk_fma_f32 v[230:231], v[202:203], s[30:31], v[214:215] op_sel:[0,0,1] op_sel_hi:[1,0,0] neg_hi:[0,0,1]
	v_pk_mul_f32 v[214:215], v[228:229], s[26:27] op_sel_hi:[1,0]
	v_pk_fma_f32 v[242:243], v[228:229], s[24:25], v[214:215] op_sel:[0,0,1] op_sel_hi:[1,0,0] neg_lo:[0,0,1]
	s_mov_b32 s25, s34
	v_pk_mul_f32 v[214:215], v[220:221], s[30:31] op_sel_hi:[1,0]
	v_pk_add_f32 v[202:203], v[210:211], v[230:231]
	v_pk_fma_f32 v[228:229], v[220:221], s[30:31], v[214:215] op_sel:[0,0,1] op_sel_hi:[1,0,0] neg_hi:[0,0,1]
	v_pk_add_f32 v[210:211], v[210:211], v[230:231] neg_lo:[0,1] neg_hi:[0,1]
	v_pk_mul_f32 v[214:215], v[204:205], s[34:35] op_sel_hi:[0,1]
	v_pk_fma_f32 v[204:205], v[204:205], s[24:25], v[214:215] op_sel:[1,0,0]
	v_pk_add_f32 v[214:215], v[218:219], v[206:207]
	v_pk_add_f32 v[206:207], v[218:219], v[206:207] neg_lo:[0,1] neg_hi:[0,1]
	v_pk_add_f32 v[218:219], v[216:217], v[212:213]
	v_pk_add_f32 v[212:213], v[216:217], v[212:213] neg_lo:[0,1] neg_hi:[0,1]
	v_pk_add_f32 v[222:223], v[234:235], v[228:229] neg_lo:[0,1] neg_hi:[0,1]
	v_xor_b32_e32 v216, 0x80000000, v213
	v_mov_b32_e32 v217, v212
	v_pk_add_f32 v[212:213], v[214:215], v[218:219]
	v_pk_add_f32 v[220:221], v[206:207], v[216:217]
	v_pk_add_f32 v[214:215], v[214:215], v[218:219] neg_lo:[0,1] neg_hi:[0,1]
	v_pk_add_f32 v[206:207], v[206:207], v[216:217] neg_lo:[0,1] neg_hi:[0,1]
	v_pk_add_f32 v[216:217], v[236:237], v[224:225]
	v_pk_add_f32 v[218:219], v[236:237], v[224:225] neg_lo:[0,1] neg_hi:[0,1]
	v_pk_add_f32 v[224:225], v[226:227], v[242:243]
	v_pk_add_f32 v[226:227], v[226:227], v[242:243] neg_lo:[0,1] neg_hi:[0,1]
	s_nop 0
	v_xor_b32_e32 v236, 0x80000000, v227
	v_mov_b32_e32 v237, v226
	v_pk_add_f32 v[226:227], v[216:217], v[224:225]
	v_pk_add_f32 v[216:217], v[216:217], v[224:225] neg_lo:[0,1] neg_hi:[0,1]
	v_pk_add_f32 v[224:225], v[200:201], v[208:209]
	v_pk_add_f32 v[200:201], v[200:201], v[208:209] neg_lo:[0,1] neg_hi:[0,1]
	v_pk_add_f32 v[208:209], v[234:235], v[228:229]
	v_xor_b32_e32 v228, 0x80000000, v223
	v_mov_b32_e32 v229, v222
	v_pk_add_f32 v[222:223], v[224:225], v[208:209]
	v_pk_add_f32 v[208:209], v[224:225], v[208:209] neg_lo:[0,1] neg_hi:[0,1]
	v_pk_add_f32 v[224:225], v[238:239], v[204:205]
	v_pk_add_f32 v[204:205], v[238:239], v[204:205] neg_lo:[0,1] neg_hi:[0,1]
	v_pk_add_f32 v[234:235], v[200:201], v[228:229]
	v_pk_add_f32 v[200:201], v[200:201], v[228:229] neg_lo:[0,1] neg_hi:[0,1]
	v_xor_b32_e32 v228, 0x80000000, v205
	v_mov_b32_e32 v229, v204
	v_pk_add_f32 v[204:205], v[202:203], v[224:225]
	v_pk_add_f32 v[202:203], v[202:203], v[224:225] neg_lo:[0,1] neg_hi:[0,1]
	v_lshlrev_b32_e32 v224, 7, v233
	v_add3_u32 v181, v181, v224, v244
	v_add_u32_e32 v224, 0x1880, v181
	ds_write2_b64 v224, v[212:213], v[226:227] offset1:1
	v_add_u32_e32 v212, 0x1890, v181
	v_pk_add_f32 v[242:243], v[218:219], v[236:237]
	ds_write2_b64 v212, v[222:223], v[204:205] offset1:1
	v_add_u32_e32 v204, 0x18a0, v181
	v_pk_add_f32 v[230:231], v[210:211], v[228:229]
	ds_write2_b64 v204, v[220:221], v[242:243] offset1:1
	v_add_u32_e32 v204, 0x18b0, v181
	ds_write2_b64 v204, v[234:235], v[230:231] offset1:1
	v_add_u32_e32 v204, 0x18c0, v181
	ds_write2_b64 v204, v[214:215], v[216:217] offset1:1
	v_add_u32_e32 v204, 0x18d0, v181
	v_pk_add_f32 v[218:219], v[218:219], v[236:237] neg_lo:[0,1] neg_hi:[0,1]
	v_pk_add_f32 v[210:211], v[210:211], v[228:229] neg_lo:[0,1] neg_hi:[0,1]
	ds_write2_b64 v204, v[208:209], v[202:203] offset1:1
	v_add_u32_e32 v202, 0x18e0, v181
	v_add_u32_e32 v181, 0x18f0, v181
	ds_write2_b64 v202, v[206:207], v[218:219] offset1:1
	ds_write2_b64 v181, v[200:201], v[210:211] offset1:1

.LBB0_366:
	s_or_b64 exec, exec, s[2:3]
	v_mov_b32_e32 v200, v180
	s_waitcnt lgkmcnt(0)
	s_barrier
	s_nop 0
	v_cmp_gt_i32_e32 vcc, s56, v200
	s_and_saveexec_b64 s[2:3], vcc
	s_cbranch_execz .LBB0_368
	v_ashrrev_i32_e32 v181, 31, v200
	v_add_u32_sdwa v181, v200, v181 dst_sel:DWORD dst_unused:UNUSED_PAD src0_sel:DWORD src1_sel:BYTE_3
	v_ashrrev_i32_e32 v181, 8, v181
	v_mul_i32_i24_e32 v201, 0x100, v181
	v_sub_u32_e32 v200, v200, v201
	v_mul_i32_i24_e32 v181, 0x1100, v181
	v_lshlrev_b32_e32 v181, 3, v181
	v_lshlrev_b32_e32 v224, 3, v200
	v_ashrrev_i32_e32 v200, 4, v200
	v_add_u32_e32 v201, s57, v181
	v_lshlrev_b32_e32 v233, 3, v200
	v_add3_u32 v234, v201, v224, v233
	v_add_u32_e32 v248, 0, v224
	ds_read_b64 v[200:201], v234
	ds_read_b64 v[202:203], v234 offset:2176
	ds_read_b64 v[204:205], v234 offset:4352
	ds_read_b64 v[206:207], v234 offset:6528
	ds_read_b64 v[208:209], v234 offset:8704
	ds_read_b64 v[210:211], v234 offset:10880
	ds_read_b64 v[212:213], v234 offset:13056
	ds_read_b64 v[214:215], v234 offset:15232
	ds_read_b64 v[216:217], v234 offset:17408
	ds_read_b64 v[218:219], v234 offset:19584
	ds_read_b64 v[220:221], v234 offset:21760
	ds_read_b64 v[222:223], v234 offset:23936
	ds_read_b64 v[224:225], v248
	ds_read_b64 v[226:227], v234 offset:26112
	ds_read_b64 v[228:229], v234 offset:28288
	ds_read_b64 v[230:231], v234 offset:30464
	ds_read_b64 v[234:235], v234 offset:32640
	s_waitcnt lgkmcnt(4)
	v_pk_mul_f32 v[238:239], v[202:203], v[224:225] op_sel:[0,1]
	v_xor_b32_e32 v236, 0x80000000, v225
	v_pk_fma_f32 v[242:243], v[202:203], v[224:225], v[238:239] op_sel:[0,0,1] op_sel_hi:[1,0,0] neg_hi:[0,0,1]
	v_mov_b32_e32 v237, v224
	v_pk_mul_f32 v[202:203], v[224:225], v[224:225] op_sel:[1,0]
	s_mov_b32 s35, s60
	v_pk_fma_f32 v[202:203], v[224:225], v[236:237], v[202:203] op_sel_hi:[0,1,1] neg_lo:[0,0,1] neg_hi:[0,0,1]
	v_pk_mul_f32 v[236:237], v[204:205], v[202:203] op_sel:[1,0] op_sel_hi:[0,0]
	v_pk_fma_f32 v[238:239], v[204:205], v[202:203], v[236:237] op_sel:[0,1,0] neg_lo:[0,0,1]
	v_add3_u32 v181, v248, v181, v233
	v_pk_mul_f32 v[204:205], v[224:225], v[202:203] op_sel:[0,1] op_sel_hi:[1,0]
	v_pk_mul_f32 v[202:203], v[224:225], v[202:203]
	v_pk_add_f32 v[204:205], v[204:205], v[204:205] op_sel:[0,1] op_sel_hi:[0,1]
	v_pk_add_f32 v[202:203], v[202:203], v[202:203] op_sel:[0,1] op_sel_hi:[0,1] neg_lo:[0,1] neg_hi:[0,1]
	v_pk_mul_f32 v[236:237], v[206:207], v[202:203]
	s_nop 0
	v_pk_fma_f32 v[244:245], v[206:207], v[204:205], v[236:237] op_sel:[0,0,1] op_sel_hi:[1,1,0] neg_lo:[0,0,1]
	v_pk_mul_f32 v[204:205], v[224:225], v[204:205]
	v_pk_fma_f32 v[206:207], v[224:225], v[202:203], v[204:205] op_sel:[0,0,1] op_sel_hi:[1,1,0] neg_lo:[0,0,1] neg_hi:[0,0,1]
	v_pk_fma_f32 v[202:203], v[224:225], v[202:203], v[204:205] op_sel:[0,0,1] op_sel_hi:[1,1,0]
	v_mov_b32_e32 v204, v206
	v_mov_b32_e32 v205, v203
	v_pk_mul_f32 v[236:237], v[208:209], v[206:207] op_sel:[1,0] op_sel_hi:[0,0]
	v_pk_mov_b32 v[206:207], v[202:203], v[206:207] op_sel:[1,0]
	v_pk_fma_f32 v[246:247], v[208:209], v[202:203], v[236:237] op_sel:[0,1,0] neg_lo:[0,0,1]
	v_pk_mul_f32 v[204:205], v[224:225], v[204:205]
	v_pk_mul_f32 v[202:203], v[224:225], v[206:207]
	v_pk_add_f32 v[204:205], v[204:205], v[204:205] op_sel:[0,1] op_sel_hi:[0,1] neg_lo:[0,1] neg_hi:[0,1]
	v_pk_mul_f32 v[206:207], v[210:211], v[204:205]
	v_pk_add_f32 v[202:203], v[202:203], v[202:203] op_sel:[0,1] op_sel_hi:[0,1]
	v_pk_fma_f32 v[208:209], v[210:211], v[202:203], v[206:207] op_sel:[0,0,1] op_sel_hi:[1,1,0] neg_lo:[0,0,1]
	v_pk_mul_f32 v[202:203], v[224:225], v[202:203]
	v_pk_fma_f32 v[206:207], v[224:225], v[204:205], v[202:203] op_sel:[0,0,1] op_sel_hi:[1,1,0] neg_lo:[0,0,1] neg_hi:[0,0,1]
	v_pk_fma_f32 v[202:203], v[224:225], v[204:205], v[202:203] op_sel:[0,0,1] op_sel_hi:[1,1,0]
	v_mov_b32_e32 v204, v206
	v_mov_b32_e32 v205, v203
	v_pk_mul_f32 v[210:211], v[212:213], v[206:207] op_sel:[1,0] op_sel_hi:[0,0]
	v_pk_mov_b32 v[206:207], v[202:203], v[206:207] op_sel:[1,0]
	v_pk_fma_f32 v[236:237], v[212:213], v[202:203], v[210:211] op_sel:[0,1,0] neg_lo:[0,0,1]
	v_pk_mul_f32 v[204:205], v[224:225], v[204:205]
	v_pk_mul_f32 v[202:203], v[224:225], v[206:207]
	v_pk_add_f32 v[204:205], v[204:205], v[204:205] op_sel:[0,1] op_sel_hi:[0,1] neg_lo:[0,1] neg_hi:[0,1]
	v_pk_mul_f32 v[206:207], v[214:215], v[204:205]
	v_pk_add_f32 v[202:203], v[202:203], v[202:203] op_sel:[0,1] op_sel_hi:[0,1]
	v_pk_fma_f32 v[210:211], v[214:215], v[202:203], v[206:207] op_sel:[0,0,1] op_sel_hi:[1,1,0] neg_lo:[0,0,1]
	v_pk_mul_f32 v[202:203], v[224:225], v[202:203]
	v_pk_fma_f32 v[206:207], v[224:225], v[204:205], v[202:203] op_sel:[0,0,1] op_sel_hi:[1,1,0] neg_lo:[0,0,1] neg_hi:[0,0,1]
	v_pk_fma_f32 v[202:203], v[224:225], v[204:205], v[202:203] op_sel:[0,0,1] op_sel_hi:[1,1,0]
	v_mov_b32_e32 v204, v206
	v_mov_b32_e32 v205, v203
	v_pk_mul_f32 v[212:213], v[216:217], v[206:207] op_sel:[1,0] op_sel_hi:[0,0]
	v_pk_mov_b32 v[206:207], v[202:203], v[206:207] op_sel:[1,0]
	v_pk_fma_f32 v[214:215], v[216:217], v[202:203], v[212:213] op_sel:[0,1,0] neg_lo:[0,0,1]
	v_pk_mul_f32 v[204:205], v[224:225], v[204:205]
	v_pk_mul_f32 v[202:203], v[224:225], v[206:207]
	v_pk_add_f32 v[204:205], v[204:205], v[204:205] op_sel:[0,1] op_sel_hi:[0,1] neg_lo:[0,1] neg_hi:[0,1]
	v_pk_mul_f32 v[206:207], v[218:219], v[204:205]
	v_pk_add_f32 v[202:203], v[202:203], v[202:203] op_sel:[0,1] op_sel_hi:[0,1]
	v_pk_fma_f32 v[212:213], v[218:219], v[202:203], v[206:207] op_sel:[0,0,1] op_sel_hi:[1,1,0] neg_lo:[0,0,1]
	v_pk_mul_f32 v[202:203], v[224:225], v[202:203]
	v_pk_fma_f32 v[206:207], v[224:225], v[204:205], v[202:203] op_sel:[0,0,1] op_sel_hi:[1,1,0] neg_lo:[0,0,1] neg_hi:[0,0,1]
	v_pk_fma_f32 v[202:203], v[224:225], v[204:205], v[202:203] op_sel:[0,0,1] op_sel_hi:[1,1,0]
	v_mov_b32_e32 v204, v206
	v_mov_b32_e32 v205, v203
	v_pk_mul_f32 v[216:217], v[220:221], v[206:207] op_sel:[1,0] op_sel_hi:[0,0]
	v_pk_mov_b32 v[206:207], v[202:203], v[206:207] op_sel:[1,0]
	v_pk_fma_f32 v[218:219], v[220:221], v[202:203], v[216:217] op_sel:[0,1,0] neg_lo:[0,0,1]
	v_pk_mul_f32 v[204:205], v[224:225], v[204:205]
	v_pk_mul_f32 v[202:203], v[224:225], v[206:207]
	v_pk_add_f32 v[204:205], v[204:205], v[204:205] op_sel:[0,1] op_sel_hi:[0,1] neg_lo:[0,1] neg_hi:[0,1]
	v_pk_mul_f32 v[206:207], v[222:223], v[204:205]
	v_pk_add_f32 v[202:203], v[202:203], v[202:203] op_sel:[0,1] op_sel_hi:[0,1]
	v_pk_fma_f32 v[216:217], v[222:223], v[202:203], v[206:207] op_sel:[0,0,1] op_sel_hi:[1,1,0] neg_lo:[0,0,1]
	v_pk_mul_f32 v[202:203], v[224:225], v[202:203]
	v_pk_fma_f32 v[206:207], v[224:225], v[204:205], v[202:203] op_sel:[0,0,1] op_sel_hi:[1,1,0] neg_lo:[0,0,1] neg_hi:[0,0,1]
	v_pk_fma_f32 v[202:203], v[224:225], v[204:205], v[202:203] op_sel:[0,0,1] op_sel_hi:[1,1,0]
	v_mov_b32_e32 v204, v206
	v_mov_b32_e32 v205, v203
	s_waitcnt lgkmcnt(3)
	v_pk_mul_f32 v[220:221], v[226:227], v[206:207] op_sel:[1,0] op_sel_hi:[0,0]
	v_pk_mov_b32 v[206:207], v[202:203], v[206:207] op_sel:[1,0]
	v_pk_fma_f32 v[222:223], v[226:227], v[202:203], v[220:221] op_sel:[0,1,0] neg_lo:[0,0,1]
	v_pk_mul_f32 v[204:205], v[224:225], v[204:205]
	v_pk_mul_f32 v[202:203], v[224:225], v[206:207]
	v_pk_add_f32 v[204:205], v[204:205], v[204:205] op_sel:[0,1] op_sel_hi:[0,1] neg_lo:[0,1] neg_hi:[0,1]
	s_waitcnt lgkmcnt(2)
	v_pk_mul_f32 v[206:207], v[228:229], v[204:205]
	v_pk_add_f32 v[202:203], v[202:203], v[202:203] op_sel:[0,1] op_sel_hi:[0,1]
	v_pk_fma_f32 v[220:221], v[228:229], v[202:203], v[206:207] op_sel:[0,0,1] op_sel_hi:[1,1,0] neg_lo:[0,0,1]
	v_pk_mul_f32 v[202:203], v[224:225], v[202:203]
	v_pk_fma_f32 v[206:207], v[224:225], v[204:205], v[202:203] op_sel:[0,0,1] op_sel_hi:[1,1,0] neg_lo:[0,0,1] neg_hi:[0,0,1]
	v_pk_fma_f32 v[202:203], v[224:225], v[204:205], v[202:203] op_sel:[0,0,1] op_sel_hi:[1,1,0]
	v_mov_b32_e32 v204, v206
	v_mov_b32_e32 v205, v203
	s_waitcnt lgkmcnt(1)
	v_pk_mul_f32 v[226:227], v[230:231], v[206:207] op_sel:[1,0] op_sel_hi:[0,0]
	v_pk_mov_b32 v[206:207], v[202:203], v[206:207] op_sel:[1,0]
	v_pk_fma_f32 v[228:229], v[230:231], v[202:203], v[226:227] op_sel:[0,1,0] neg_lo:[0,0,1]
	v_pk_mul_f32 v[204:205], v[224:225], v[204:205]
	v_pk_mul_f32 v[202:203], v[224:225], v[206:207]
	v_pk_add_f32 v[204:205], v[204:205], v[204:205] op_sel:[0,1] op_sel_hi:[0,1] neg_lo:[0,1] neg_hi:[0,1]
	s_waitcnt lgkmcnt(0)
	v_pk_mul_f32 v[204:205], v[234:235], v[204:205] op_sel:[1,0] op_sel_hi:[0,1]
	v_pk_add_f32 v[202:203], v[202:203], v[202:203] op_sel:[0,1] op_sel_hi:[0,1]
	v_pk_fma_f32 v[206:207], v[234:235], v[202:203], v[204:205] neg_lo:[0,0,1]
	v_pk_add_f32 v[204:205], v[246:247], v[222:223]
	v_pk_add_f32 v[202:203], v[200:201], v[214:215]
	v_pk_add_f32 v[200:201], v[200:201], v[214:215] neg_lo:[0,1] neg_hi:[0,1]
	v_pk_add_f32 v[214:215], v[246:247], v[222:223] neg_lo:[0,1] neg_hi:[0,1]
	s_nop 0
	v_xor_b32_e32 v222, 0x80000000, v215
	v_mov_b32_e32 v223, v214
	v_pk_add_f32 v[214:215], v[202:203], v[204:205]
	v_pk_add_f32 v[224:225], v[200:201], v[222:223]
	v_pk_add_f32 v[202:203], v[202:203], v[204:205] neg_lo:[0,1] neg_hi:[0,1]
	v_pk_add_f32 v[200:201], v[200:201], v[222:223] neg_lo:[0,1] neg_hi:[0,1]
	v_pk_add_f32 v[204:205], v[242:243], v[212:213]
	v_pk_add_f32 v[222:223], v[208:209], v[220:221]
	v_pk_add_f32 v[208:209], v[208:209], v[220:221] neg_lo:[0,1] neg_hi:[0,1]
	v_pk_add_f32 v[212:213], v[242:243], v[212:213] neg_lo:[0,1] neg_hi:[0,1]
	v_xor_b32_e32 v220, 0x80000000, v209
	v_mov_b32_e32 v221, v208
	v_pk_add_f32 v[208:209], v[204:205], v[222:223]
	v_pk_add_f32 v[204:205], v[204:205], v[222:223] neg_lo:[0,1] neg_hi:[0,1]
	v_pk_add_f32 v[222:223], v[236:237], v[228:229]
	v_pk_add_f32 v[228:229], v[236:237], v[228:229] neg_lo:[0,1] neg_hi:[0,1]
	v_pk_add_f32 v[226:227], v[212:213], v[220:221]
	v_pk_add_f32 v[212:213], v[212:213], v[220:221] neg_lo:[0,1] neg_hi:[0,1]
	v_pk_add_f32 v[220:221], v[238:239], v[218:219]
	v_pk_add_f32 v[218:219], v[238:239], v[218:219] neg_lo:[0,1] neg_hi:[0,1]
	v_pk_add_f32 v[234:235], v[218:219], v[228:229] op_sel:[0,1] op_sel_hi:[1,0] neg_lo:[0,1]
	v_pk_add_f32 v[218:219], v[218:219], v[228:229] op_sel:[0,1] op_sel_hi:[1,0] neg_hi:[0,1]
	v_pk_add_f32 v[230:231], v[210:211], v[206:207]
	v_pk_add_f32 v[206:207], v[210:211], v[206:207] neg_lo:[0,1] neg_hi:[0,1]
	v_pk_add_f32 v[228:229], v[220:221], v[222:223]
	v_pk_add_f32 v[220:221], v[220:221], v[222:223] neg_lo:[0,1] neg_hi:[0,1]
	v_pk_add_f32 v[222:223], v[244:245], v[216:217]
	v_pk_add_f32 v[216:217], v[244:245], v[216:217] neg_lo:[0,1] neg_hi:[0,1]
	v_pk_add_f32 v[236:237], v[216:217], v[206:207] op_sel:[0,1] op_sel_hi:[1,0] neg_lo:[0,1]
	v_pk_add_f32 v[210:211], v[216:217], v[206:207] op_sel:[0,1] op_sel_hi:[1,0] neg_hi:[0,1]
	v_pk_mul_f32 v[216:217], v[226:227], s[24:25] op_sel_hi:[1,0]
	v_pk_add_f32 v[206:207], v[222:223], v[230:231]
	v_pk_add_f32 v[222:223], v[222:223], v[230:231] neg_lo:[0,1] neg_hi:[0,1]
	v_pk_fma_f32 v[230:231], v[226:227], s[26:27], v[216:217] op_sel:[0,0,1] op_sel_hi:[1,0,0] neg_lo:[0,0,1]
	s_nop 0
	v_pk_mul_f32 v[216:217], v[204:205], s[28:29] op_sel_hi:[1,0]
	s_nop 0
	v_pk_fma_f32 v[226:227], v[204:205], s[28:29], v[216:217] op_sel:[0,0,1] op_sel_hi:[1,0,0] neg_lo:[0,0,1]
	v_pk_mul_f32 v[216:217], v[212:213], s[26:27] op_sel_hi:[1,0]
	v_pk_fma_f32 v[238:239], v[212:213], s[24:25], v[216:217] op_sel:[0,0,1] op_sel_hi:[1,0,0] neg_lo:[0,0,1]
	s_nop 0
	v_pk_mul_f32 v[212:213], v[234:235], s[28:29] op_sel_hi:[1,0]
	s_nop 0
	v_pk_fma_f32 v[216:217], v[234:235], s[28:29], v[212:213] op_sel:[0,0,1] op_sel_hi:[1,0,0] neg_lo:[0,0,1]
	s_nop 0
	v_pk_fma_f32 v[212:213], v[220:221], 0, v[220:221] op_sel:[0,0,1] op_sel_hi:[1,0,0] neg_lo:[0,0,1]
	s_nop 0
	v_pk_mul_f32 v[220:221], v[218:219], s[30:31] op_sel_hi:[1,0]
	s_nop 0
	v_pk_fma_f32 v[234:235], v[218:219], s[30:31], v[220:221] op_sel:[0,0,1] op_sel_hi:[1,0,0] neg_hi:[0,0,1]
	v_pk_mul_f32 v[220:221], v[236:237], s[26:27] op_sel_hi:[1,0]
	v_pk_fma_f32 v[242:243], v[236:237], s[24:25], v[220:221] op_sel:[0,0,1] op_sel_hi:[1,0,0] neg_lo:[0,0,1]
	s_mov_b32 s25, s34
	v_pk_mul_f32 v[220:221], v[222:223], s[30:31] op_sel_hi:[1,0]
	v_pk_add_f32 v[218:219], v[200:201], v[234:235]
	v_pk_fma_f32 v[236:237], v[222:223], s[30:31], v[220:221] op_sel:[0,0,1] op_sel_hi:[1,0,0] neg_hi:[0,0,1]
	v_pk_add_f32 v[222:223], v[208:209], v[206:207]
	v_pk_mul_f32 v[220:221], v[210:211], s[34:35] op_sel_hi:[0,1]
	v_pk_add_f32 v[206:207], v[208:209], v[206:207] neg_lo:[0,1] neg_hi:[0,1]
	v_pk_fma_f32 v[210:211], v[210:211], s[24:25], v[220:221] op_sel:[1,0,0]
	v_pk_add_f32 v[220:221], v[214:215], v[228:229]
	v_pk_add_f32 v[214:215], v[214:215], v[228:229] neg_lo:[0,1] neg_hi:[0,1]
	v_xor_b32_e32 v208, 0x80000000, v207
	v_mov_b32_e32 v209, v206
	v_pk_add_f32 v[206:207], v[220:221], v[222:223]
	v_pk_add_f32 v[228:229], v[214:215], v[208:209]
	v_pk_add_f32 v[220:221], v[220:221], v[222:223] neg_lo:[0,1] neg_hi:[0,1]
	v_pk_add_f32 v[208:209], v[214:215], v[208:209] neg_lo:[0,1] neg_hi:[0,1]
	v_pk_add_f32 v[214:215], v[224:225], v[216:217]
	v_pk_add_f32 v[216:217], v[224:225], v[216:217] neg_lo:[0,1] neg_hi:[0,1]
	v_pk_add_f32 v[222:223], v[230:231], v[242:243]
	v_pk_add_f32 v[224:225], v[230:231], v[242:243] neg_lo:[0,1] neg_hi:[0,1]
	v_pk_add_f32 v[204:205], v[226:227], v[236:237]
	v_xor_b32_e32 v230, 0x80000000, v225
	v_mov_b32_e32 v231, v224
	v_pk_add_f32 v[224:225], v[214:215], v[222:223]
	v_pk_add_f32 v[214:215], v[214:215], v[222:223] neg_lo:[0,1] neg_hi:[0,1]
	v_pk_add_f32 v[222:223], v[202:203], v[212:213]
	v_pk_add_f32 v[202:203], v[202:203], v[212:213] neg_lo:[0,1] neg_hi:[0,1]
	v_pk_add_f32 v[212:213], v[226:227], v[236:237] neg_lo:[0,1] neg_hi:[0,1]
	v_pk_add_f32 v[242:243], v[216:217], v[230:231]
	v_xor_b32_e32 v226, 0x80000000, v213
	v_mov_b32_e32 v227, v212
	v_pk_add_f32 v[212:213], v[222:223], v[204:205]
	v_pk_add_f32 v[204:205], v[222:223], v[204:205] neg_lo:[0,1] neg_hi:[0,1]
	v_pk_add_f32 v[222:223], v[238:239], v[210:211]
	v_pk_add_f32 v[210:211], v[238:239], v[210:211] neg_lo:[0,1] neg_hi:[0,1]
	v_pk_add_f32 v[216:217], v[216:217], v[230:231] neg_lo:[0,1] neg_hi:[0,1]
	v_pk_add_f32 v[230:231], v[202:203], v[226:227]
	v_pk_add_f32 v[202:203], v[202:203], v[226:227] neg_lo:[0,1] neg_hi:[0,1]
	v_pk_add_f32 v[200:201], v[200:201], v[234:235] neg_lo:[0,1] neg_hi:[0,1]
	v_xor_b32_e32 v226, 0x80000000, v211
	v_mov_b32_e32 v227, v210
	v_pk_add_f32 v[210:211], v[218:219], v[222:223]
	v_pk_add_f32 v[234:235], v[200:201], v[226:227]
	v_pk_add_f32 v[218:219], v[218:219], v[222:223] neg_lo:[0,1] neg_hi:[0,1]
	v_pk_add_f32 v[200:201], v[200:201], v[226:227] neg_lo:[0,1] neg_hi:[0,1]
	ds_write_b64 v181, v[206:207] offset:6272
	ds_write_b64 v181, v[224:225] offset:8448
	ds_write_b64 v181, v[212:213] offset:10624
	ds_write_b64 v181, v[210:211] offset:12800
	ds_write_b64 v181, v[228:229] offset:14976
	ds_write_b64 v181, v[242:243] offset:17152
	ds_write_b64 v181, v[230:231] offset:19328
	ds_write_b64 v181, v[234:235] offset:21504
	ds_write_b64 v181, v[220:221] offset:23680
	ds_write_b64 v181, v[214:215] offset:25856
	ds_write_b64 v181, v[204:205] offset:28032
	ds_write_b64 v181, v[218:219] offset:30208
	ds_write_b64 v181, v[208:209] offset:32384
	ds_write_b64 v181, v[216:217] offset:34560
	ds_write_b64 v181, v[202:203] offset:36736
	ds_write_b64 v181, v[200:201] offset:38912
.LBB0_368:
	s_or_b64 exec, exec, s[2:3]
	v_add_u32_e32 v235, 0x1880, v0
	s_waitcnt lgkmcnt(0)
	s_barrier
	ds_read2_b64 v[200:203], v235 offset1:1
	v_add_u32_e32 v236, 0x1890, v0
	v_add_u32_e32 v234, 0xa080, v0
	v_add_u32_e32 v233, 0xa090, v0
	s_waitcnt lgkmcnt(0)
	v_mov_b32_e32 v205, v200
	v_mov_b32_e32 v200, v203
	v_mov_b32_e32 v204, v202
	v_pk_fma_f32 v[192:193], v[2:3], v[192:193], v[200:201]
	ds_read2_b64 v[200:203], v236 offset1:1
	v_pk_fma_f32 v[196:197], v[2:3], v[196:197], v[204:205]
	v_pk_mul_f32 v[192:193], v[170:171], v[192:193]
	v_pk_mul_f32 v[196:197], v[178:179], v[196:197]
	s_waitcnt lgkmcnt(0)
	v_mov_b32_e32 v205, v202
	v_mov_b32_e32 v202, v201
	v_mov_b32_e32 v204, v200
	v_pk_fma_f32 v[194:195], v[2:3], v[194:195], v[202:203]
	ds_read2_b64 v[200:203], v234 offset1:1
	v_pk_fma_f32 v[198:199], v[2:3], v[198:199], v[204:205]
	v_pk_mul_f32 v[194:195], v[172:173], v[194:195]
	v_pk_mul_f32 v[198:199], v[182:183], v[198:199]
	s_waitcnt lgkmcnt(0)
	v_mov_b32_e32 v205, v200
	v_mov_b32_e32 v200, v203
	v_mov_b32_e32 v204, v202
	v_pk_fma_f32 v[184:185], v[2:3], v[184:185], v[200:201]
	ds_read2_b64 v[200:203], v233 offset1:1
	v_pk_fma_f32 v[188:189], v[2:3], v[188:189], v[204:205]
	s_waitcnt lgkmcnt(0)
	s_barrier
	v_mov_b32_e32 v204, v200
	v_mov_b32_e32 v205, v202
	v_mov_b32_e32 v202, v201
	v_mov_b32_e32 v200, v197
	v_mov_b32_e32 v201, v193
	ds_write_b64 v0, v[200:201] offset:6272
	ds_write_b64 v232, v[240:241] offset:22656
	v_mov_b32_e32 v200, v196
	v_mov_b32_e32 v201, v192
	ds_write_b64 v0, v[200:201] offset:6280
	ds_write_b64 v232, v[240:241] offset:22664
	v_mov_b32_e32 v200, v198
	v_mov_b32_e32 v201, v194
	v_pk_mul_f32 v[188:189], v[158:159], v[188:189]
	v_pk_mul_f32 v[184:185], v[82:83], v[184:185]
	ds_write_b64 v0, v[200:201] offset:6288
	ds_write_b64 v232, v[240:241] offset:22672
	v_mov_b32_e32 v200, v199
	v_mov_b32_e32 v201, v195
	v_pk_fma_f32 v[190:191], v[2:3], v[190:191], v[204:205]
	v_pk_fma_f32 v[186:187], v[2:3], v[186:187], v[202:203]
	ds_write_b64 v0, v[200:201] offset:6296
	ds_write_b64 v232, v[240:241] offset:22680
	v_mov_b32_e32 v200, v189
	v_mov_b32_e32 v201, v185
	v_pk_mul_f32 v[190:191], v[160:161], v[190:191]
	v_pk_mul_f32 v[186:187], v[96:97], v[186:187]
	ds_write_b64 v0, v[200:201] offset:41088
	ds_write_b64 v232, v[240:241] offset:57472
	v_mov_b32_e32 v200, v188
	v_mov_b32_e32 v201, v184
	ds_write_b64 v0, v[200:201] offset:41096
	ds_write_b64 v232, v[240:241] offset:57480
	v_mov_b32_e32 v200, v190
	v_mov_b32_e32 v201, v186
	ds_write_b64 v0, v[200:201] offset:41104
	ds_write_b64 v232, v[240:241] offset:57488
	v_mov_b32_e32 v200, v191
	v_mov_b32_e32 v201, v187
	ds_write_b64 v0, v[200:201] offset:41112
	ds_write_b64 v232, v[240:241] offset:57496
	v_mov_b32_e32 v200, v180
	s_waitcnt lgkmcnt(0)
	s_barrier
	s_nop 0
	v_cmp_gt_i32_e32 vcc, s56, v200
	s_and_saveexec_b64 s[2:3], vcc
	s_cbranch_execz .LBB0_370
	v_ashrrev_i32_e32 v181, 31, v200
	v_add_u32_sdwa v181, v200, v181 dst_sel:DWORD dst_unused:UNUSED_PAD src0_sel:DWORD src1_sel:BYTE_3
	v_ashrrev_i32_e32 v181, 8, v181
	v_mul_i32_i24_e32 v201, 0x100, v181
	v_sub_u32_e32 v237, v200, v201
	v_mul_i32_i24_e32 v181, 0x1100, v181
	v_lshlrev_b32_e32 v181, 3, v181
	v_ashrrev_i32_e32 v201, 4, v237
	v_add_u32_e32 v200, 0, v181
	v_lshlrev_b32_e32 v248, 3, v237
	v_lshlrev_b32_e32 v201, 3, v201
	v_add3_u32 v230, v200, v248, v201
	ds_read_b64 v[200:201], v230 offset:6272
	ds_read_b64 v[202:203], v230 offset:8448
	ds_read_b64 v[204:205], v230 offset:10624
	ds_read_b64 v[206:207], v230 offset:12800
	ds_read_b64 v[208:209], v230 offset:14976
	ds_read_b64 v[210:211], v230 offset:17152
	ds_read_b64 v[212:213], v230 offset:19328
	ds_read_b64 v[214:215], v230 offset:21504
	ds_read_b64 v[216:217], v230 offset:23680
	ds_read_b64 v[218:219], v230 offset:25856
	ds_read_b64 v[220:221], v230 offset:28032
	ds_read_b64 v[222:223], v230 offset:30208
	ds_read_b64 v[224:225], v230 offset:32384
	ds_read_b64 v[226:227], v230 offset:34560
	ds_read_b64 v[228:229], v230 offset:36736
	ds_read_b64 v[230:231], v230 offset:38912
	s_waitcnt lgkmcnt(7)
	v_pk_add_f32 v[238:239], v[200:201], v[216:217]
	v_pk_add_f32 v[200:201], v[200:201], v[216:217] neg_lo:[0,1] neg_hi:[0,1]
	s_waitcnt lgkmcnt(3)
	v_pk_add_f32 v[216:217], v[208:209], v[224:225]
	v_pk_add_f32 v[208:209], v[208:209], v[224:225] neg_lo:[0,1] neg_hi:[0,1]
	s_mov_b32 s61, s34
	v_pk_add_f32 v[242:243], v[200:201], v[208:209] op_sel:[0,1] op_sel_hi:[1,0] neg_hi:[0,1]
	v_pk_add_f32 v[200:201], v[200:201], v[208:209] op_sel:[0,1] op_sel_hi:[1,0] neg_lo:[0,1]
	v_pk_add_f32 v[224:225], v[202:203], v[218:219]
	v_pk_add_f32 v[202:203], v[202:203], v[218:219] neg_lo:[0,1] neg_hi:[0,1]
	s_waitcnt lgkmcnt(2)
	v_pk_add_f32 v[218:219], v[210:211], v[226:227]
	v_pk_add_f32 v[210:211], v[210:211], v[226:227] neg_lo:[0,1] neg_hi:[0,1]
	v_pk_add_f32 v[208:209], v[238:239], v[216:217]
	v_xor_b32_e32 v227, 0x80000000, v210
	v_mov_b32_e32 v226, v211
	v_pk_add_f32 v[210:211], v[224:225], v[218:219]
	v_pk_add_f32 v[218:219], v[224:225], v[218:219] neg_lo:[0,1] neg_hi:[0,1]
	v_pk_add_f32 v[224:225], v[204:205], v[220:221]
	v_pk_add_f32 v[204:205], v[204:205], v[220:221] neg_lo:[0,1] neg_hi:[0,1]
	s_waitcnt lgkmcnt(1)
	v_pk_add_f32 v[220:221], v[212:213], v[228:229]
	v_pk_add_f32 v[212:213], v[212:213], v[228:229] neg_lo:[0,1] neg_hi:[0,1]
	v_pk_add_f32 v[216:217], v[238:239], v[216:217] neg_lo:[0,1] neg_hi:[0,1]
	v_pk_add_f32 v[238:239], v[202:203], v[226:227]
	v_pk_add_f32 v[202:203], v[202:203], v[226:227] neg_lo:[0,1] neg_hi:[0,1]
	v_xor_b32_e32 v227, 0x80000000, v212
	v_mov_b32_e32 v226, v213
	v_pk_add_f32 v[212:213], v[224:225], v[220:221]
	v_pk_add_f32 v[220:221], v[224:225], v[220:221] neg_lo:[0,1] neg_hi:[0,1]
	v_pk_add_f32 v[224:225], v[206:207], v[222:223]
	v_pk_add_f32 v[206:207], v[206:207], v[222:223] neg_lo:[0,1] neg_hi:[0,1]
	s_waitcnt lgkmcnt(0)
	v_pk_add_f32 v[222:223], v[214:215], v[230:231]
	v_pk_add_f32 v[214:215], v[214:215], v[230:231] neg_lo:[0,1] neg_hi:[0,1]
	v_pk_add_f32 v[228:229], v[204:205], v[226:227]
	v_pk_add_f32 v[204:205], v[204:205], v[226:227] neg_lo:[0,1] neg_hi:[0,1]
	v_xor_b32_e32 v227, 0x80000000, v214
	v_mov_b32_e32 v226, v215
	v_pk_add_f32 v[214:215], v[224:225], v[222:223]
	v_pk_add_f32 v[222:223], v[224:225], v[222:223] neg_lo:[0,1] neg_hi:[0,1]
	v_pk_mul_f32 v[224:225], v[238:239], s[24:25] op_sel_hi:[1,0]
	v_pk_add_f32 v[230:231], v[206:207], v[226:227]
	v_pk_add_f32 v[206:207], v[206:207], v[226:227] neg_lo:[0,1] neg_hi:[0,1]
	v_pk_fma_f32 v[226:227], v[238:239], s[26:27], v[224:225] op_sel:[0,0,1] op_sel_hi:[1,0,0] neg_hi:[0,0,1]
	s_mov_b32 s35, s24
	v_pk_mul_f32 v[224:225], v[218:219], s[28:29] op_sel_hi:[1,0]
	v_add_u32_e32 v181, s57, v181
	v_pk_fma_f32 v[238:239], v[218:219], s[28:29], v[224:225] op_sel:[0,0,1] op_sel_hi:[1,0,0] neg_hi:[0,0,1]
	v_pk_mul_f32 v[224:225], v[202:203], s[26:27] op_sel_hi:[1,0]
	v_pk_fma_f32 v[244:245], v[202:203], s[24:25], v[224:225] op_sel:[0,0,1] op_sel_hi:[1,0,0] neg_hi:[0,0,1]
	s_nop 0
	v_pk_mul_f32 v[202:203], v[228:229], s[28:29] op_sel_hi:[1,0]
	s_nop 0
	v_pk_fma_f32 v[224:225], v[228:229], s[28:29], v[202:203] op_sel:[0,0,1] op_sel_hi:[1,0,0] neg_hi:[0,0,1]
	s_nop 0
	v_pk_fma_f32 v[202:203], v[220:221], 0, v[220:221] op_sel:[0,0,1] op_sel_hi:[1,0,0] neg_hi:[0,0,1]
	s_nop 0
	v_pk_mul_f32 v[220:221], v[204:205], s[30:31] op_sel_hi:[1,0]
	s_nop 0
	v_pk_fma_f32 v[228:229], v[204:205], s[30:31], v[220:221] op_sel:[0,0,1] op_sel_hi:[1,0,0] neg_lo:[0,0,1]
	v_pk_mul_f32 v[220:221], v[230:231], s[26:27] op_sel_hi:[1,0]
	v_pk_fma_f32 v[246:247], v[230:231], s[24:25], v[220:221] op_sel:[0,0,1] op_sel_hi:[1,0,0] neg_hi:[0,0,1]
	v_pk_add_f32 v[204:205], v[200:201], v[228:229]
	v_pk_mul_f32 v[220:221], v[222:223], s[30:31] op_sel_hi:[1,0]
	v_pk_add_f32 v[200:201], v[200:201], v[228:229] neg_lo:[0,1] neg_hi:[0,1]
	v_pk_fma_f32 v[230:231], v[222:223], s[30:31], v[220:221] op_sel:[0,0,1] op_sel_hi:[1,0,0] neg_lo:[0,0,1]
	s_nop 0
	v_pk_mul_f32 v[220:221], v[206:207], s[60:61] op_sel:[1,0]
	v_pk_add_f32 v[218:219], v[238:239], v[230:231] neg_lo:[0,1] neg_hi:[0,1]
	v_pk_fma_f32 v[206:207], v[206:207], s[34:35], v[220:221] op_sel_hi:[0,1,1]
	v_pk_add_f32 v[220:221], v[208:209], v[212:213]
	v_pk_add_f32 v[208:209], v[208:209], v[212:213] neg_lo:[0,1] neg_hi:[0,1]
	v_pk_add_f32 v[212:213], v[210:211], v[214:215]
	v_pk_add_f32 v[210:211], v[210:211], v[214:215] neg_lo:[0,1] neg_hi:[0,1]
	s_nop 0
	v_xor_b32_e32 v215, 0x80000000, v210
	v_mov_b32_e32 v214, v211
	v_pk_add_f32 v[210:211], v[220:221], v[212:213]
	v_pk_add_f32 v[222:223], v[208:209], v[214:215]
	v_pk_add_f32 v[212:213], v[220:221], v[212:213] neg_lo:[0,1] neg_hi:[0,1]
	v_pk_add_f32 v[208:209], v[208:209], v[214:215] neg_lo:[0,1] neg_hi:[0,1]
	v_pk_add_f32 v[214:215], v[242:243], v[224:225]
	v_pk_add_f32 v[220:221], v[242:243], v[224:225] neg_lo:[0,1] neg_hi:[0,1]
	v_pk_add_f32 v[224:225], v[226:227], v[246:247]
	v_pk_add_f32 v[226:227], v[226:227], v[246:247] neg_lo:[0,1] neg_hi:[0,1]
	s_nop 0
	v_xor_b32_e32 v243, 0x80000000, v226
	v_mov_b32_e32 v242, v227
	v_pk_add_f32 v[226:227], v[214:215], v[224:225]
	v_pk_add_f32 v[214:215], v[214:215], v[224:225] neg_lo:[0,1] neg_hi:[0,1]
	v_pk_add_f32 v[224:225], v[216:217], v[202:203]
	v_pk_add_f32 v[202:203], v[216:217], v[202:203] neg_lo:[0,1] neg_hi:[0,1]
	v_pk_add_f32 v[216:217], v[238:239], v[230:231]
	v_xor_b32_e32 v231, 0x80000000, v218
	v_mov_b32_e32 v230, v219
	v_pk_add_f32 v[218:219], v[224:225], v[216:217]
	v_pk_add_f32 v[216:217], v[224:225], v[216:217] neg_lo:[0,1] neg_hi:[0,1]
	v_pk_add_f32 v[224:225], v[244:245], v[206:207]
	v_pk_add_f32 v[206:207], v[244:245], v[206:207] neg_lo:[0,1] neg_hi:[0,1]
	v_pk_add_f32 v[246:247], v[220:221], v[242:243]
	v_xor_b32_e32 v229, 0x80000000, v206
	v_mov_b32_e32 v228, v207
	v_pk_add_f32 v[206:207], v[204:205], v[224:225]
	v_pk_add_f32 v[204:205], v[204:205], v[224:225] neg_lo:[0,1] neg_hi:[0,1]
	v_lshlrev_b32_e32 v224, 7, v237
	v_add3_u32 v181, v181, v224, v248
	v_pk_add_f32 v[220:221], v[220:221], v[242:243] neg_lo:[0,1] neg_hi:[0,1]
	v_pk_add_f32 v[238:239], v[202:203], v[230:231]
	v_pk_add_f32 v[202:203], v[202:203], v[230:231] neg_lo:[0,1] neg_hi:[0,1]
	v_pk_add_f32 v[230:231], v[200:201], v[228:229]
	v_pk_add_f32 v[200:201], v[200:201], v[228:229] neg_lo:[0,1] neg_hi:[0,1]
	ds_write2_b64 v181, v[210:211], v[226:227] offset1:1
	ds_write2_b64 v181, v[218:219], v[206:207] offset0:2 offset1:3
	ds_write2_b64 v181, v[222:223], v[246:247] offset0:4 offset1:5
	ds_write2_b64 v181, v[238:239], v[230:231] offset0:6 offset1:7
	ds_write2_b64 v181, v[212:213], v[214:215] offset0:8 offset1:9
	ds_write2_b64 v181, v[216:217], v[204:205] offset0:10 offset1:11
	ds_write2_b64 v181, v[208:209], v[220:221] offset0:12 offset1:13
	ds_write2_b64 v181, v[202:203], v[200:201] offset0:14 offset1:15

.LBB0_372:
	s_or_b64 exec, exec, s[2:3]
	v_mov_b32_e32 v200, v180
	s_waitcnt lgkmcnt(0)
	s_barrier
	s_nop 0
	v_cmp_gt_i32_e32 vcc, s56, v200
	s_and_saveexec_b64 s[2:3], vcc
	s_cbranch_execz .LBB0_374
	v_ashrrev_i32_e32 v181, 31, v200
	v_add_u32_sdwa v181, v200, v181 dst_sel:DWORD dst_unused:UNUSED_PAD src0_sel:DWORD src1_sel:BYTE_3
	v_ashrrev_i32_e32 v181, 8, v181
	v_mul_i32_i24_e32 v201, 0x100, v181
	v_sub_u32_e32 v200, v200, v201
	v_mul_i32_i24_e32 v181, 0x1100, v181
	v_lshlrev_b32_e32 v237, 3, v200
	v_ashrrev_i32_e32 v200, 4, v200
	v_lshlrev_b32_e32 v181, 3, v181
	v_lshlrev_b32_e32 v252, 3, v200
	v_add_u32_e32 v222, 0, v237
	v_add3_u32 v238, v222, v181, v252
	ds_read_b64 v[200:201], v238 offset:6272
	ds_read_b64 v[202:203], v238 offset:8448
	ds_read_b64 v[204:205], v238 offset:10624
	ds_read_b64 v[206:207], v238 offset:12800
	ds_read_b64 v[208:209], v238 offset:14976
	ds_read_b64 v[210:211], v238 offset:17152
	ds_read_b64 v[212:213], v238 offset:19328
	ds_read_b64 v[214:215], v238 offset:21504
	ds_read_b64 v[216:217], v238 offset:34560
	ds_read_b64 v[218:219], v238 offset:36736
	ds_read_b64 v[220:221], v238 offset:38912
	ds_read_b64 v[222:223], v222
	ds_read_b64 v[224:225], v238 offset:23680
	ds_read_b64 v[226:227], v238 offset:25856
	ds_read_b64 v[228:229], v238 offset:28032
	ds_read_b64 v[230:231], v238 offset:30208
	ds_read_b64 v[238:239], v238 offset:32384
	s_waitcnt lgkmcnt(5)
	v_pk_mul_f32 v[242:243], v[202:203], v[222:223] op_sel:[1,1] op_sel_hi:[1,0]
	s_mov_b32 s61, s34
	v_pk_fma_f32 v[244:245], v[202:203], v[222:223], v[242:243] op_sel_hi:[0,1,1] neg_lo:[0,0,1]
	v_pk_mul_f32 v[202:203], v[222:223], v[222:223] op_sel:[1,1] op_sel_hi:[1,0]
	s_mov_b32 s35, s24
	v_pk_fma_f32 v[242:243], v[222:223], v[222:223], v[202:203] op_sel_hi:[1,0,1] neg_lo:[0,0,1] neg_hi:[0,0,1]
	v_pk_fma_f32 v[202:203], v[222:223], v[222:223], v[202:203] op_sel_hi:[1,0,1]
	v_mov_b32_e32 v246, v242
	v_mov_b32_e32 v247, v203
	v_pk_mul_f32 v[202:203], v[204:205], v[202:203] op_sel:[1,1] op_sel_hi:[0,1]
	v_pk_fma_f32 v[248:249], v[204:205], v[242:243], v[202:203] op_sel_hi:[1,0,1] neg_lo:[0,0,1]
	v_pk_mul_f32 v[204:205], v[222:223], v[246:247] op_sel:[1,0] op_sel_hi:[0,1]
	v_pk_mul_f32 v[202:203], v[222:223], v[246:247]
	v_pk_add_f32 v[204:205], v[204:205], v[204:205] op_sel:[0,1] op_sel_hi:[0,1]
	v_pk_mul_f32 v[242:243], v[206:207], v[204:205]
	v_pk_add_f32 v[202:203], v[202:203], v[202:203] op_sel:[0,1] op_sel_hi:[0,1] neg_lo:[0,1] neg_hi:[0,1]
	v_pk_fma_f32 v[246:247], v[206:207], v[202:203], v[242:243] op_sel:[0,0,1] op_sel_hi:[1,1,0] neg_lo:[0,0,1]
	v_pk_mul_f32 v[204:205], v[222:223], v[204:205]
	v_pk_fma_f32 v[206:207], v[222:223], v[202:203], v[204:205] op_sel:[0,0,1] op_sel_hi:[1,1,0] neg_lo:[0,0,1] neg_hi:[0,0,1]
	v_pk_fma_f32 v[202:203], v[222:223], v[202:203], v[204:205] op_sel:[0,0,1] op_sel_hi:[1,1,0]
	v_mov_b32_e32 v204, v206
	v_mov_b32_e32 v205, v203
	v_pk_mul_f32 v[202:203], v[208:209], v[202:203] op_sel:[1,1] op_sel_hi:[0,1]
	v_pk_fma_f32 v[242:243], v[208:209], v[206:207], v[202:203] op_sel_hi:[1,0,1] neg_lo:[0,0,1]
	v_add_u32_e32 v181, s57, v181
	v_pk_mul_f32 v[202:203], v[222:223], v[204:205]
	v_pk_mul_f32 v[204:205], v[222:223], v[204:205] op_sel:[1,0] op_sel_hi:[0,1]
	v_pk_add_f32 v[204:205], v[204:205], v[204:205] op_sel:[0,1] op_sel_hi:[0,1]
	v_pk_mul_f32 v[206:207], v[210:211], v[204:205]
	v_pk_add_f32 v[202:203], v[202:203], v[202:203] op_sel:[0,1] op_sel_hi:[0,1] neg_lo:[0,1] neg_hi:[0,1]
	v_pk_fma_f32 v[208:209], v[210:211], v[202:203], v[206:207] op_sel:[0,0,1] op_sel_hi:[1,1,0] neg_lo:[0,0,1]
	v_pk_mul_f32 v[204:205], v[222:223], v[204:205]
	v_pk_fma_f32 v[206:207], v[222:223], v[202:203], v[204:205] op_sel:[0,0,1] op_sel_hi:[1,1,0] neg_lo:[0,0,1] neg_hi:[0,0,1]
	v_pk_fma_f32 v[202:203], v[222:223], v[202:203], v[204:205] op_sel:[0,0,1] op_sel_hi:[1,1,0]
	v_mov_b32_e32 v204, v206
	v_mov_b32_e32 v205, v203
	v_pk_mul_f32 v[202:203], v[212:213], v[202:203] op_sel:[1,1] op_sel_hi:[0,1]
	v_pk_fma_f32 v[210:211], v[212:213], v[206:207], v[202:203] op_sel_hi:[1,0,1] neg_lo:[0,0,1]
	v_add3_u32 v181, v181, v237, v252
	v_pk_mul_f32 v[202:203], v[222:223], v[204:205]
	v_pk_mul_f32 v[204:205], v[222:223], v[204:205] op_sel:[1,0] op_sel_hi:[0,1]
	v_pk_add_f32 v[204:205], v[204:205], v[204:205] op_sel:[0,1] op_sel_hi:[0,1]
	v_pk_mul_f32 v[206:207], v[214:215], v[204:205]
	v_pk_add_f32 v[202:203], v[202:203], v[202:203] op_sel:[0,1] op_sel_hi:[0,1] neg_lo:[0,1] neg_hi:[0,1]
	v_pk_fma_f32 v[212:213], v[214:215], v[202:203], v[206:207] op_sel:[0,0,1] op_sel_hi:[1,1,0] neg_lo:[0,0,1]
	v_pk_mul_f32 v[204:205], v[222:223], v[204:205]
	v_pk_fma_f32 v[206:207], v[222:223], v[202:203], v[204:205] op_sel:[0,0,1] op_sel_hi:[1,1,0] neg_lo:[0,0,1] neg_hi:[0,0,1]
	v_pk_fma_f32 v[202:203], v[222:223], v[202:203], v[204:205] op_sel:[0,0,1] op_sel_hi:[1,1,0]
	v_mov_b32_e32 v204, v206
	v_mov_b32_e32 v205, v203
	s_waitcnt lgkmcnt(4)
	v_pk_mul_f32 v[202:203], v[224:225], v[202:203] op_sel:[1,1] op_sel_hi:[0,1]
	v_pk_fma_f32 v[214:215], v[224:225], v[206:207], v[202:203] op_sel_hi:[1,0,1] neg_lo:[0,0,1]
	s_nop 0
	v_pk_mul_f32 v[202:203], v[222:223], v[204:205]
	v_pk_mul_f32 v[204:205], v[222:223], v[204:205] op_sel:[1,0] op_sel_hi:[0,1]
	v_pk_add_f32 v[204:205], v[204:205], v[204:205] op_sel:[0,1] op_sel_hi:[0,1]
	s_waitcnt lgkmcnt(3)
	v_pk_mul_f32 v[206:207], v[226:227], v[204:205]
	v_pk_add_f32 v[202:203], v[202:203], v[202:203] op_sel:[0,1] op_sel_hi:[0,1] neg_lo:[0,1] neg_hi:[0,1]
	v_pk_fma_f32 v[224:225], v[226:227], v[202:203], v[206:207] op_sel:[0,0,1] op_sel_hi:[1,1,0] neg_lo:[0,0,1]
	v_pk_mul_f32 v[204:205], v[222:223], v[204:205]
	v_pk_fma_f32 v[206:207], v[222:223], v[202:203], v[204:205] op_sel:[0,0,1] op_sel_hi:[1,1,0] neg_lo:[0,0,1] neg_hi:[0,0,1]
	v_pk_fma_f32 v[202:203], v[222:223], v[202:203], v[204:205] op_sel:[0,0,1] op_sel_hi:[1,1,0]
	v_mov_b32_e32 v204, v206
	v_mov_b32_e32 v205, v203
	s_waitcnt lgkmcnt(2)
	v_pk_mul_f32 v[202:203], v[228:229], v[202:203] op_sel:[1,1] op_sel_hi:[0,1]
	v_pk_fma_f32 v[226:227], v[228:229], v[206:207], v[202:203] op_sel_hi:[1,0,1] neg_lo:[0,0,1]
	s_nop 0
	v_pk_mul_f32 v[202:203], v[222:223], v[204:205]
	v_pk_mul_f32 v[204:205], v[222:223], v[204:205] op_sel:[1,0] op_sel_hi:[0,1]
	v_pk_add_f32 v[204:205], v[204:205], v[204:205] op_sel:[0,1] op_sel_hi:[0,1]
	s_waitcnt lgkmcnt(1)
	v_pk_mul_f32 v[206:207], v[230:231], v[204:205]
	v_pk_add_f32 v[202:203], v[202:203], v[202:203] op_sel:[0,1] op_sel_hi:[0,1] neg_lo:[0,1] neg_hi:[0,1]
	v_pk_fma_f32 v[228:229], v[230:231], v[202:203], v[206:207] op_sel:[0,0,1] op_sel_hi:[1,1,0] neg_lo:[0,0,1]
	v_pk_mul_f32 v[204:205], v[222:223], v[204:205]
	v_pk_fma_f32 v[206:207], v[222:223], v[202:203], v[204:205] op_sel:[0,0,1] op_sel_hi:[1,1,0] neg_lo:[0,0,1] neg_hi:[0,0,1]
	v_pk_fma_f32 v[202:203], v[222:223], v[202:203], v[204:205] op_sel:[0,0,1] op_sel_hi:[1,1,0]
	v_mov_b32_e32 v204, v206
	v_mov_b32_e32 v205, v203
	s_waitcnt lgkmcnt(0)
	v_pk_mul_f32 v[202:203], v[238:239], v[202:203] op_sel:[1,1] op_sel_hi:[0,1]
	v_pk_fma_f32 v[230:231], v[238:239], v[206:207], v[202:203] op_sel_hi:[1,0,1] neg_lo:[0,0,1]
	s_nop 0
	v_pk_mul_f32 v[202:203], v[222:223], v[204:205]
	v_pk_mul_f32 v[204:205], v[222:223], v[204:205] op_sel:[1,0] op_sel_hi:[0,1]
	v_pk_add_f32 v[204:205], v[204:205], v[204:205] op_sel:[0,1] op_sel_hi:[0,1]
	v_pk_mul_f32 v[206:207], v[216:217], v[204:205]
	v_pk_add_f32 v[202:203], v[202:203], v[202:203] op_sel:[0,1] op_sel_hi:[0,1] neg_lo:[0,1] neg_hi:[0,1]
	v_pk_fma_f32 v[238:239], v[216:217], v[202:203], v[206:207] op_sel:[0,0,1] op_sel_hi:[1,1,0] neg_lo:[0,0,1]
	v_pk_mul_f32 v[202:203], v[222:223], v[202:203]
	v_pk_fma_f32 v[206:207], v[222:223], v[204:205], v[202:203] op_sel:[0,0,1] op_sel_hi:[1,1,0] neg_lo:[1,0,0] neg_hi:[1,0,0]
	v_pk_fma_f32 v[202:203], v[222:223], v[204:205], v[202:203] op_sel:[0,0,1] op_sel_hi:[1,1,0]
	v_mov_b32_e32 v205, v207
	v_mov_b32_e32 v204, v202
	v_pk_mul_f32 v[216:217], v[218:219], v[202:203] op_sel:[1,0] op_sel_hi:[0,0]
	v_pk_mov_b32 v[202:203], v[206:207], v[202:203] op_sel:[1,0]
	v_pk_mul_f32 v[204:205], v[222:223], v[204:205]
	v_pk_mul_f32 v[202:203], v[222:223], v[202:203]
	v_pk_add_f32 v[204:205], v[204:205], v[204:205] op_sel:[1,0] op_sel_hi:[1,0]
	v_pk_fma_f32 v[250:251], v[218:219], v[206:207], v[216:217] op_sel:[0,1,0] neg_lo:[0,0,1]
	v_pk_mul_f32 v[204:205], v[220:221], v[204:205] op_sel:[1,0] op_sel_hi:[0,1]
	v_pk_add_f32 v[202:203], v[202:203], v[202:203] op_sel:[0,1] op_sel_hi:[0,1] neg_lo:[0,1] neg_hi:[0,1]
	v_pk_fma_f32 v[206:207], v[220:221], v[202:203], v[204:205] neg_lo:[0,0,1]
	v_pk_add_f32 v[204:205], v[242:243], v[230:231]
	v_pk_add_f32 v[202:203], v[200:201], v[214:215]
	v_pk_add_f32 v[200:201], v[200:201], v[214:215] neg_lo:[0,1] neg_hi:[0,1]
	v_pk_add_f32 v[214:215], v[242:243], v[230:231] neg_lo:[0,1] neg_hi:[0,1]
	v_pk_add_f32 v[220:221], v[208:209], v[238:239]
	v_xor_b32_e32 v217, 0x80000000, v214
	v_mov_b32_e32 v216, v215
	v_pk_add_f32 v[208:209], v[208:209], v[238:239] neg_lo:[0,1] neg_hi:[0,1]
	v_pk_add_f32 v[214:215], v[202:203], v[204:205]
	v_pk_add_f32 v[218:219], v[200:201], v[216:217]
	v_pk_add_f32 v[202:203], v[202:203], v[204:205] neg_lo:[0,1] neg_hi:[0,1]
	v_pk_add_f32 v[200:201], v[200:201], v[216:217] neg_lo:[0,1] neg_hi:[0,1]
	v_pk_add_f32 v[204:205], v[244:245], v[224:225]
	v_pk_add_f32 v[216:217], v[244:245], v[224:225] neg_lo:[0,1] neg_hi:[0,1]
	v_xor_b32_e32 v223, 0x80000000, v208
	v_mov_b32_e32 v222, v209
	v_pk_add_f32 v[208:209], v[204:205], v[220:221]
	v_pk_add_f32 v[224:225], v[216:217], v[222:223]
	v_pk_add_f32 v[204:205], v[204:205], v[220:221] neg_lo:[0,1] neg_hi:[0,1]
	v_pk_add_f32 v[216:217], v[216:217], v[222:223] neg_lo:[0,1] neg_hi:[0,1]
	v_pk_add_f32 v[220:221], v[248:249], v[226:227]
	v_pk_add_f32 v[222:223], v[248:249], v[226:227] neg_lo:[0,1] neg_hi:[0,1]
	v_pk_add_f32 v[226:227], v[210:211], v[250:251]
	v_pk_add_f32 v[210:211], v[210:211], v[250:251] neg_lo:[0,1] neg_hi:[0,1]
	s_nop 0
	v_pk_add_f32 v[238:239], v[222:223], v[210:211] op_sel:[0,1] op_sel_hi:[1,0] neg_hi:[0,1]
	v_pk_add_f32 v[222:223], v[222:223], v[210:211] op_sel:[0,1] op_sel_hi:[1,0] neg_lo:[0,1]
	v_pk_add_f32 v[230:231], v[212:213], v[206:207]
	v_pk_add_f32 v[206:207], v[212:213], v[206:207] neg_lo:[0,1] neg_hi:[0,1]
	v_pk_add_f32 v[210:211], v[220:221], v[226:227]
	v_pk_add_f32 v[220:221], v[220:221], v[226:227] neg_lo:[0,1] neg_hi:[0,1]
	v_pk_add_f32 v[226:227], v[246:247], v[228:229]
	v_pk_add_f32 v[228:229], v[246:247], v[228:229] neg_lo:[0,1] neg_hi:[0,1]
	v_pk_add_f32 v[242:243], v[228:229], v[206:207] op_sel:[0,1] op_sel_hi:[1,0] neg_hi:[0,1]
	v_pk_add_f32 v[212:213], v[228:229], v[206:207] op_sel:[0,1] op_sel_hi:[1,0] neg_lo:[0,1]
	v_pk_mul_f32 v[228:229], v[224:225], s[24:25] op_sel_hi:[1,0]
	v_pk_add_f32 v[206:207], v[226:227], v[230:231]
	v_pk_add_f32 v[226:227], v[226:227], v[230:231] neg_lo:[0,1] neg_hi:[0,1]
	v_pk_fma_f32 v[230:231], v[224:225], s[26:27], v[228:229] op_sel:[0,0,1] op_sel_hi:[1,0,0] neg_hi:[0,0,1]
	s_nop 0
	v_pk_mul_f32 v[224:225], v[204:205], s[28:29] op_sel_hi:[1,0]
	s_nop 0
	v_pk_fma_f32 v[228:229], v[204:205], s[28:29], v[224:225] op_sel:[0,0,1] op_sel_hi:[1,0,0] neg_hi:[0,0,1]
	v_pk_mul_f32 v[224:225], v[216:217], s[26:27] op_sel_hi:[1,0]
	v_pk_fma_f32 v[244:245], v[216:217], s[24:25], v[224:225] op_sel:[0,0,1] op_sel_hi:[1,0,0] neg_hi:[0,0,1]
	s_nop 0
	v_pk_mul_f32 v[216:217], v[238:239], s[28:29] op_sel_hi:[1,0]
	s_nop 0
	v_pk_fma_f32 v[224:225], v[238:239], s[28:29], v[216:217] op_sel:[0,0,1] op_sel_hi:[1,0,0] neg_hi:[0,0,1]
	s_nop 0
	v_pk_fma_f32 v[216:217], v[220:221], 0, v[220:221] op_sel:[0,0,1] op_sel_hi:[1,0,0] neg_hi:[0,0,1]
	s_nop 0
	v_pk_mul_f32 v[220:221], v[222:223], s[30:31] op_sel_hi:[1,0]
	s_nop 0
	v_pk_fma_f32 v[238:239], v[222:223], s[30:31], v[220:221] op_sel:[0,0,1] op_sel_hi:[1,0,0] neg_lo:[0,0,1]
	v_pk_mul_f32 v[222:223], v[242:243], s[26:27] op_sel_hi:[1,0]
	v_pk_fma_f32 v[246:247], v[242:243], s[24:25], v[222:223] op_sel:[0,0,1] op_sel_hi:[1,0,0] neg_hi:[0,0,1]
	v_pk_add_f32 v[220:221], v[200:201], v[238:239]
	v_pk_mul_f32 v[222:223], v[226:227], s[30:31] op_sel_hi:[1,0]
	v_pk_add_f32 v[200:201], v[200:201], v[238:239] neg_lo:[0,1] neg_hi:[0,1]
	v_pk_fma_f32 v[242:243], v[226:227], s[30:31], v[222:223] op_sel:[0,0,1] op_sel_hi:[1,0,0] neg_lo:[0,0,1]
	s_nop 0
	v_pk_mul_f32 v[222:223], v[212:213], s[60:61] op_sel:[1,0]
	v_pk_add_f32 v[204:205], v[228:229], v[242:243]
	v_pk_fma_f32 v[212:213], v[212:213], s[34:35], v[222:223] op_sel_hi:[0,1,1]
	v_pk_add_f32 v[222:223], v[214:215], v[210:211]
	v_pk_add_f32 v[210:211], v[214:215], v[210:211] neg_lo:[0,1] neg_hi:[0,1]
	v_pk_add_f32 v[214:215], v[208:209], v[206:207]
	v_pk_add_f32 v[206:207], v[208:209], v[206:207] neg_lo:[0,1] neg_hi:[0,1]
	s_nop 0
	v_xor_b32_e32 v209, 0x80000000, v206
	v_mov_b32_e32 v208, v207
	v_pk_add_f32 v[206:207], v[222:223], v[214:215]
	v_pk_add_f32 v[226:227], v[210:211], v[208:209]
	v_pk_add_f32 v[214:215], v[222:223], v[214:215] neg_lo:[0,1] neg_hi:[0,1]
	v_pk_add_f32 v[208:209], v[210:211], v[208:209] neg_lo:[0,1] neg_hi:[0,1]
	v_pk_add_f32 v[210:211], v[218:219], v[224:225]
	v_pk_add_f32 v[218:219], v[218:219], v[224:225] neg_lo:[0,1] neg_hi:[0,1]
	v_pk_add_f32 v[222:223], v[230:231], v[246:247]
	v_pk_add_f32 v[224:225], v[230:231], v[246:247] neg_lo:[0,1] neg_hi:[0,1]
	s_nop 0
	v_xor_b32_e32 v231, 0x80000000, v224
	v_mov_b32_e32 v230, v225
	v_pk_add_f32 v[224:225], v[210:211], v[222:223]
	v_pk_add_f32 v[210:211], v[210:211], v[222:223] neg_lo:[0,1] neg_hi:[0,1]
	v_pk_add_f32 v[222:223], v[202:203], v[216:217]
	v_pk_add_f32 v[202:203], v[202:203], v[216:217] neg_lo:[0,1] neg_hi:[0,1]
	v_pk_add_f32 v[216:217], v[228:229], v[242:243] neg_lo:[0,1] neg_hi:[0,1]
	v_pk_add_f32 v[246:247], v[218:219], v[230:231]
	v_xor_b32_e32 v229, 0x80000000, v216
	v_mov_b32_e32 v228, v217
	v_pk_add_f32 v[216:217], v[222:223], v[204:205]
	v_pk_add_f32 v[204:205], v[222:223], v[204:205] neg_lo:[0,1] neg_hi:[0,1]
	v_pk_add_f32 v[222:223], v[244:245], v[212:213]
	v_pk_add_f32 v[212:213], v[244:245], v[212:213] neg_lo:[0,1] neg_hi:[0,1]
	v_pk_add_f32 v[218:219], v[218:219], v[230:231] neg_lo:[0,1] neg_hi:[0,1]
	v_pk_add_f32 v[230:231], v[202:203], v[228:229]
	v_pk_add_f32 v[202:203], v[202:203], v[228:229] neg_lo:[0,1] neg_hi:[0,1]
	v_xor_b32_e32 v229, 0x80000000, v212
	v_mov_b32_e32 v228, v213
	v_pk_add_f32 v[212:213], v[220:221], v[222:223]
	v_pk_add_f32 v[238:239], v[200:201], v[228:229]
	v_pk_add_f32 v[220:221], v[220:221], v[222:223] neg_lo:[0,1] neg_hi:[0,1]
	v_pk_add_f32 v[200:201], v[200:201], v[228:229] neg_lo:[0,1] neg_hi:[0,1]
	ds_write_b64 v181, v[206:207]
	ds_write_b64 v181, v[224:225] offset:2176
	ds_write_b64 v181, v[216:217] offset:4352
	ds_write_b64 v181, v[212:213] offset:6528
	ds_write_b64 v181, v[226:227] offset:8704
	ds_write_b64 v181, v[246:247] offset:10880
	ds_write_b64 v181, v[230:231] offset:13056
	ds_write_b64 v181, v[238:239] offset:15232
	ds_write_b64 v181, v[214:215] offset:17408
	ds_write_b64 v181, v[210:211] offset:19584
	ds_write_b64 v181, v[204:205] offset:21760
	ds_write_b64 v181, v[220:221] offset:23936
	ds_write_b64 v181, v[208:209] offset:26112
	ds_write_b64 v181, v[218:219] offset:28288
	ds_write_b64 v181, v[202:203] offset:30464
	ds_write_b64 v181, v[200:201] offset:32640
.LBB0_374:
	s_or_b64 exec, exec, s[2:3]
	v_mov_b32_e32 v200, v180
	s_waitcnt lgkmcnt(0)
	s_barrier
	s_nop 0
	v_cmp_gt_i32_e32 vcc, s56, v200
	s_and_saveexec_b64 s[2:3], vcc
	s_cbranch_execz .LBB0_376
	v_ashrrev_i32_e32 v181, 31, v200
	v_add_u32_sdwa v181, v200, v181 dst_sel:DWORD dst_unused:UNUSED_PAD src0_sel:DWORD src1_sel:BYTE_3
	v_ashrrev_i32_e32 v181, 8, v181
	v_mul_i32_i24_e32 v201, 0x100, v181
	v_sub_u32_e32 v237, v200, v201
	v_mul_i32_i24_e32 v181, 0x1100, v181
	v_lshlrev_b32_e32 v181, 3, v181
	v_ashrrev_i32_e32 v201, 4, v237
	v_add_u32_e32 v200, s57, v181
	v_lshlrev_b32_e32 v248, 3, v237
	v_lshlrev_b32_e32 v201, 3, v201
	v_add3_u32 v230, v200, v248, v201
	ds_read_b64 v[200:201], v230
	ds_read_b64 v[202:203], v230 offset:2176
	ds_read_b64 v[204:205], v230 offset:4352
	ds_read_b64 v[206:207], v230 offset:6528
	v_pk_mov_b32 v[208:209], v[44:45], v[44:45] op_sel:[1,0]
	v_pk_mov_b32 v[216:217], v[60:61], v[60:61] op_sel:[1,0]
	s_waitcnt lgkmcnt(3)
	v_pk_mul_f32 v[208:209], v[208:209], v[200:201] op_sel:[0,1]
	s_mov_b32 s35, s60
	v_pk_fma_f32 v[210:211], v[44:45], v[200:201], v[208:209] op_sel_hi:[1,0,1] neg_lo:[0,0,1]
	v_add_u32_e32 v181, 0, v181
	v_pk_mov_b32 v[200:201], v[48:49], v[48:49] op_sel:[1,0]
	s_waitcnt lgkmcnt(2)
	v_pk_mul_f32 v[200:201], v[200:201], v[202:203] op_sel:[0,1]
	s_nop 0
	v_pk_fma_f32 v[208:209], v[48:49], v[202:203], v[200:201] op_sel_hi:[1,0,1] neg_lo:[0,0,1]
	s_nop 0
	v_pk_mov_b32 v[200:201], v[52:53], v[52:53] op_sel:[1,0]
	s_waitcnt lgkmcnt(1)
	v_pk_mul_f32 v[200:201], v[200:201], v[204:205] op_sel:[0,1]
	s_nop 0
	v_pk_fma_f32 v[202:203], v[52:53], v[204:205], v[200:201] op_sel_hi:[1,0,1] neg_lo:[0,0,1]
	s_nop 0
	v_pk_mov_b32 v[200:201], v[56:57], v[56:57] op_sel:[1,0]
	s_waitcnt lgkmcnt(0)
	v_pk_mul_f32 v[200:201], v[200:201], v[206:207] op_sel:[0,1]
	s_nop 0
	v_pk_fma_f32 v[204:205], v[56:57], v[206:207], v[200:201] op_sel_hi:[1,0,1] neg_lo:[0,0,1]
	ds_read_b64 v[206:207], v230 offset:8704
	ds_read_b64 v[200:201], v230 offset:10880
	ds_read_b64 v[212:213], v230 offset:13056
	ds_read_b64 v[214:215], v230 offset:15232
	s_waitcnt lgkmcnt(3)
	v_pk_mul_f32 v[216:217], v[216:217], v[206:207] op_sel:[0,1]
	s_nop 0
	v_pk_fma_f32 v[218:219], v[60:61], v[206:207], v[216:217] op_sel_hi:[1,0,1] neg_lo:[0,0,1]
	s_nop 0
	v_pk_mov_b32 v[206:207], v[64:65], v[64:65] op_sel:[1,0]
	s_waitcnt lgkmcnt(2)
	v_pk_mul_f32 v[206:207], v[206:207], v[200:201] op_sel:[0,1]
	s_nop 0
	v_pk_fma_f32 v[216:217], v[64:65], v[200:201], v[206:207] op_sel_hi:[1,0,1] neg_lo:[0,0,1]
	s_nop 0
	v_pk_mov_b32 v[200:201], v[68:69], v[68:69] op_sel:[1,0]
	s_waitcnt lgkmcnt(1)
	v_pk_mul_f32 v[200:201], v[200:201], v[212:213] op_sel:[0,1]
	s_nop 0
	v_pk_fma_f32 v[206:207], v[68:69], v[212:213], v[200:201] op_sel_hi:[1,0,1] neg_lo:[0,0,1]
	s_nop 0
	s_waitcnt lgkmcnt(0)
	v_pk_mul_f32 v[200:201], v[138:139], v[214:215] op_sel:[0,1]
	s_nop 0
	v_pk_fma_f32 v[212:213], v[72:73], v[214:215], v[200:201] op_sel_hi:[1,0,1] neg_lo:[0,0,1]
	ds_read_b64 v[214:215], v230 offset:17408
	ds_read_b64 v[200:201], v230 offset:19584
	ds_read_b64 v[220:221], v230 offset:21760
	ds_read_b64 v[222:223], v230 offset:23936
	s_waitcnt lgkmcnt(3)
	v_pk_mul_f32 v[224:225], v[140:141], v[214:215] op_sel:[0,1]
	s_nop 0
	v_pk_fma_f32 v[226:227], v[76:77], v[214:215], v[224:225] op_sel_hi:[1,0,1] neg_lo:[0,0,1]
	s_nop 0
	s_waitcnt lgkmcnt(2)
	v_pk_mul_f32 v[214:215], v[142:143], v[200:201] op_sel:[0,1]
	s_nop 0
	v_pk_fma_f32 v[224:225], v[80:81], v[200:201], v[214:215] op_sel_hi:[1,0,1] neg_lo:[0,0,1]
	s_nop 0
	s_waitcnt lgkmcnt(1)
	v_pk_mul_f32 v[200:201], v[144:145], v[220:221] op_sel:[0,1]
	s_nop 0
	v_pk_fma_f32 v[214:215], v[86:87], v[220:221], v[200:201] op_sel_hi:[1,0,1] neg_lo:[0,0,1]
	s_nop 0
	s_waitcnt lgkmcnt(0)
	v_pk_mul_f32 v[200:201], v[146:147], v[222:223] op_sel:[0,1]
	s_nop 0
	v_pk_fma_f32 v[220:221], v[90:91], v[222:223], v[200:201] op_sel_hi:[1,0,1] neg_lo:[0,0,1]
	ds_read_b64 v[222:223], v230 offset:26112
	ds_read_b64 v[200:201], v230 offset:28288
	ds_read_b64 v[228:229], v230 offset:30464
	ds_read_b64 v[230:231], v230 offset:32640
	s_waitcnt lgkmcnt(3)
	v_pk_mul_f32 v[238:239], v[148:149], v[222:223] op_sel:[0,1]
	s_nop 0
	v_pk_fma_f32 v[242:243], v[94:95], v[222:223], v[238:239] op_sel_hi:[1,0,1] neg_lo:[0,0,1]
	s_nop 0
	s_waitcnt lgkmcnt(2)
	v_pk_mul_f32 v[222:223], v[150:151], v[200:201] op_sel:[0,1]
	s_nop 0
	v_pk_fma_f32 v[238:239], v[100:101], v[200:201], v[222:223] op_sel_hi:[1,0,1] neg_lo:[0,0,1]
	s_nop 0
	s_waitcnt lgkmcnt(1)
	v_pk_mul_f32 v[200:201], v[152:153], v[228:229] op_sel:[0,1]
	s_nop 0
	v_pk_fma_f32 v[222:223], v[104:105], v[228:229], v[200:201] op_sel_hi:[1,0,1] neg_lo:[0,0,1]
	s_nop 0
	s_waitcnt lgkmcnt(0)
	v_pk_mul_f32 v[200:201], v[154:155], v[230:231] op_sel:[0,1]
	s_nop 0
	v_pk_fma_f32 v[228:229], v[108:109], v[230:231], v[200:201] op_sel_hi:[1,0,1] neg_lo:[0,0,1]
	s_nop 0
	v_pk_add_f32 v[200:201], v[210:211], v[226:227]
	v_pk_add_f32 v[210:211], v[210:211], v[226:227] neg_lo:[0,1] neg_hi:[0,1]
	v_pk_add_f32 v[226:227], v[218:219], v[242:243]
	v_pk_add_f32 v[218:219], v[218:219], v[242:243] neg_lo:[0,1] neg_hi:[0,1]
	s_nop 0
	v_xor_b32_e32 v230, 0x80000000, v219
	v_mov_b32_e32 v231, v218
	v_pk_add_f32 v[218:219], v[200:201], v[226:227]
	v_pk_add_f32 v[200:201], v[200:201], v[226:227] neg_lo:[0,1] neg_hi:[0,1]
	v_pk_add_f32 v[226:227], v[208:209], v[224:225]
	v_pk_add_f32 v[208:209], v[208:209], v[224:225] neg_lo:[0,1] neg_hi:[0,1]
	v_pk_add_f32 v[224:225], v[216:217], v[238:239]
	v_pk_add_f32 v[216:217], v[216:217], v[238:239] neg_lo:[0,1] neg_hi:[0,1]
	v_pk_add_f32 v[242:243], v[210:211], v[230:231]
	v_pk_add_f32 v[210:211], v[210:211], v[230:231] neg_lo:[0,1] neg_hi:[0,1]
	v_xor_b32_e32 v230, 0x80000000, v217
	v_mov_b32_e32 v231, v216
	v_pk_add_f32 v[216:217], v[226:227], v[224:225]
	v_pk_add_f32 v[224:225], v[226:227], v[224:225] neg_lo:[0,1] neg_hi:[0,1]
	v_pk_add_f32 v[226:227], v[202:203], v[214:215]
	v_pk_add_f32 v[202:203], v[202:203], v[214:215] neg_lo:[0,1] neg_hi:[0,1]
	v_pk_add_f32 v[214:215], v[206:207], v[222:223]
	v_pk_add_f32 v[206:207], v[206:207], v[222:223] neg_lo:[0,1] neg_hi:[0,1]
	v_pk_add_f32 v[238:239], v[208:209], v[230:231]
	v_pk_add_f32 v[208:209], v[208:209], v[230:231] neg_lo:[0,1] neg_hi:[0,1]
	v_pk_add_f32 v[230:231], v[202:203], v[206:207] op_sel:[0,1] op_sel_hi:[1,0] neg_lo:[0,1]
	v_pk_add_f32 v[202:203], v[202:203], v[206:207] op_sel:[0,1] op_sel_hi:[1,0] neg_hi:[0,1]
	v_pk_add_f32 v[222:223], v[204:205], v[220:221]
	v_pk_add_f32 v[204:205], v[204:205], v[220:221] neg_lo:[0,1] neg_hi:[0,1]
	v_pk_add_f32 v[220:221], v[212:213], v[228:229]
	v_pk_add_f32 v[212:213], v[212:213], v[228:229] neg_lo:[0,1] neg_hi:[0,1]
	v_pk_add_f32 v[206:207], v[226:227], v[214:215]
	v_pk_add_f32 v[214:215], v[226:227], v[214:215] neg_lo:[0,1] neg_hi:[0,1]
	v_xor_b32_e32 v226, 0x80000000, v213
	v_mov_b32_e32 v227, v212
	v_pk_add_f32 v[212:213], v[222:223], v[220:221]
	v_pk_add_f32 v[220:221], v[222:223], v[220:221] neg_lo:[0,1] neg_hi:[0,1]
	v_pk_mul_f32 v[222:223], v[238:239], s[24:25] op_sel_hi:[1,0]
	v_pk_add_f32 v[228:229], v[204:205], v[226:227]
	v_pk_add_f32 v[204:205], v[204:205], v[226:227] neg_lo:[0,1] neg_hi:[0,1]
	v_pk_fma_f32 v[226:227], v[238:239], s[26:27], v[222:223] op_sel:[0,0,1] op_sel_hi:[1,0,0] neg_lo:[0,0,1]
	s_nop 0
	v_pk_mul_f32 v[222:223], v[224:225], s[28:29] op_sel_hi:[1,0]
	s_nop 0
	v_pk_fma_f32 v[238:239], v[224:225], s[28:29], v[222:223] op_sel:[0,0,1] op_sel_hi:[1,0,0] neg_lo:[0,0,1]
	v_pk_mul_f32 v[224:225], v[208:209], s[26:27] op_sel_hi:[1,0]
	v_pk_fma_f32 v[244:245], v[208:209], s[24:25], v[224:225] op_sel:[0,0,1] op_sel_hi:[1,0,0] neg_lo:[0,0,1]
	s_nop 0
	v_pk_mul_f32 v[208:209], v[230:231], s[28:29] op_sel_hi:[1,0]
	s_nop 0
	v_pk_fma_f32 v[224:225], v[230:231], s[28:29], v[208:209] op_sel:[0,0,1] op_sel_hi:[1,0,0] neg_lo:[0,0,1]
	s_nop 0
	v_pk_fma_f32 v[208:209], v[214:215], 0, v[214:215] op_sel:[0,0,1] op_sel_hi:[1,0,0] neg_lo:[0,0,1]
	s_nop 0
	v_pk_mul_f32 v[214:215], v[202:203], s[30:31] op_sel_hi:[1,0]
	s_nop 0
	v_pk_fma_f32 v[230:231], v[202:203], s[30:31], v[214:215] op_sel:[0,0,1] op_sel_hi:[1,0,0] neg_hi:[0,0,1]
	v_pk_mul_f32 v[214:215], v[228:229], s[26:27] op_sel_hi:[1,0]
	v_pk_fma_f32 v[246:247], v[228:229], s[24:25], v[214:215] op_sel:[0,0,1] op_sel_hi:[1,0,0] neg_lo:[0,0,1]
	s_mov_b32 s25, s34
	v_pk_mul_f32 v[214:215], v[220:221], s[30:31] op_sel_hi:[1,0]
	v_pk_add_f32 v[202:203], v[210:211], v[230:231]
	v_pk_fma_f32 v[228:229], v[220:221], s[30:31], v[214:215] op_sel:[0,0,1] op_sel_hi:[1,0,0] neg_hi:[0,0,1]
	v_pk_add_f32 v[210:211], v[210:211], v[230:231] neg_lo:[0,1] neg_hi:[0,1]
	v_pk_mul_f32 v[214:215], v[204:205], s[34:35] op_sel_hi:[0,1]
	v_pk_fma_f32 v[204:205], v[204:205], s[24:25], v[214:215] op_sel:[1,0,0]
	v_pk_add_f32 v[214:215], v[218:219], v[206:207]
	v_pk_add_f32 v[206:207], v[218:219], v[206:207] neg_lo:[0,1] neg_hi:[0,1]
	v_pk_add_f32 v[218:219], v[216:217], v[212:213]
	v_pk_add_f32 v[212:213], v[216:217], v[212:213] neg_lo:[0,1] neg_hi:[0,1]
	v_pk_add_f32 v[222:223], v[238:239], v[228:229] neg_lo:[0,1] neg_hi:[0,1]
	v_xor_b32_e32 v216, 0x80000000, v213
	v_mov_b32_e32 v217, v212
	v_pk_add_f32 v[212:213], v[214:215], v[218:219]
	v_pk_add_f32 v[220:221], v[206:207], v[216:217]
	v_pk_add_f32 v[214:215], v[214:215], v[218:219] neg_lo:[0,1] neg_hi:[0,1]
	v_pk_add_f32 v[206:207], v[206:207], v[216:217] neg_lo:[0,1] neg_hi:[0,1]
	v_pk_add_f32 v[216:217], v[242:243], v[224:225]
	v_pk_add_f32 v[218:219], v[242:243], v[224:225] neg_lo:[0,1] neg_hi:[0,1]
	v_pk_add_f32 v[224:225], v[226:227], v[246:247]
	v_pk_add_f32 v[226:227], v[226:227], v[246:247] neg_lo:[0,1] neg_hi:[0,1]
	s_nop 0
	v_xor_b32_e32 v242, 0x80000000, v227
	v_mov_b32_e32 v243, v226
	v_pk_add_f32 v[226:227], v[216:217], v[224:225]
	v_pk_add_f32 v[216:217], v[216:217], v[224:225] neg_lo:[0,1] neg_hi:[0,1]
	v_pk_add_f32 v[224:225], v[200:201], v[208:209]
	v_pk_add_f32 v[200:201], v[200:201], v[208:209] neg_lo:[0,1] neg_hi:[0,1]
	v_pk_add_f32 v[208:209], v[238:239], v[228:229]
	v_xor_b32_e32 v228, 0x80000000, v223
	v_mov_b32_e32 v229, v222
	v_pk_add_f32 v[222:223], v[224:225], v[208:209]
	v_pk_add_f32 v[208:209], v[224:225], v[208:209] neg_lo:[0,1] neg_hi:[0,1]
	v_pk_add_f32 v[224:225], v[244:245], v[204:205]
	v_pk_add_f32 v[204:205], v[244:245], v[204:205] neg_lo:[0,1] neg_hi:[0,1]
	v_pk_add_f32 v[238:239], v[200:201], v[228:229]
	v_pk_add_f32 v[200:201], v[200:201], v[228:229] neg_lo:[0,1] neg_hi:[0,1]
	v_xor_b32_e32 v228, 0x80000000, v205
	v_mov_b32_e32 v229, v204
	v_pk_add_f32 v[204:205], v[202:203], v[224:225]
	v_pk_add_f32 v[202:203], v[202:203], v[224:225] neg_lo:[0,1] neg_hi:[0,1]
	v_lshlrev_b32_e32 v224, 7, v237
	v_add3_u32 v181, v181, v224, v248
	v_add_u32_e32 v224, 0x1880, v181
	ds_write2_b64 v224, v[212:213], v[226:227] offset1:1
	v_add_u32_e32 v212, 0x1890, v181
	v_pk_add_f32 v[246:247], v[218:219], v[242:243]
	ds_write2_b64 v212, v[222:223], v[204:205] offset1:1
	v_add_u32_e32 v204, 0x18a0, v181
	v_pk_add_f32 v[230:231], v[210:211], v[228:229]
	ds_write2_b64 v204, v[220:221], v[246:247] offset1:1
	v_add_u32_e32 v204, 0x18b0, v181
	ds_write2_b64 v204, v[238:239], v[230:231] offset1:1
	v_add_u32_e32 v204, 0x18c0, v181
	ds_write2_b64 v204, v[214:215], v[216:217] offset1:1
	v_add_u32_e32 v204, 0x18d0, v181
	v_pk_add_f32 v[218:219], v[218:219], v[242:243] neg_lo:[0,1] neg_hi:[0,1]
	v_pk_add_f32 v[210:211], v[210:211], v[228:229] neg_lo:[0,1] neg_hi:[0,1]
	ds_write2_b64 v204, v[208:209], v[202:203] offset1:1
	v_add_u32_e32 v202, 0x18e0, v181
	v_add_u32_e32 v181, 0x18f0, v181
	ds_write2_b64 v202, v[206:207], v[218:219] offset1:1
	ds_write2_b64 v181, v[200:201], v[210:211] offset1:1

.LBB0_378:
	s_or_b64 exec, exec, s[2:3]
	v_mov_b32_e32 v200, v180
	s_waitcnt lgkmcnt(0)
	s_barrier
	s_nop 0
	v_cmp_gt_i32_e32 vcc, s56, v200
	s_and_saveexec_b64 s[2:3], vcc
	s_cbranch_execz .LBB0_380
	v_ashrrev_i32_e32 v181, 31, v200
	v_add_u32_sdwa v181, v200, v181 dst_sel:DWORD dst_unused:UNUSED_PAD src0_sel:DWORD src1_sel:BYTE_3
	v_ashrrev_i32_e32 v181, 8, v181
	v_mul_i32_i24_e32 v201, 0x100, v181
	v_sub_u32_e32 v200, v200, v201
	v_mul_i32_i24_e32 v181, 0x1100, v181
	v_lshlrev_b32_e32 v181, 3, v181
	v_lshlrev_b32_e32 v224, 3, v200
	v_ashrrev_i32_e32 v200, 4, v200
	v_add_u32_e32 v201, s57, v181
	v_lshlrev_b32_e32 v237, 3, v200
	v_add3_u32 v238, v201, v224, v237
	v_add_u32_e32 v252, 0, v224
	ds_read_b64 v[200:201], v238
	ds_read_b64 v[202:203], v238 offset:2176
	ds_read_b64 v[204:205], v238 offset:4352
	ds_read_b64 v[206:207], v238 offset:6528
	ds_read_b64 v[208:209], v238 offset:8704
	ds_read_b64 v[210:211], v238 offset:10880
	ds_read_b64 v[212:213], v238 offset:13056
	ds_read_b64 v[214:215], v238 offset:15232
	ds_read_b64 v[216:217], v238 offset:17408
	ds_read_b64 v[218:219], v238 offset:19584
	ds_read_b64 v[220:221], v238 offset:21760
	ds_read_b64 v[222:223], v238 offset:23936
	ds_read_b64 v[224:225], v252
	ds_read_b64 v[226:227], v238 offset:26112
	ds_read_b64 v[228:229], v238 offset:28288
	ds_read_b64 v[230:231], v238 offset:30464
	ds_read_b64 v[238:239], v238 offset:32640
	s_waitcnt lgkmcnt(4)
	v_pk_mul_f32 v[244:245], v[202:203], v[224:225] op_sel:[0,1]
	v_xor_b32_e32 v242, 0x80000000, v225
	v_pk_fma_f32 v[246:247], v[202:203], v[224:225], v[244:245] op_sel:[0,0,1] op_sel_hi:[1,0,0] neg_hi:[0,0,1]
	v_mov_b32_e32 v243, v224
	v_pk_mul_f32 v[202:203], v[224:225], v[224:225] op_sel:[1,0]
	s_mov_b32 s35, s60
	v_pk_fma_f32 v[202:203], v[224:225], v[242:243], v[202:203] op_sel_hi:[0,1,1] neg_lo:[0,0,1] neg_hi:[0,0,1]
	v_pk_mul_f32 v[242:243], v[204:205], v[202:203] op_sel:[1,0] op_sel_hi:[0,0]
	v_pk_fma_f32 v[244:245], v[204:205], v[202:203], v[242:243] op_sel:[0,1,0] neg_lo:[0,0,1]
	v_add3_u32 v181, v252, v181, v237
	v_pk_mul_f32 v[204:205], v[224:225], v[202:203] op_sel:[0,1] op_sel_hi:[1,0]
	v_pk_mul_f32 v[202:203], v[224:225], v[202:203]
	v_pk_add_f32 v[204:205], v[204:205], v[204:205] op_sel:[0,1] op_sel_hi:[0,1]
	v_pk_add_f32 v[202:203], v[202:203], v[202:203] op_sel:[0,1] op_sel_hi:[0,1] neg_lo:[0,1] neg_hi:[0,1]
	v_pk_mul_f32 v[242:243], v[206:207], v[202:203]
	s_nop 0
	v_pk_fma_f32 v[248:249], v[206:207], v[204:205], v[242:243] op_sel:[0,0,1] op_sel_hi:[1,1,0] neg_lo:[0,0,1]
	v_pk_mul_f32 v[204:205], v[224:225], v[204:205]
	v_pk_fma_f32 v[206:207], v[224:225], v[202:203], v[204:205] op_sel:[0,0,1] op_sel_hi:[1,1,0] neg_lo:[0,0,1] neg_hi:[0,0,1]
	v_pk_fma_f32 v[202:203], v[224:225], v[202:203], v[204:205] op_sel:[0,0,1] op_sel_hi:[1,1,0]
	v_mov_b32_e32 v204, v206
	v_mov_b32_e32 v205, v203
	v_pk_mul_f32 v[242:243], v[208:209], v[206:207] op_sel:[1,0] op_sel_hi:[0,0]
	v_pk_mov_b32 v[206:207], v[202:203], v[206:207] op_sel:[1,0]
	v_pk_fma_f32 v[250:251], v[208:209], v[202:203], v[242:243] op_sel:[0,1,0] neg_lo:[0,0,1]
	v_pk_mul_f32 v[204:205], v[224:225], v[204:205]
	v_pk_mul_f32 v[202:203], v[224:225], v[206:207]
	v_pk_add_f32 v[204:205], v[204:205], v[204:205] op_sel:[0,1] op_sel_hi:[0,1] neg_lo:[0,1] neg_hi:[0,1]
	v_pk_mul_f32 v[206:207], v[210:211], v[204:205]
	v_pk_add_f32 v[202:203], v[202:203], v[202:203] op_sel:[0,1] op_sel_hi:[0,1]
	v_pk_fma_f32 v[208:209], v[210:211], v[202:203], v[206:207] op_sel:[0,0,1] op_sel_hi:[1,1,0] neg_lo:[0,0,1]
	v_pk_mul_f32 v[202:203], v[224:225], v[202:203]
	v_pk_fma_f32 v[206:207], v[224:225], v[204:205], v[202:203] op_sel:[0,0,1] op_sel_hi:[1,1,0] neg_lo:[0,0,1] neg_hi:[0,0,1]
	v_pk_fma_f32 v[202:203], v[224:225], v[204:205], v[202:203] op_sel:[0,0,1] op_sel_hi:[1,1,0]
	v_mov_b32_e32 v204, v206
	v_mov_b32_e32 v205, v203
	v_pk_mul_f32 v[210:211], v[212:213], v[206:207] op_sel:[1,0] op_sel_hi:[0,0]
	v_pk_mov_b32 v[206:207], v[202:203], v[206:207] op_sel:[1,0]
	v_pk_fma_f32 v[242:243], v[212:213], v[202:203], v[210:211] op_sel:[0,1,0] neg_lo:[0,0,1]
	v_pk_mul_f32 v[204:205], v[224:225], v[204:205]
	v_pk_mul_f32 v[202:203], v[224:225], v[206:207]
	v_pk_add_f32 v[204:205], v[204:205], v[204:205] op_sel:[0,1] op_sel_hi:[0,1] neg_lo:[0,1] neg_hi:[0,1]
	v_pk_mul_f32 v[206:207], v[214:215], v[204:205]
	v_pk_add_f32 v[202:203], v[202:203], v[202:203] op_sel:[0,1] op_sel_hi:[0,1]
	v_pk_fma_f32 v[210:211], v[214:215], v[202:203], v[206:207] op_sel:[0,0,1] op_sel_hi:[1,1,0] neg_lo:[0,0,1]
	v_pk_mul_f32 v[202:203], v[224:225], v[202:203]
	v_pk_fma_f32 v[206:207], v[224:225], v[204:205], v[202:203] op_sel:[0,0,1] op_sel_hi:[1,1,0] neg_lo:[0,0,1] neg_hi:[0,0,1]
	v_pk_fma_f32 v[202:203], v[224:225], v[204:205], v[202:203] op_sel:[0,0,1] op_sel_hi:[1,1,0]
	v_mov_b32_e32 v204, v206
	v_mov_b32_e32 v205, v203
	v_pk_mul_f32 v[212:213], v[216:217], v[206:207] op_sel:[1,0] op_sel_hi:[0,0]
	v_pk_mov_b32 v[206:207], v[202:203], v[206:207] op_sel:[1,0]
	v_pk_fma_f32 v[214:215], v[216:217], v[202:203], v[212:213] op_sel:[0,1,0] neg_lo:[0,0,1]
	v_pk_mul_f32 v[204:205], v[224:225], v[204:205]
	v_pk_mul_f32 v[202:203], v[224:225], v[206:207]
	v_pk_add_f32 v[204:205], v[204:205], v[204:205] op_sel:[0,1] op_sel_hi:[0,1] neg_lo:[0,1] neg_hi:[0,1]
	v_pk_mul_f32 v[206:207], v[218:219], v[204:205]
	v_pk_add_f32 v[202:203], v[202:203], v[202:203] op_sel:[0,1] op_sel_hi:[0,1]
	v_pk_fma_f32 v[212:213], v[218:219], v[202:203], v[206:207] op_sel:[0,0,1] op_sel_hi:[1,1,0] neg_lo:[0,0,1]
	v_pk_mul_f32 v[202:203], v[224:225], v[202:203]
	v_pk_fma_f32 v[206:207], v[224:225], v[204:205], v[202:203] op_sel:[0,0,1] op_sel_hi:[1,1,0] neg_lo:[0,0,1] neg_hi:[0,0,1]
	v_pk_fma_f32 v[202:203], v[224:225], v[204:205], v[202:203] op_sel:[0,0,1] op_sel_hi:[1,1,0]
	v_mov_b32_e32 v204, v206
	v_mov_b32_e32 v205, v203
	v_pk_mul_f32 v[216:217], v[220:221], v[206:207] op_sel:[1,0] op_sel_hi:[0,0]
	v_pk_mov_b32 v[206:207], v[202:203], v[206:207] op_sel:[1,0]
	v_pk_fma_f32 v[218:219], v[220:221], v[202:203], v[216:217] op_sel:[0,1,0] neg_lo:[0,0,1]
	v_pk_mul_f32 v[204:205], v[224:225], v[204:205]
	v_pk_mul_f32 v[202:203], v[224:225], v[206:207]
	v_pk_add_f32 v[204:205], v[204:205], v[204:205] op_sel:[0,1] op_sel_hi:[0,1] neg_lo:[0,1] neg_hi:[0,1]
	v_pk_mul_f32 v[206:207], v[222:223], v[204:205]
	v_pk_add_f32 v[202:203], v[202:203], v[202:203] op_sel:[0,1] op_sel_hi:[0,1]
	v_pk_fma_f32 v[216:217], v[222:223], v[202:203], v[206:207] op_sel:[0,0,1] op_sel_hi:[1,1,0] neg_lo:[0,0,1]
	v_pk_mul_f32 v[202:203], v[224:225], v[202:203]
	v_pk_fma_f32 v[206:207], v[224:225], v[204:205], v[202:203] op_sel:[0,0,1] op_sel_hi:[1,1,0] neg_lo:[0,0,1] neg_hi:[0,0,1]
	v_pk_fma_f32 v[202:203], v[224:225], v[204:205], v[202:203] op_sel:[0,0,1] op_sel_hi:[1,1,0]
	v_mov_b32_e32 v204, v206
	v_mov_b32_e32 v205, v203
	s_waitcnt lgkmcnt(3)
	v_pk_mul_f32 v[220:221], v[226:227], v[206:207] op_sel:[1,0] op_sel_hi:[0,0]
	v_pk_mov_b32 v[206:207], v[202:203], v[206:207] op_sel:[1,0]
	v_pk_fma_f32 v[222:223], v[226:227], v[202:203], v[220:221] op_sel:[0,1,0] neg_lo:[0,0,1]
	v_pk_mul_f32 v[204:205], v[224:225], v[204:205]
	v_pk_mul_f32 v[202:203], v[224:225], v[206:207]
	v_pk_add_f32 v[204:205], v[204:205], v[204:205] op_sel:[0,1] op_sel_hi:[0,1] neg_lo:[0,1] neg_hi:[0,1]
	s_waitcnt lgkmcnt(2)
	v_pk_mul_f32 v[206:207], v[228:229], v[204:205]
	v_pk_add_f32 v[202:203], v[202:203], v[202:203] op_sel:[0,1] op_sel_hi:[0,1]
	v_pk_fma_f32 v[220:221], v[228:229], v[202:203], v[206:207] op_sel:[0,0,1] op_sel_hi:[1,1,0] neg_lo:[0,0,1]
	v_pk_mul_f32 v[202:203], v[224:225], v[202:203]
	v_pk_fma_f32 v[206:207], v[224:225], v[204:205], v[202:203] op_sel:[0,0,1] op_sel_hi:[1,1,0] neg_lo:[0,0,1] neg_hi:[0,0,1]
	v_pk_fma_f32 v[202:203], v[224:225], v[204:205], v[202:203] op_sel:[0,0,1] op_sel_hi:[1,1,0]
	v_mov_b32_e32 v204, v206
	v_mov_b32_e32 v205, v203
	s_waitcnt lgkmcnt(1)
	v_pk_mul_f32 v[226:227], v[230:231], v[206:207] op_sel:[1,0] op_sel_hi:[0,0]
	v_pk_mov_b32 v[206:207], v[202:203], v[206:207] op_sel:[1,0]
	v_pk_fma_f32 v[228:229], v[230:231], v[202:203], v[226:227] op_sel:[0,1,0] neg_lo:[0,0,1]
	v_pk_mul_f32 v[204:205], v[224:225], v[204:205]
	v_pk_mul_f32 v[202:203], v[224:225], v[206:207]
	v_pk_add_f32 v[204:205], v[204:205], v[204:205] op_sel:[0,1] op_sel_hi:[0,1] neg_lo:[0,1] neg_hi:[0,1]
	s_waitcnt lgkmcnt(0)
	v_pk_mul_f32 v[204:205], v[238:239], v[204:205] op_sel:[1,0] op_sel_hi:[0,1]
	v_pk_add_f32 v[202:203], v[202:203], v[202:203] op_sel:[0,1] op_sel_hi:[0,1]
	v_pk_fma_f32 v[206:207], v[238:239], v[202:203], v[204:205] neg_lo:[0,0,1]
	v_pk_add_f32 v[204:205], v[250:251], v[222:223]
	v_pk_add_f32 v[202:203], v[200:201], v[214:215]
	v_pk_add_f32 v[200:201], v[200:201], v[214:215] neg_lo:[0,1] neg_hi:[0,1]
	v_pk_add_f32 v[214:215], v[250:251], v[222:223] neg_lo:[0,1] neg_hi:[0,1]
	s_nop 0
	v_xor_b32_e32 v222, 0x80000000, v215
	v_mov_b32_e32 v223, v214
	v_pk_add_f32 v[214:215], v[202:203], v[204:205]
	v_pk_add_f32 v[224:225], v[200:201], v[222:223]
	v_pk_add_f32 v[202:203], v[202:203], v[204:205] neg_lo:[0,1] neg_hi:[0,1]
	v_pk_add_f32 v[200:201], v[200:201], v[222:223] neg_lo:[0,1] neg_hi:[0,1]
	v_pk_add_f32 v[204:205], v[246:247], v[212:213]
	v_pk_add_f32 v[222:223], v[208:209], v[220:221]
	v_pk_add_f32 v[208:209], v[208:209], v[220:221] neg_lo:[0,1] neg_hi:[0,1]
	v_pk_add_f32 v[212:213], v[246:247], v[212:213] neg_lo:[0,1] neg_hi:[0,1]
	v_xor_b32_e32 v220, 0x80000000, v209
	v_mov_b32_e32 v221, v208
	v_pk_add_f32 v[208:209], v[204:205], v[222:223]
	v_pk_add_f32 v[204:205], v[204:205], v[222:223] neg_lo:[0,1] neg_hi:[0,1]
	v_pk_add_f32 v[222:223], v[242:243], v[228:229]
	v_pk_add_f32 v[228:229], v[242:243], v[228:229] neg_lo:[0,1] neg_hi:[0,1]
	v_pk_add_f32 v[226:227], v[212:213], v[220:221]
	v_pk_add_f32 v[212:213], v[212:213], v[220:221] neg_lo:[0,1] neg_hi:[0,1]
	v_pk_add_f32 v[220:221], v[244:245], v[218:219]
	v_pk_add_f32 v[218:219], v[244:245], v[218:219] neg_lo:[0,1] neg_hi:[0,1]
	v_pk_add_f32 v[238:239], v[218:219], v[228:229] op_sel:[0,1] op_sel_hi:[1,0] neg_lo:[0,1]
	v_pk_add_f32 v[218:219], v[218:219], v[228:229] op_sel:[0,1] op_sel_hi:[1,0] neg_hi:[0,1]
	v_pk_add_f32 v[230:231], v[210:211], v[206:207]
	v_pk_add_f32 v[206:207], v[210:211], v[206:207] neg_lo:[0,1] neg_hi:[0,1]
	v_pk_add_f32 v[228:229], v[220:221], v[222:223]
	v_pk_add_f32 v[220:221], v[220:221], v[222:223] neg_lo:[0,1] neg_hi:[0,1]
	v_pk_add_f32 v[222:223], v[248:249], v[216:217]
	v_pk_add_f32 v[216:217], v[248:249], v[216:217] neg_lo:[0,1] neg_hi:[0,1]
	v_pk_add_f32 v[242:243], v[216:217], v[206:207] op_sel:[0,1] op_sel_hi:[1,0] neg_lo:[0,1]
	v_pk_add_f32 v[210:211], v[216:217], v[206:207] op_sel:[0,1] op_sel_hi:[1,0] neg_hi:[0,1]
	v_pk_mul_f32 v[216:217], v[226:227], s[24:25] op_sel_hi:[1,0]
	v_pk_add_f32 v[206:207], v[222:223], v[230:231]
	v_pk_add_f32 v[222:223], v[222:223], v[230:231] neg_lo:[0,1] neg_hi:[0,1]
	v_pk_fma_f32 v[230:231], v[226:227], s[26:27], v[216:217] op_sel:[0,0,1] op_sel_hi:[1,0,0] neg_lo:[0,0,1]
	s_nop 0
	v_pk_mul_f32 v[216:217], v[204:205], s[28:29] op_sel_hi:[1,0]
	s_nop 0
	v_pk_fma_f32 v[226:227], v[204:205], s[28:29], v[216:217] op_sel:[0,0,1] op_sel_hi:[1,0,0] neg_lo:[0,0,1]
	v_pk_mul_f32 v[216:217], v[212:213], s[26:27] op_sel_hi:[1,0]
	v_pk_fma_f32 v[244:245], v[212:213], s[24:25], v[216:217] op_sel:[0,0,1] op_sel_hi:[1,0,0] neg_lo:[0,0,1]
	s_nop 0
	v_pk_mul_f32 v[212:213], v[238:239], s[28:29] op_sel_hi:[1,0]
	s_nop 0
	v_pk_fma_f32 v[216:217], v[238:239], s[28:29], v[212:213] op_sel:[0,0,1] op_sel_hi:[1,0,0] neg_lo:[0,0,1]
	s_nop 0
	v_pk_fma_f32 v[212:213], v[220:221], 0, v[220:221] op_sel:[0,0,1] op_sel_hi:[1,0,0] neg_lo:[0,0,1]
	s_nop 0
	v_pk_mul_f32 v[220:221], v[218:219], s[30:31] op_sel_hi:[1,0]
	s_nop 0
	v_pk_fma_f32 v[238:239], v[218:219], s[30:31], v[220:221] op_sel:[0,0,1] op_sel_hi:[1,0,0] neg_hi:[0,0,1]
	v_pk_mul_f32 v[220:221], v[242:243], s[26:27] op_sel_hi:[1,0]
	v_pk_fma_f32 v[246:247], v[242:243], s[24:25], v[220:221] op_sel:[0,0,1] op_sel_hi:[1,0,0] neg_lo:[0,0,1]
	s_mov_b32 s25, s34
	v_pk_mul_f32 v[220:221], v[222:223], s[30:31] op_sel_hi:[1,0]
	v_pk_add_f32 v[218:219], v[200:201], v[238:239]
	v_pk_fma_f32 v[242:243], v[222:223], s[30:31], v[220:221] op_sel:[0,0,1] op_sel_hi:[1,0,0] neg_hi:[0,0,1]
	v_pk_add_f32 v[222:223], v[208:209], v[206:207]
	v_pk_mul_f32 v[220:221], v[210:211], s[34:35] op_sel_hi:[0,1]
	v_pk_add_f32 v[206:207], v[208:209], v[206:207] neg_lo:[0,1] neg_hi:[0,1]
	v_pk_fma_f32 v[210:211], v[210:211], s[24:25], v[220:221] op_sel:[1,0,0]
	v_pk_add_f32 v[220:221], v[214:215], v[228:229]
	v_pk_add_f32 v[214:215], v[214:215], v[228:229] neg_lo:[0,1] neg_hi:[0,1]
	v_xor_b32_e32 v208, 0x80000000, v207
	v_mov_b32_e32 v209, v206
	v_pk_add_f32 v[206:207], v[220:221], v[222:223]
	v_pk_add_f32 v[228:229], v[214:215], v[208:209]
	v_pk_add_f32 v[220:221], v[220:221], v[222:223] neg_lo:[0,1] neg_hi:[0,1]
	v_pk_add_f32 v[208:209], v[214:215], v[208:209] neg_lo:[0,1] neg_hi:[0,1]
	v_pk_add_f32 v[214:215], v[224:225], v[216:217]
	v_pk_add_f32 v[216:217], v[224:225], v[216:217] neg_lo:[0,1] neg_hi:[0,1]
	v_pk_add_f32 v[222:223], v[230:231], v[246:247]
	v_pk_add_f32 v[224:225], v[230:231], v[246:247] neg_lo:[0,1] neg_hi:[0,1]
	v_pk_add_f32 v[204:205], v[226:227], v[242:243]
	v_xor_b32_e32 v230, 0x80000000, v225
	v_mov_b32_e32 v231, v224
	v_pk_add_f32 v[224:225], v[214:215], v[222:223]
	v_pk_add_f32 v[214:215], v[214:215], v[222:223] neg_lo:[0,1] neg_hi:[0,1]
	v_pk_add_f32 v[222:223], v[202:203], v[212:213]
	v_pk_add_f32 v[202:203], v[202:203], v[212:213] neg_lo:[0,1] neg_hi:[0,1]
	v_pk_add_f32 v[212:213], v[226:227], v[242:243] neg_lo:[0,1] neg_hi:[0,1]
	v_pk_add_f32 v[246:247], v[216:217], v[230:231]
	v_xor_b32_e32 v226, 0x80000000, v213
	v_mov_b32_e32 v227, v212
	v_pk_add_f32 v[212:213], v[222:223], v[204:205]
	v_pk_add_f32 v[204:205], v[222:223], v[204:205] neg_lo:[0,1] neg_hi:[0,1]
	v_pk_add_f32 v[222:223], v[244:245], v[210:211]
	v_pk_add_f32 v[210:211], v[244:245], v[210:211] neg_lo:[0,1] neg_hi:[0,1]
	v_pk_add_f32 v[216:217], v[216:217], v[230:231] neg_lo:[0,1] neg_hi:[0,1]
	v_pk_add_f32 v[230:231], v[202:203], v[226:227]
	v_pk_add_f32 v[202:203], v[202:203], v[226:227] neg_lo:[0,1] neg_hi:[0,1]
	v_pk_add_f32 v[200:201], v[200:201], v[238:239] neg_lo:[0,1] neg_hi:[0,1]
	v_xor_b32_e32 v226, 0x80000000, v211
	v_mov_b32_e32 v227, v210
	v_pk_add_f32 v[210:211], v[218:219], v[222:223]
	v_pk_add_f32 v[238:239], v[200:201], v[226:227]
	v_pk_add_f32 v[218:219], v[218:219], v[222:223] neg_lo:[0,1] neg_hi:[0,1]
	v_pk_add_f32 v[200:201], v[200:201], v[226:227] neg_lo:[0,1] neg_hi:[0,1]
	ds_write_b64 v181, v[206:207] offset:6272
	ds_write_b64 v181, v[224:225] offset:8448
	ds_write_b64 v181, v[212:213] offset:10624
	ds_write_b64 v181, v[210:211] offset:12800
	ds_write_b64 v181, v[228:229] offset:14976
	ds_write_b64 v181, v[246:247] offset:17152
	ds_write_b64 v181, v[230:231] offset:19328
	ds_write_b64 v181, v[238:239] offset:21504
	ds_write_b64 v181, v[220:221] offset:23680
	ds_write_b64 v181, v[214:215] offset:25856
	ds_write_b64 v181, v[204:205] offset:28032
	ds_write_b64 v181, v[218:219] offset:30208
	ds_write_b64 v181, v[208:209] offset:32384
	ds_write_b64 v181, v[216:217] offset:34560
	ds_write_b64 v181, v[202:203] offset:36736
	ds_write_b64 v181, v[200:201] offset:38912

.LBB0_489:
	s_or_b64 exec, exec, s[2:3]
	v_ashrrev_i32_e32 v1, 2, v88
	v_add_u32_e32 v197, v18, v1
	s_waitcnt vmcnt(2)
	v_lshlrev_b32_e32 v1, 16, v52
	v_mul_f32_e32 v5, v94, v89
	v_and_b32_e32 v2, 0xffff0000, v52
	v_fmac_f32_e32 v5, v96, v1
	v_fmac_f32_e32 v5, v95, v2
	v_lshlrev_b32_e32 v3, 16, v53
	v_add_f32_e32 v89, v93, v5
	v_mul_f32_e32 v5, v96, v2
	v_fmac_f32_e32 v5, v94, v1
	v_mul_f32_e32 v1, v96, v3
	v_and_b32_e32 v4, 0xffff0000, v53
	v_fmac_f32_e32 v1, v94, v2
	v_fmac_f32_e32 v1, v95, v4
	v_add_f32_e32 v85, v93, v1
	v_mul_f32_e32 v1, v96, v4
	v_fmac_f32_e32 v1, v94, v3
	v_fmac_f32_e32 v5, v95, v3
	v_fmac_f32_e32 v1, v95, v105
	v_add_f32_e32 v91, v93, v5
	v_add_f32_e32 v87, v93, v1
	v_lshlrev_b32_e32 v1, 16, v50
	v_mul_f32_e32 v5, v94, v90
	v_and_b32_e32 v2, 0xffff0000, v50
	v_fmac_f32_e32 v5, v96, v1
	v_fmac_f32_e32 v5, v95, v2
	v_lshlrev_b32_e32 v3, 16, v51
	v_add_f32_e32 v88, v93, v5
	v_mul_f32_e32 v5, v96, v2
	v_fmac_f32_e32 v5, v94, v1
	v_mul_f32_e32 v1, v96, v3
	v_and_b32_e32 v4, 0xffff0000, v51
	v_fmac_f32_e32 v1, v94, v2
	v_fmac_f32_e32 v1, v95, v4
	v_add_f32_e32 v84, v93, v1
	v_mul_f32_e32 v1, v96, v4
	v_fmac_f32_e32 v1, v94, v3
	v_fmac_f32_e32 v1, v95, v104
	v_add_f32_e32 v86, v93, v1
	v_lshlrev_b32_e32 v1, 16, v48
	v_mul_f32_e32 v4, v101, v97
	v_and_b32_e32 v2, 0xffff0000, v48
	v_fmac_f32_e32 v4, v102, v1
	v_fmac_f32_e32 v4, v100, v2
	v_fmac_f32_e32 v5, v95, v3
	v_lshlrev_b32_e32 v8, 16, v49
	v_add_f32_e32 v95, v98, v4
	v_mul_f32_e32 v4, v102, v2
	v_fmac_f32_e32 v4, v101, v1
	v_mul_f32_e32 v1, v102, v8
	v_mov_b32_e32 v52, v180
	v_fmac_f32_e32 v1, v101, v2
	s_waitcnt lgkmcnt(0)
	s_barrier
	v_and_b32_e32 v3, 0xffff0000, v49
	v_ashrrev_i32_e32 v2, 31, v52
	v_add_u32_sdwa v2, v52, v2 dst_sel:DWORD dst_unused:UNUSED_PAD src0_sel:DWORD src1_sel:BYTE_3
	v_fmac_f32_e32 v1, v100, v3
	v_ashrrev_i32_e32 v2, 8, v2
	v_add_f32_e32 v90, v93, v5
	v_add_f32_e32 v93, v98, v1
	v_mul_f32_e32 v1, v102, v3
	v_mul_i32_i24_e32 v3, 0x100, v2
	v_sub_u32_e32 v3, v52, v3
	v_mul_i32_i24_e32 v48, 0x220, v2
	v_ashrrev_i32_e32 v2, 4, v3
	v_add_u32_e32 v49, 0x100, v3
	v_fmac_f32_e32 v4, v100, v8
	v_add_u32_e32 v2, v2, v3
	v_lshrrev_b32_e32 v50, 4, v49
	v_add_f32_e32 v97, v98, v4
	v_add_lshl_u32 v53, v2, v48, 3
	v_add3_u32 v4, v48, v3, v50
	v_add_u32_e32 v2, 0, v53
	v_lshl_add_u32 v4, v4, 3, 0
	v_lshl_add_u32 v6, v3, 3, 0
	ds_read_b64 v[2:3], v2 offset:6272
	ds_read_b64 v[4:5], v4 offset:8320
	ds_read_b64 v[6:7], v6 offset:4224
	v_fmac_f32_e32 v1, v101, v8
	v_fmac_f32_e32 v1, v100, v99
	v_add_f32_e32 v99, v98, v1
	v_add3_u32 v1, v48, v49, v50
	s_waitcnt lgkmcnt(0)
	v_pk_mul_f32 v[48:49], v[4:5], v[6:7] op_sel:[1,1] op_sel_hi:[1,0]
	v_lshl_add_u32 v1, v1, 3, s18
	v_pk_fma_f32 v[50:51], v[4:5], v[6:7], v[48:49] op_sel_hi:[0,1,1] neg_lo:[0,0,1]
	v_pk_add_f32 v[4:5], v[2:3], v[50:51]
	v_add_u32_e32 v6, s18, v53
	v_pk_add_f32 v[2:3], v[2:3], v[50:51] neg_lo:[0,1] neg_hi:[0,1]
	ds_write_b64 v6, v[4:5]
	ds_write_b64 v1, v[2:3]
	v_add_u32_e32 v1, 0x200, v52
	v_ashrrev_i32_e32 v2, 31, v1
	v_add_u32_sdwa v2, v1, v2 dst_sel:DWORD dst_unused:UNUSED_PAD src0_sel:DWORD src1_sel:BYTE_3
	v_ashrrev_i32_e32 v2, 8, v2
	v_mul_i32_i24_e32 v3, 0x100, v2
	v_sub_u32_e32 v1, v1, v3
	v_mul_i32_i24_e32 v8, 0x220, v2
	v_ashrrev_i32_e32 v2, 4, v1
	v_add_u32_e32 v48, 0x100, v1
	v_add_u32_e32 v2, v2, v1
	v_lshrrev_b32_e32 v49, 4, v48
	v_add_lshl_u32 v53, v2, v8, 3
	v_add3_u32 v3, v8, v1, v49
	v_add_u32_e32 v2, 0, v53
	v_lshl_add_u32 v4, v3, 3, 0
	v_lshl_add_u32 v1, v1, 3, 0
	ds_read_b64 v[2:3], v2 offset:6272
	ds_read_b64 v[4:5], v4 offset:8320
	ds_read_b64 v[6:7], v1 offset:4224
	v_add3_u32 v8, v8, v48, v49
	v_lshlrev_b32_e32 v1, 16, v46
	v_and_b32_e32 v54, 0xffff0000, v46
	v_lshlrev_b32_e32 v55, 16, v47
	s_waitcnt lgkmcnt(0)
	v_pk_mul_f32 v[48:49], v[4:5], v[6:7] op_sel:[1,1] op_sel_hi:[1,0]
	v_add_u32_e32 v0, 0x100, v18
	v_pk_fma_f32 v[50:51], v[4:5], v[6:7], v[48:49] op_sel_hi:[0,1,1] neg_lo:[0,0,1]
	v_pk_add_f32 v[4:5], v[2:3], v[50:51]
	v_add_u32_e32 v6, s18, v53
	ds_write_b64 v6, v[4:5]
	v_pk_add_f32 v[2:3], v[2:3], v[50:51] neg_lo:[0,1] neg_hi:[0,1]
	v_lshl_add_u32 v4, v8, 3, s18
	ds_write_b64 v4, v[2:3]
	v_add_u32_e32 v2, 0x400, v52
	v_ashrrev_i32_e32 v3, 31, v2
	v_add_u32_sdwa v3, v2, v3 dst_sel:DWORD dst_unused:UNUSED_PAD src0_sel:DWORD src1_sel:BYTE_3
	v_ashrrev_i32_e32 v3, 8, v3
	v_mul_i32_i24_e32 v4, 0x100, v3
	v_sub_u32_e32 v2, v2, v4
	v_mul_i32_i24_e32 v8, 0x220, v3
	v_ashrrev_i32_e32 v3, 4, v2
	v_add_u32_e32 v46, 0x100, v2
	v_add_u32_e32 v3, v3, v2
	v_lshrrev_b32_e32 v48, 4, v46
	v_add_lshl_u32 v50, v3, v8, 3
	v_add3_u32 v4, v8, v2, v48
	v_add_u32_e32 v3, 0, v50
	v_lshl_add_u32 v4, v4, 3, 0
	v_lshl_add_u32 v6, v2, 3, 0
	ds_read_b64 v[2:3], v3 offset:6272
	ds_read_b64 v[4:5], v4 offset:8320
	ds_read_b64 v[6:7], v6 offset:4224
	v_and_b32_e32 v51, 0xffff0000, v47
	v_add3_u32 v8, v8, v46, v48
	v_mul_f32_e32 v53, v101, v92
	v_fmac_f32_e32 v53, v102, v1
	s_waitcnt lgkmcnt(0)
	v_pk_mul_f32 v[46:47], v[4:5], v[6:7] op_sel:[1,1] op_sel_hi:[1,0]
	v_fmac_f32_e32 v53, v100, v54
	v_pk_fma_f32 v[48:49], v[4:5], v[6:7], v[46:47] op_sel_hi:[0,1,1] neg_lo:[0,0,1]
	v_pk_add_f32 v[4:5], v[2:3], v[48:49]
	v_add_u32_e32 v6, s18, v50
	ds_write_b64 v6, v[4:5]
	v_pk_add_f32 v[2:3], v[2:3], v[48:49] neg_lo:[0,1] neg_hi:[0,1]
	v_lshl_add_u32 v4, v8, 3, s18
	ds_write_b64 v4, v[2:3]
	v_add_u32_e32 v2, 0x600, v52
	v_ashrrev_i32_e32 v3, 31, v2
	v_add_u32_sdwa v3, v2, v3 dst_sel:DWORD dst_unused:UNUSED_PAD src0_sel:DWORD src1_sel:BYTE_3
	v_ashrrev_i32_e32 v3, 8, v3
	v_mul_i32_i24_e32 v4, 0x100, v3
	v_sub_u32_e32 v2, v2, v4
	v_mul_i32_i24_e32 v8, 0x220, v3
	v_ashrrev_i32_e32 v3, 4, v2
	v_add_u32_e32 v46, 0x100, v2
	v_add_u32_e32 v3, v3, v2
	v_lshrrev_b32_e32 v47, 4, v46
	v_add_lshl_u32 v50, v3, v8, 3
	v_add3_u32 v4, v8, v2, v47
	v_add_u32_e32 v3, 0, v50
	v_lshl_add_u32 v4, v4, 3, 0
	v_lshl_add_u32 v6, v2, 3, 0
	ds_read_b64 v[2:3], v3 offset:6272
	ds_read_b64 v[4:5], v4 offset:8320
	ds_read_b64 v[6:7], v6 offset:4224
	v_add3_u32 v8, v8, v46, v47
	v_add_f32_e32 v94, v98, v53
	v_mul_f32_e32 v53, v102, v54
	v_fmac_f32_e32 v53, v101, v1
	s_waitcnt lgkmcnt(0)
	v_pk_mul_f32 v[46:47], v[4:5], v[6:7] op_sel:[1,1] op_sel_hi:[1,0]
	v_fmac_f32_e32 v53, v100, v55
	v_pk_fma_f32 v[48:49], v[4:5], v[6:7], v[46:47] op_sel_hi:[0,1,1] neg_lo:[0,0,1]
	v_pk_add_f32 v[4:5], v[2:3], v[48:49]
	v_add_u32_e32 v6, s18, v50
	ds_write_b64 v6, v[4:5]
	v_pk_add_f32 v[2:3], v[2:3], v[48:49] neg_lo:[0,1] neg_hi:[0,1]
	v_lshl_add_u32 v4, v8, 3, s18
	ds_write_b64 v4, v[2:3]
	v_add_u32_e32 v2, 0x800, v52
	v_ashrrev_i32_e32 v3, 31, v2
	v_add_u32_sdwa v3, v2, v3 dst_sel:DWORD dst_unused:UNUSED_PAD src0_sel:DWORD src1_sel:BYTE_3
	v_ashrrev_i32_e32 v3, 8, v3
	v_mul_i32_i24_e32 v4, 0x100, v3
	v_sub_u32_e32 v2, v2, v4
	v_mul_i32_i24_e32 v8, 0x220, v3
	v_ashrrev_i32_e32 v3, 4, v2
	v_add_u32_e32 v46, 0x100, v2
	v_add_u32_e32 v3, v3, v2
	v_lshrrev_b32_e32 v47, 4, v46
	v_add_lshl_u32 v50, v3, v8, 3
	v_add3_u32 v4, v8, v2, v47
	v_add_u32_e32 v3, 0, v50
	v_lshl_add_u32 v4, v4, 3, 0
	v_lshl_add_u32 v6, v2, 3, 0
	ds_read_b64 v[2:3], v3 offset:6272
	ds_read_b64 v[4:5], v4 offset:8320
	ds_read_b64 v[6:7], v6 offset:4224
	v_add3_u32 v1, v8, v46, v47
	v_lshl_add_u32 v1, v1, 3, s18
	v_add_f32_e32 v96, v98, v53
	v_mul_lo_u32 v196, v132, s17
	s_waitcnt lgkmcnt(0)
	v_pk_mul_f32 v[46:47], v[4:5], v[6:7] op_sel:[1,1] op_sel_hi:[1,0]
	v_lshrrev_b32_e32 v0, 1, v0
	v_pk_fma_f32 v[48:49], v[4:5], v[6:7], v[46:47] op_sel_hi:[0,1,1] neg_lo:[0,0,1]
	v_pk_add_f32 v[4:5], v[2:3], v[48:49]
	v_add_u32_e32 v6, s18, v50
	v_pk_add_f32 v[2:3], v[2:3], v[48:49] neg_lo:[0,1] neg_hi:[0,1]
	ds_write_b64 v6, v[4:5]
	ds_write_b64 v1, v[2:3]
	v_add_u32_e32 v1, 0xa00, v52
	v_ashrrev_i32_e32 v2, 31, v1
	v_add_u32_sdwa v2, v1, v2 dst_sel:DWORD dst_unused:UNUSED_PAD src0_sel:DWORD src1_sel:BYTE_3
	v_ashrrev_i32_e32 v2, 8, v2
	v_mul_i32_i24_e32 v3, 0x100, v2
	v_sub_u32_e32 v1, v1, v3
	v_mul_i32_i24_e32 v8, 0x220, v2
	v_ashrrev_i32_e32 v2, 4, v1
	v_add_u32_e32 v46, 0x100, v1
	v_add_u32_e32 v2, v2, v1
	v_lshrrev_b32_e32 v47, 4, v46
	v_add_lshl_u32 v50, v2, v8, 3
	v_add3_u32 v3, v8, v1, v47
	v_add_u32_e32 v2, 0, v50
	v_lshl_add_u32 v4, v3, 3, 0
	v_lshl_add_u32 v1, v1, 3, 0
	ds_read_b64 v[2:3], v2 offset:6272
	ds_read_b64 v[4:5], v4 offset:8320
	ds_read_b64 v[6:7], v1 offset:4224
	v_add3_u32 v8, v8, v46, v47
	v_mul_f32_e32 v1, v102, v55
	v_fmac_f32_e32 v1, v101, v54
	v_fmac_f32_e32 v1, v100, v51
	s_waitcnt lgkmcnt(0)
	v_pk_mul_f32 v[46:47], v[4:5], v[6:7] op_sel:[1,1] op_sel_hi:[1,0]
	v_add_f32_e32 v92, v98, v1
	v_pk_fma_f32 v[48:49], v[4:5], v[6:7], v[46:47] op_sel_hi:[0,1,1] neg_lo:[0,0,1]
	v_pk_add_f32 v[4:5], v[2:3], v[48:49]
	v_add_u32_e32 v6, s18, v50
	ds_write_b64 v6, v[4:5]
	v_pk_add_f32 v[2:3], v[2:3], v[48:49] neg_lo:[0,1] neg_hi:[0,1]
	v_lshl_add_u32 v4, v8, 3, s18
	ds_write_b64 v4, v[2:3]
	v_add_u32_e32 v2, 0xc00, v52
	v_ashrrev_i32_e32 v3, 31, v2
	v_add_u32_sdwa v3, v2, v3 dst_sel:DWORD dst_unused:UNUSED_PAD src0_sel:DWORD src1_sel:BYTE_3
	v_ashrrev_i32_e32 v3, 8, v3
	v_mul_i32_i24_e32 v4, 0x100, v3
	v_sub_u32_e32 v2, v2, v4
	v_mul_i32_i24_e32 v8, 0x220, v3
	v_ashrrev_i32_e32 v3, 4, v2
	v_add_u32_e32 v46, 0x100, v2
	v_add_u32_e32 v3, v3, v2
	v_lshrrev_b32_e32 v47, 4, v46
	v_add_lshl_u32 v50, v3, v8, 3
	v_add3_u32 v4, v8, v2, v47
	v_add_u32_e32 v3, 0, v50
	v_lshl_add_u32 v4, v4, 3, 0
	v_lshl_add_u32 v6, v2, 3, 0
	ds_read_b64 v[2:3], v3 offset:6272
	ds_read_b64 v[4:5], v4 offset:8320
	ds_read_b64 v[6:7], v6 offset:4224
	v_add3_u32 v8, v8, v46, v47
	v_mul_f32_e32 v1, v102, v51
	v_fmac_f32_e32 v1, v101, v55
	v_fmac_f32_e32 v1, v100, v103
	s_waitcnt lgkmcnt(0)
	v_pk_mul_f32 v[46:47], v[4:5], v[6:7] op_sel:[1,1] op_sel_hi:[1,0]
	v_add_f32_e32 v98, v98, v1
	v_pk_fma_f32 v[48:49], v[4:5], v[6:7], v[46:47] op_sel_hi:[0,1,1] neg_lo:[0,0,1]
	v_pk_add_f32 v[4:5], v[2:3], v[48:49]
	v_add_u32_e32 v6, s18, v50
	ds_write_b64 v6, v[4:5]
	v_pk_add_f32 v[2:3], v[2:3], v[48:49] neg_lo:[0,1] neg_hi:[0,1]
	v_lshl_add_u32 v4, v8, 3, s18
	ds_write_b64 v4, v[2:3]
	v_add_u32_e32 v2, 0xe00, v52
	v_ashrrev_i32_e32 v3, 31, v2
	v_add_u32_sdwa v3, v2, v3 dst_sel:DWORD dst_unused:UNUSED_PAD src0_sel:DWORD src1_sel:BYTE_3
	v_ashrrev_i32_e32 v3, 8, v3
	v_mul_i32_i24_e32 v4, 0x100, v3
	v_sub_u32_e32 v2, v2, v4
	v_mul_i32_i24_e32 v8, 0x220, v3
	v_ashrrev_i32_e32 v3, 4, v2
	v_add_u32_e32 v46, 0x100, v2
	v_add_u32_e32 v3, v3, v2
	v_lshrrev_b32_e32 v47, 4, v46
	v_add_lshl_u32 v50, v3, v8, 3
	v_add3_u32 v4, v8, v2, v47
	v_add_u32_e32 v3, 0, v50
	v_lshl_add_u32 v4, v4, 3, 0
	v_lshl_add_u32 v6, v2, 3, 0
	ds_read_b64 v[2:3], v3 offset:6272
	ds_read_b64 v[4:5], v4 offset:8320
	ds_read_b64 v[6:7], v6 offset:4224
	v_add3_u32 v8, v8, v46, v47
	v_mov_b32_e32 v1, s18
	v_and_b32_e32 v0, 0x7ffffff8, v0
	s_waitcnt lgkmcnt(0)
	v_pk_mul_f32 v[46:47], v[4:5], v[6:7] op_sel:[1,1] op_sel_hi:[1,0]
	s_nop 0
	v_pk_fma_f32 v[48:49], v[4:5], v[6:7], v[46:47] op_sel_hi:[0,1,1] neg_lo:[0,0,1]
	v_pk_add_f32 v[4:5], v[2:3], v[48:49]
	v_add_u32_e32 v6, s18, v50
	ds_write_b64 v6, v[4:5]
	v_pk_add_f32 v[2:3], v[2:3], v[48:49] neg_lo:[0,1] neg_hi:[0,1]
	v_lshl_add_u32 v4, v8, 3, s18
	ds_write_b64 v4, v[2:3]
	v_lshrrev_b32_e32 v2, 27, v45
	v_add_u32_e32 v2, v44, v2
	v_and_b32_e32 v2, 0xffffffe0, v2
	v_lshrrev_b32_e32 v3, 5, v44
	v_sub_u32_e32 v2, v44, v2
	v_and_b32_e32 v3, 0xfffff8, v3
	v_mad_u32_u24 v1, v3, s17, v1
	v_ashrrev_i32_e32 v3, 4, v2
	v_add_u32_e32 v4, 32, v2
	v_add_u32_e32 v3, v3, v2
	v_lshrrev_b32_e32 v4, 4, v4
	v_lshl_add_u32 v3, v3, 3, v1
	v_add_u32_e32 v4, v4, v2
	s_waitcnt lgkmcnt(0)
	s_barrier
	v_lshl_add_u32 v4, v4, 3, v1
	ds_read_b64 v[100:101], v3
	ds_read_b64 v[44:45], v3 offset:4352
	ds_read_b64 v[102:103], v4 offset:256
	ds_read_b64 v[46:47], v4 offset:4608
	v_add_u32_e32 v3, 64, v2
	v_lshrrev_b32_e32 v3, 4, v3
	v_add_u32_e32 v4, 0x60, v2
	v_add_u32_e32 v3, v3, v2
	v_lshrrev_b32_e32 v4, 4, v4
	v_lshl_add_u32 v3, v3, 3, v1
	v_add_u32_e32 v4, v4, v2
	v_lshl_add_u32 v4, v4, 3, v1
	ds_read_b64 v[104:105], v3 offset:512
	ds_read_b64 v[48:49], v3 offset:4864
	ds_read_b64 v[106:107], v4 offset:768
	ds_read_b64 v[50:51], v4 offset:5120
	v_add_u32_e32 v3, 0x80, v2
	v_lshrrev_b32_e32 v3, 4, v3
	v_add_u32_e32 v4, 0xa0, v2
	v_add_u32_e32 v3, v3, v2
	v_lshrrev_b32_e32 v4, 4, v4
	v_lshl_add_u32 v3, v3, 3, v1
	v_add_u32_e32 v4, v4, v2
	v_lshl_add_u32 v4, v4, 3, v1
	ds_read_b64 v[108:109], v3 offset:1024
	ds_read_b64 v[52:53], v3 offset:5376
	ds_read_b64 v[110:111], v4 offset:1280
	ds_read_b64 v[54:55], v4 offset:5632
	v_add_u32_e32 v3, 0xc0, v2
	v_lshrrev_b32_e32 v3, 4, v3
	v_add_u32_e32 v4, 0xe0, v2
	v_add_u32_e32 v3, v3, v2
	v_lshrrev_b32_e32 v4, 4, v4
	v_lshl_add_u32 v3, v3, 3, v1
	v_add_u32_e32 v4, v4, v2
	v_lshl_add_u32 v4, v4, 3, v1
	ds_read_b64 v[112:113], v3 offset:1536
	ds_read_b64 v[56:57], v3 offset:5888
	ds_read_b64 v[114:115], v4 offset:1792
	ds_read_b64 v[58:59], v4 offset:6144
	v_add_u32_e32 v3, 0x100, v2
	v_lshrrev_b32_e32 v3, 4, v3
	v_add_u32_e32 v4, 0x120, v2
	v_add_u32_e32 v3, v3, v2
	v_lshrrev_b32_e32 v4, 4, v4
	v_lshl_add_u32 v3, v3, 3, v1
	v_add_u32_e32 v4, v4, v2
	v_lshl_add_u32 v4, v4, 3, v1
	ds_read_b64 v[116:117], v3 offset:2048
	ds_read_b64 v[60:61], v3 offset:6400
	ds_read_b64 v[118:119], v4 offset:2304
	ds_read_b64 v[62:63], v4 offset:6656
	v_add_u32_e32 v3, 0x140, v2
	v_lshrrev_b32_e32 v3, 4, v3
	v_add_u32_e32 v4, 0x160, v2
	v_add_u32_e32 v3, v3, v2
	v_lshrrev_b32_e32 v4, 4, v4
	v_lshl_add_u32 v3, v3, 3, v1
	v_add_u32_e32 v4, v4, v2
	v_lshl_add_u32 v4, v4, 3, v1
	ds_read_b64 v[120:121], v3 offset:2560
	ds_read_b64 v[64:65], v3 offset:6912
	ds_read_b64 v[122:123], v4 offset:2816
	ds_read_b64 v[66:67], v4 offset:7168
	v_add_u32_e32 v3, 0x180, v2
	v_lshrrev_b32_e32 v3, 4, v3
	v_add_u32_e32 v4, 0x1a0, v2
	v_add_u32_e32 v3, v3, v2
	v_lshrrev_b32_e32 v4, 4, v4
	v_lshl_add_u32 v3, v3, 3, v1
	v_add_u32_e32 v4, v4, v2
	v_lshl_add_u32 v4, v4, 3, v1
	ds_read_b64 v[124:125], v3 offset:3072
	ds_read_b64 v[70:71], v3 offset:7424
	ds_read_b64 v[126:127], v4 offset:3328
	ds_read_b64 v[72:73], v4 offset:7680
	v_add_u32_e32 v3, 0x1c0, v2
	v_lshrrev_b32_e32 v3, 4, v3
	v_add_u32_e32 v4, 0x1e0, v2
	v_add_u32_e32 v3, v3, v2
	v_lshrrev_b32_e32 v4, 4, v4
	v_lshl_add_u32 v3, v3, 3, v1
	v_add_u32_e32 v2, v4, v2
	v_lshl_add_u32 v1, v2, 3, v1
	ds_read_b64 v[128:129], v3 offset:3584
	ds_read_b64 v[74:75], v3 offset:7936
	ds_read_b64 v[130:131], v1 offset:3840
	ds_read_b64 v[76:77], v1 offset:8192
	v_add_u32_e32 v1, 0, v196
	v_lshlrev_b32_e32 v2, 3, v18
	v_lshl_add_u32 v8, v197, 3, v1
	v_add3_u32 v195, v1, v2, v0
	v_mov_b32_e32 v0, v180
	s_waitcnt lgkmcnt(0)
	s_barrier
	ds_write_b64 v8, v[94:95] offset:6272
	ds_write_b64 v195, v[202:203] offset:8320
	ds_write_b64 v8, v[96:97] offset:6280
	ds_write_b64 v195, v[202:203] offset:8328
	ds_write_b64 v8, v[92:93] offset:6288
	ds_write_b64 v195, v[202:203] offset:8336
	ds_write_b64 v8, v[98:99] offset:6296
	ds_write_b64 v195, v[202:203] offset:8344
	ds_write_b64 v8, v[88:89] offset:41088
	ds_write_b64 v195, v[202:203] offset:43136
	ds_write_b64 v8, v[90:91] offset:41096
	ds_write_b64 v195, v[202:203] offset:43144
	ds_write_b64 v8, v[84:85] offset:41104
	ds_write_b64 v195, v[202:203] offset:43152
	ds_write_b64 v8, v[86:87] offset:41112
	ds_write_b64 v195, v[202:203] offset:43160
	s_waitcnt lgkmcnt(0)
	s_barrier
	s_nop 0
	v_cmp_gt_i32_e32 vcc, s16, v0
	s_and_saveexec_b64 s[2:3], vcc
	s_cbranch_execz .LBB0_491
	v_ashrrev_i32_e32 v1, 31, v0
	v_lshrrev_b32_e32 v1, 27, v1
	v_add_u32_e32 v1, v0, v1
	v_lshrrev_b32_e32 v2, 5, v1
	v_and_b32_e32 v1, 0xffffffe0, v1
	v_sub_u32_e32 v181, v0, v1
	v_mul_lo_u32 v206, v2, s17
	v_ashrrev_i32_e32 v1, 4, v181
	v_add_u32_e32 v0, 0, v206
	v_lshlrev_b32_e32 v207, 3, v181
	v_lshlrev_b32_e32 v1, 3, v1
	v_add3_u32 v152, v0, v207, v1
	v_add_u32_e32 v136, 0x1800, v152
	v_add_u32_e32 v148, 0x2000, v152
	ds_read2_b64 v[0:3], v136 offset0:16 offset1:50
	ds_read2_b64 v[4:7], v136 offset0:84 offset1:118
	ds_read2_b64 v[132:135], v136 offset0:152 offset1:186
	ds_read2_b64 v[136:139], v136 offset0:220 offset1:254
	ds_read2_b64 v[140:143], v148 offset0:32 offset1:66
	ds_read2_b64 v[144:147], v148 offset0:100 offset1:134
	ds_read2_b64 v[148:151], v148 offset0:168 offset1:202
	v_add_u32_e32 v152, 0x2400, v152
	ds_read2_b64 v[152:155], v152 offset0:108 offset1:142
	s_waitcnt lgkmcnt(3)
	v_pk_add_f32 v[156:157], v[0:1], v[140:141]
	v_pk_add_f32 v[0:1], v[0:1], v[140:141] neg_lo:[0,1] neg_hi:[0,1]
	s_waitcnt lgkmcnt(1)
	v_pk_add_f32 v[140:141], v[132:133], v[148:149]
	v_pk_add_f32 v[132:133], v[132:133], v[148:149] neg_lo:[0,1] neg_hi:[0,1]
	s_mov_b32 s31, s28
	v_pk_add_f32 v[198:199], v[0:1], v[132:133] op_sel:[0,1] op_sel_hi:[1,0] neg_hi:[0,1]
	v_pk_add_f32 v[0:1], v[0:1], v[132:133] op_sel:[0,1] op_sel_hi:[1,0] neg_lo:[0,1]
	v_pk_add_f32 v[148:149], v[2:3], v[142:143]
	v_pk_add_f32 v[2:3], v[2:3], v[142:143] neg_lo:[0,1] neg_hi:[0,1]
	v_pk_add_f32 v[142:143], v[134:135], v[150:151]
	v_pk_add_f32 v[134:135], v[134:135], v[150:151] neg_lo:[0,1] neg_hi:[0,1]
	v_pk_add_f32 v[132:133], v[156:157], v[140:141]
	v_xor_b32_e32 v151, 0x80000000, v134
	v_mov_b32_e32 v150, v135
	v_pk_add_f32 v[134:135], v[148:149], v[142:143]
	v_pk_add_f32 v[142:143], v[148:149], v[142:143] neg_lo:[0,1] neg_hi:[0,1]
	v_pk_add_f32 v[148:149], v[4:5], v[144:145]
	v_pk_add_f32 v[4:5], v[4:5], v[144:145] neg_lo:[0,1] neg_hi:[0,1]
	s_waitcnt lgkmcnt(0)
	v_pk_add_f32 v[144:145], v[136:137], v[152:153]
	v_pk_add_f32 v[136:137], v[136:137], v[152:153] neg_lo:[0,1] neg_hi:[0,1]
	v_pk_add_f32 v[140:141], v[156:157], v[140:141] neg_lo:[0,1] neg_hi:[0,1]
	v_pk_add_f32 v[156:157], v[2:3], v[150:151]
	v_pk_add_f32 v[2:3], v[2:3], v[150:151] neg_lo:[0,1] neg_hi:[0,1]
	v_xor_b32_e32 v151, 0x80000000, v136
	v_mov_b32_e32 v150, v137
	v_pk_add_f32 v[136:137], v[148:149], v[144:145]
	v_pk_add_f32 v[144:145], v[148:149], v[144:145] neg_lo:[0,1] neg_hi:[0,1]
	v_pk_add_f32 v[148:149], v[6:7], v[146:147]
	v_pk_add_f32 v[6:7], v[6:7], v[146:147] neg_lo:[0,1] neg_hi:[0,1]
	v_pk_add_f32 v[146:147], v[138:139], v[154:155]
	v_pk_add_f32 v[138:139], v[138:139], v[154:155] neg_lo:[0,1] neg_hi:[0,1]
	v_pk_add_f32 v[152:153], v[4:5], v[150:151]
	v_pk_add_f32 v[4:5], v[4:5], v[150:151] neg_lo:[0,1] neg_hi:[0,1]
	v_xor_b32_e32 v151, 0x80000000, v138
	v_mov_b32_e32 v150, v139
	v_pk_add_f32 v[138:139], v[148:149], v[146:147]
	v_pk_add_f32 v[146:147], v[148:149], v[146:147] neg_lo:[0,1] neg_hi:[0,1]
	v_pk_mul_f32 v[148:149], v[156:157], s[14:15] op_sel_hi:[1,0]
	v_pk_add_f32 v[154:155], v[6:7], v[150:151]
	v_pk_add_f32 v[6:7], v[6:7], v[150:151] neg_lo:[0,1] neg_hi:[0,1]
	v_pk_fma_f32 v[150:151], v[156:157], s[22:23], v[148:149] op_sel:[0,0,1] op_sel_hi:[1,0,0] neg_hi:[0,0,1]
	s_mov_b32 s29, s14
	v_pk_mul_f32 v[148:149], v[142:143], s[24:25] op_sel_hi:[1,0]
	s_nop 0
	v_pk_fma_f32 v[156:157], v[142:143], s[24:25], v[148:149] op_sel:[0,0,1] op_sel_hi:[1,0,0] neg_hi:[0,0,1]
	v_pk_mul_f32 v[148:149], v[2:3], s[22:23] op_sel_hi:[1,0]
	v_pk_fma_f32 v[200:201], v[2:3], s[14:15], v[148:149] op_sel:[0,0,1] op_sel_hi:[1,0,0] neg_hi:[0,0,1]
	s_nop 0
	v_pk_mul_f32 v[2:3], v[152:153], s[24:25] op_sel_hi:[1,0]
	s_nop 0
	v_pk_fma_f32 v[148:149], v[152:153], s[24:25], v[2:3] op_sel:[0,0,1] op_sel_hi:[1,0,0] neg_hi:[0,0,1]
	s_nop 0
	v_pk_fma_f32 v[2:3], v[144:145], 0, v[144:145] op_sel:[0,0,1] op_sel_hi:[1,0,0] neg_hi:[0,0,1]
	s_nop 0
	v_pk_mul_f32 v[144:145], v[4:5], s[26:27] op_sel_hi:[1,0]
	s_nop 0
	v_pk_fma_f32 v[152:153], v[4:5], s[26:27], v[144:145] op_sel:[0,0,1] op_sel_hi:[1,0,0] neg_lo:[0,0,1]
	v_pk_mul_f32 v[144:145], v[154:155], s[22:23] op_sel_hi:[1,0]
	v_pk_fma_f32 v[204:205], v[154:155], s[14:15], v[144:145] op_sel:[0,0,1] op_sel_hi:[1,0,0] neg_hi:[0,0,1]
	v_pk_add_f32 v[4:5], v[0:1], v[152:153]
	v_pk_mul_f32 v[144:145], v[146:147], s[26:27] op_sel_hi:[1,0]
	v_pk_add_f32 v[0:1], v[0:1], v[152:153] neg_lo:[0,1] neg_hi:[0,1]
	v_pk_fma_f32 v[154:155], v[146:147], s[26:27], v[144:145] op_sel:[0,0,1] op_sel_hi:[1,0,0] neg_lo:[0,0,1]
	s_nop 0
	v_pk_mul_f32 v[144:145], v[6:7], s[30:31] op_sel:[1,0]
	v_pk_add_f32 v[142:143], v[156:157], v[154:155] neg_lo:[0,1] neg_hi:[0,1]
	v_pk_fma_f32 v[6:7], v[6:7], s[28:29], v[144:145] op_sel_hi:[0,1,1]
	v_pk_add_f32 v[144:145], v[132:133], v[136:137]
	v_pk_add_f32 v[132:133], v[132:133], v[136:137] neg_lo:[0,1] neg_hi:[0,1]
	v_pk_add_f32 v[136:137], v[134:135], v[138:139]
	v_pk_add_f32 v[134:135], v[134:135], v[138:139] neg_lo:[0,1] neg_hi:[0,1]
	s_nop 0
	v_xor_b32_e32 v139, 0x80000000, v134
	v_mov_b32_e32 v138, v135
	v_pk_add_f32 v[134:135], v[144:145], v[136:137]
	v_pk_add_f32 v[146:147], v[132:133], v[138:139]
	v_pk_add_f32 v[136:137], v[144:145], v[136:137] neg_lo:[0,1] neg_hi:[0,1]
	v_pk_add_f32 v[132:133], v[132:133], v[138:139] neg_lo:[0,1] neg_hi:[0,1]
	v_pk_add_f32 v[138:139], v[198:199], v[148:149]
	v_pk_add_f32 v[144:145], v[198:199], v[148:149] neg_lo:[0,1] neg_hi:[0,1]
	v_pk_add_f32 v[148:149], v[150:151], v[204:205]
	v_pk_add_f32 v[150:151], v[150:151], v[204:205] neg_lo:[0,1] neg_hi:[0,1]
	s_nop 0
	v_xor_b32_e32 v199, 0x80000000, v150
	v_mov_b32_e32 v198, v151
	v_pk_add_f32 v[150:151], v[138:139], v[148:149]
	v_pk_add_f32 v[138:139], v[138:139], v[148:149] neg_lo:[0,1] neg_hi:[0,1]
	v_pk_add_f32 v[148:149], v[140:141], v[2:3]
	v_pk_add_f32 v[2:3], v[140:141], v[2:3] neg_lo:[0,1] neg_hi:[0,1]
	v_pk_add_f32 v[140:141], v[156:157], v[154:155]
	v_xor_b32_e32 v155, 0x80000000, v142
	v_mov_b32_e32 v154, v143
	v_pk_add_f32 v[142:143], v[148:149], v[140:141]
	v_pk_add_f32 v[140:141], v[148:149], v[140:141] neg_lo:[0,1] neg_hi:[0,1]
	v_pk_add_f32 v[148:149], v[200:201], v[6:7]
	v_pk_add_f32 v[6:7], v[200:201], v[6:7] neg_lo:[0,1] neg_hi:[0,1]
	v_pk_add_f32 v[204:205], v[144:145], v[198:199]
	v_xor_b32_e32 v153, 0x80000000, v6
	v_mov_b32_e32 v152, v7
	v_pk_add_f32 v[6:7], v[4:5], v[148:149]
	v_pk_add_f32 v[4:5], v[4:5], v[148:149] neg_lo:[0,1] neg_hi:[0,1]
	v_add_u32_e32 v148, s18, v206
	v_lshlrev_b32_e32 v149, 7, v181
	v_add3_u32 v148, v148, v149, v207
	v_pk_add_f32 v[144:145], v[144:145], v[198:199] neg_lo:[0,1] neg_hi:[0,1]
	v_pk_add_f32 v[156:157], v[2:3], v[154:155]
	v_pk_add_f32 v[2:3], v[2:3], v[154:155] neg_lo:[0,1] neg_hi:[0,1]
	v_pk_add_f32 v[154:155], v[0:1], v[152:153]
	v_pk_add_f32 v[0:1], v[0:1], v[152:153] neg_lo:[0,1] neg_hi:[0,1]
	ds_write2_b64 v148, v[134:135], v[150:151] offset1:1
	ds_write2_b64 v148, v[142:143], v[6:7] offset0:2 offset1:3
	ds_write2_b64 v148, v[146:147], v[204:205] offset0:4 offset1:5
	ds_write2_b64 v148, v[156:157], v[154:155] offset0:6 offset1:7
	ds_write2_b64 v148, v[136:137], v[138:139] offset0:8 offset1:9
	ds_write2_b64 v148, v[140:141], v[4:5] offset0:10 offset1:11
	ds_write2_b64 v148, v[132:133], v[144:145] offset0:12 offset1:13
	ds_write2_b64 v148, v[2:3], v[0:1] offset0:14 offset1:15

.LBB0_493:
	s_or_b64 exec, exec, s[2:3]
	v_mov_b32_e32 v134, v180
	s_waitcnt lgkmcnt(0)
	s_barrier
	s_nop 0
	v_ashrrev_i32_e32 v0, 31, v134
	v_add_u32_sdwa v0, v134, v0 dst_sel:DWORD dst_unused:UNUSED_PAD src0_sel:DWORD src1_sel:BYTE_3
	v_ashrrev_i32_e32 v0, 8, v0
	v_mul_i32_i24_e32 v1, 0x100, v0
	v_sub_u32_e32 v1, v134, v1
	v_add_u32_e32 v7, 0x100, v1
	v_mul_i32_i24_e32 v6, 0x220, v0
	v_ashrrev_i32_e32 v0, 4, v1
	v_lshrrev_b32_e32 v132, 4, v7
	v_add_u32_e32 v4, v0, v1
	v_add3_u32 v0, v6, v1, v132
	v_lshl_add_u32 v0, v0, 3, 0
	v_lshl_add_u32 v2, v1, 3, 0
	ds_read_b64 v[0:1], v0 offset:8320
	ds_read_b64 v[2:3], v2 offset:4224
	v_add_lshl_u32 v135, v4, v6, 3
	v_add_u32_e32 v4, 0, v135
	ds_read_b64 v[4:5], v4 offset:6272
	v_add3_u32 v136, v6, v7, v132
	s_waitcnt lgkmcnt(1)
	v_pk_mul_f32 v[6:7], v[0:1], v[2:3] op_sel:[1,1] op_sel_hi:[1,0]
	s_nop 0
	v_pk_fma_f32 v[132:133], v[0:1], v[2:3], v[6:7] op_sel_hi:[0,1,1] neg_lo:[0,0,1]
	s_waitcnt lgkmcnt(0)
	v_pk_add_f32 v[0:1], v[4:5], v[132:133]
	v_add_u32_e32 v2, s18, v135
	ds_write_b64 v2, v[0:1]
	v_pk_add_f32 v[0:1], v[4:5], v[132:133] neg_lo:[0,1] neg_hi:[0,1]
	v_lshl_add_u32 v2, v136, 3, s18
	ds_write_b64 v2, v[0:1]
	v_add_u32_e32 v0, 0x200, v134
	v_ashrrev_i32_e32 v1, 31, v0
	v_add_u32_sdwa v1, v0, v1 dst_sel:DWORD dst_unused:UNUSED_PAD src0_sel:DWORD src1_sel:BYTE_3
	v_ashrrev_i32_e32 v1, 8, v1
	v_mul_i32_i24_e32 v2, 0x100, v1
	v_sub_u32_e32 v0, v0, v2
	v_add_u32_e32 v7, 0x100, v0
	v_mul_i32_i24_e32 v6, 0x220, v1
	v_ashrrev_i32_e32 v1, 4, v0
	v_lshrrev_b32_e32 v132, 4, v7
	v_add_u32_e32 v4, v1, v0
	v_add3_u32 v1, v6, v0, v132
	v_lshl_add_u32 v1, v1, 3, 0
	v_lshl_add_u32 v2, v0, 3, 0
	ds_read_b64 v[0:1], v1 offset:8320
	ds_read_b64 v[2:3], v2 offset:4224
	v_add_lshl_u32 v135, v4, v6, 3
	v_add_u32_e32 v4, 0, v135
	ds_read_b64 v[4:5], v4 offset:6272
	v_add3_u32 v136, v6, v7, v132
	s_waitcnt lgkmcnt(1)
	v_pk_mul_f32 v[6:7], v[0:1], v[2:3] op_sel:[1,1] op_sel_hi:[1,0]
	s_nop 0
	v_pk_fma_f32 v[132:133], v[0:1], v[2:3], v[6:7] op_sel_hi:[0,1,1] neg_lo:[0,0,1]
	s_waitcnt lgkmcnt(0)
	v_pk_add_f32 v[0:1], v[4:5], v[132:133]
	v_add_u32_e32 v2, s18, v135
	ds_write_b64 v2, v[0:1]
	v_pk_add_f32 v[0:1], v[4:5], v[132:133] neg_lo:[0,1] neg_hi:[0,1]
	v_lshl_add_u32 v2, v136, 3, s18
	ds_write_b64 v2, v[0:1]
	v_add_u32_e32 v0, 0x400, v134
	v_ashrrev_i32_e32 v1, 31, v0
	v_add_u32_sdwa v1, v0, v1 dst_sel:DWORD dst_unused:UNUSED_PAD src0_sel:DWORD src1_sel:BYTE_3
	v_ashrrev_i32_e32 v1, 8, v1
	v_mul_i32_i24_e32 v2, 0x100, v1
	v_sub_u32_e32 v0, v0, v2
	v_add_u32_e32 v7, 0x100, v0
	v_mul_i32_i24_e32 v6, 0x220, v1
	v_ashrrev_i32_e32 v1, 4, v0
	v_lshrrev_b32_e32 v132, 4, v7
	v_add_u32_e32 v4, v1, v0
	v_add3_u32 v1, v6, v0, v132
	v_lshl_add_u32 v1, v1, 3, 0
	v_lshl_add_u32 v2, v0, 3, 0
	ds_read_b64 v[0:1], v1 offset:8320
	ds_read_b64 v[2:3], v2 offset:4224
	v_add_lshl_u32 v135, v4, v6, 3
	v_add_u32_e32 v4, 0, v135
	ds_read_b64 v[4:5], v4 offset:6272
	v_add3_u32 v136, v6, v7, v132
	s_waitcnt lgkmcnt(1)
	v_pk_mul_f32 v[6:7], v[0:1], v[2:3] op_sel:[1,1] op_sel_hi:[1,0]
	s_nop 0
	v_pk_fma_f32 v[132:133], v[0:1], v[2:3], v[6:7] op_sel_hi:[0,1,1] neg_lo:[0,0,1]
	s_waitcnt lgkmcnt(0)
	v_pk_add_f32 v[0:1], v[4:5], v[132:133]
	v_add_u32_e32 v2, s18, v135
	ds_write_b64 v2, v[0:1]
	v_pk_add_f32 v[0:1], v[4:5], v[132:133] neg_lo:[0,1] neg_hi:[0,1]
	v_lshl_add_u32 v2, v136, 3, s18
	ds_write_b64 v2, v[0:1]
	v_add_u32_e32 v0, 0x600, v134
	v_ashrrev_i32_e32 v1, 31, v0
	v_add_u32_sdwa v1, v0, v1 dst_sel:DWORD dst_unused:UNUSED_PAD src0_sel:DWORD src1_sel:BYTE_3
	v_ashrrev_i32_e32 v1, 8, v1
	v_mul_i32_i24_e32 v2, 0x100, v1
	v_sub_u32_e32 v0, v0, v2
	v_add_u32_e32 v7, 0x100, v0
	v_mul_i32_i24_e32 v6, 0x220, v1
	v_ashrrev_i32_e32 v1, 4, v0
	v_lshrrev_b32_e32 v132, 4, v7
	v_add_u32_e32 v4, v1, v0
	v_add3_u32 v1, v6, v0, v132
	v_lshl_add_u32 v1, v1, 3, 0
	v_lshl_add_u32 v2, v0, 3, 0
	ds_read_b64 v[0:1], v1 offset:8320
	ds_read_b64 v[2:3], v2 offset:4224
	v_add_lshl_u32 v135, v4, v6, 3
	v_add_u32_e32 v4, 0, v135
	ds_read_b64 v[4:5], v4 offset:6272
	v_add3_u32 v136, v6, v7, v132
	s_waitcnt lgkmcnt(1)
	v_pk_mul_f32 v[6:7], v[0:1], v[2:3] op_sel:[1,1] op_sel_hi:[1,0]
	s_nop 0
	v_pk_fma_f32 v[132:133], v[0:1], v[2:3], v[6:7] op_sel_hi:[0,1,1] neg_lo:[0,0,1]
	s_waitcnt lgkmcnt(0)
	v_pk_add_f32 v[0:1], v[4:5], v[132:133]
	v_add_u32_e32 v2, s18, v135
	ds_write_b64 v2, v[0:1]
	v_pk_add_f32 v[0:1], v[4:5], v[132:133] neg_lo:[0,1] neg_hi:[0,1]
	v_lshl_add_u32 v2, v136, 3, s18
	ds_write_b64 v2, v[0:1]
	v_add_u32_e32 v0, 0x800, v134
	v_ashrrev_i32_e32 v1, 31, v0
	v_add_u32_sdwa v1, v0, v1 dst_sel:DWORD dst_unused:UNUSED_PAD src0_sel:DWORD src1_sel:BYTE_3
	v_ashrrev_i32_e32 v1, 8, v1
	v_mul_i32_i24_e32 v2, 0x100, v1
	v_sub_u32_e32 v0, v0, v2
	v_add_u32_e32 v7, 0x100, v0
	v_mul_i32_i24_e32 v6, 0x220, v1
	v_ashrrev_i32_e32 v1, 4, v0
	v_lshrrev_b32_e32 v132, 4, v7
	v_add_u32_e32 v4, v1, v0
	v_add3_u32 v1, v6, v0, v132
	v_lshl_add_u32 v1, v1, 3, 0
	v_lshl_add_u32 v2, v0, 3, 0
	ds_read_b64 v[0:1], v1 offset:8320
	ds_read_b64 v[2:3], v2 offset:4224
	v_add_lshl_u32 v135, v4, v6, 3
	v_add_u32_e32 v4, 0, v135
	ds_read_b64 v[4:5], v4 offset:6272
	v_add3_u32 v136, v6, v7, v132
	s_waitcnt lgkmcnt(1)
	v_pk_mul_f32 v[6:7], v[0:1], v[2:3] op_sel:[1,1] op_sel_hi:[1,0]
	s_nop 0
	v_pk_fma_f32 v[132:133], v[0:1], v[2:3], v[6:7] op_sel_hi:[0,1,1] neg_lo:[0,0,1]
	s_waitcnt lgkmcnt(0)
	v_pk_add_f32 v[0:1], v[4:5], v[132:133]
	v_add_u32_e32 v2, s18, v135
	ds_write_b64 v2, v[0:1]
	v_pk_add_f32 v[0:1], v[4:5], v[132:133] neg_lo:[0,1] neg_hi:[0,1]
	v_lshl_add_u32 v2, v136, 3, s18
	ds_write_b64 v2, v[0:1]
	v_add_u32_e32 v0, 0xa00, v134
	v_ashrrev_i32_e32 v1, 31, v0
	v_add_u32_sdwa v1, v0, v1 dst_sel:DWORD dst_unused:UNUSED_PAD src0_sel:DWORD src1_sel:BYTE_3
	v_ashrrev_i32_e32 v1, 8, v1
	v_mul_i32_i24_e32 v2, 0x100, v1
	v_sub_u32_e32 v0, v0, v2
	v_add_u32_e32 v7, 0x100, v0
	v_mul_i32_i24_e32 v6, 0x220, v1
	v_ashrrev_i32_e32 v1, 4, v0
	v_lshrrev_b32_e32 v132, 4, v7
	v_add_u32_e32 v4, v1, v0
	v_add3_u32 v1, v6, v0, v132
	v_lshl_add_u32 v1, v1, 3, 0
	v_lshl_add_u32 v2, v0, 3, 0
	ds_read_b64 v[0:1], v1 offset:8320
	ds_read_b64 v[2:3], v2 offset:4224
	v_add_lshl_u32 v135, v4, v6, 3
	v_add_u32_e32 v4, 0, v135
	ds_read_b64 v[4:5], v4 offset:6272
	v_add3_u32 v136, v6, v7, v132
	s_waitcnt lgkmcnt(1)
	v_pk_mul_f32 v[6:7], v[0:1], v[2:3] op_sel:[1,1] op_sel_hi:[1,0]
	s_nop 0
	v_pk_fma_f32 v[132:133], v[0:1], v[2:3], v[6:7] op_sel_hi:[0,1,1] neg_lo:[0,0,1]
	s_waitcnt lgkmcnt(0)
	v_pk_add_f32 v[0:1], v[4:5], v[132:133]
	v_add_u32_e32 v2, s18, v135
	ds_write_b64 v2, v[0:1]
	v_pk_add_f32 v[0:1], v[4:5], v[132:133] neg_lo:[0,1] neg_hi:[0,1]
	v_lshl_add_u32 v2, v136, 3, s18
	ds_write_b64 v2, v[0:1]
	v_add_u32_e32 v0, 0xc00, v134
	v_ashrrev_i32_e32 v1, 31, v0
	v_add_u32_sdwa v1, v0, v1 dst_sel:DWORD dst_unused:UNUSED_PAD src0_sel:DWORD src1_sel:BYTE_3
	v_ashrrev_i32_e32 v1, 8, v1
	v_mul_i32_i24_e32 v2, 0x100, v1
	v_sub_u32_e32 v0, v0, v2
	v_add_u32_e32 v7, 0x100, v0
	v_mul_i32_i24_e32 v6, 0x220, v1
	v_ashrrev_i32_e32 v1, 4, v0
	v_lshrrev_b32_e32 v132, 4, v7
	v_add_u32_e32 v4, v1, v0
	v_add3_u32 v1, v6, v0, v132
	v_lshl_add_u32 v1, v1, 3, 0
	v_lshl_add_u32 v2, v0, 3, 0
	ds_read_b64 v[0:1], v1 offset:8320
	ds_read_b64 v[2:3], v2 offset:4224
	v_add_lshl_u32 v135, v4, v6, 3
	v_add_u32_e32 v4, 0, v135
	ds_read_b64 v[4:5], v4 offset:6272
	v_add3_u32 v136, v6, v7, v132
	s_waitcnt lgkmcnt(1)
	v_pk_mul_f32 v[6:7], v[0:1], v[2:3] op_sel:[1,1] op_sel_hi:[1,0]
	s_nop 0
	v_pk_fma_f32 v[132:133], v[0:1], v[2:3], v[6:7] op_sel_hi:[0,1,1] neg_lo:[0,0,1]
	s_waitcnt lgkmcnt(0)
	v_pk_add_f32 v[0:1], v[4:5], v[132:133]
	v_add_u32_e32 v2, s18, v135
	ds_write_b64 v2, v[0:1]
	v_pk_add_f32 v[0:1], v[4:5], v[132:133] neg_lo:[0,1] neg_hi:[0,1]
	v_lshl_add_u32 v2, v136, 3, s18
	ds_write_b64 v2, v[0:1]
	v_add_u32_e32 v0, 0xe00, v134
	v_ashrrev_i32_e32 v1, 31, v0
	v_add_u32_sdwa v1, v0, v1 dst_sel:DWORD dst_unused:UNUSED_PAD src0_sel:DWORD src1_sel:BYTE_3
	v_ashrrev_i32_e32 v1, 8, v1
	v_mul_i32_i24_e32 v2, 0x100, v1
	v_sub_u32_e32 v0, v0, v2
	v_add_u32_e32 v7, 0x100, v0
	v_mul_i32_i24_e32 v6, 0x220, v1
	v_ashrrev_i32_e32 v1, 4, v0
	v_lshrrev_b32_e32 v132, 4, v7
	v_add_u32_e32 v4, v1, v0
	v_add3_u32 v1, v6, v0, v132
	v_lshl_add_u32 v1, v1, 3, 0
	v_lshl_add_u32 v2, v0, 3, 0
	ds_read_b64 v[0:1], v1 offset:8320
	ds_read_b64 v[2:3], v2 offset:4224
	v_add_lshl_u32 v134, v4, v6, 3
	v_add_u32_e32 v4, 0, v134
	ds_read_b64 v[4:5], v4 offset:6272
	v_add3_u32 v135, v6, v7, v132
	s_waitcnt lgkmcnt(1)
	v_pk_mul_f32 v[6:7], v[0:1], v[2:3] op_sel:[1,1] op_sel_hi:[1,0]
	s_nop 0
	v_pk_fma_f32 v[132:133], v[0:1], v[2:3], v[6:7] op_sel_hi:[0,1,1] neg_lo:[0,0,1]
	s_waitcnt lgkmcnt(0)
	v_pk_add_f32 v[0:1], v[4:5], v[132:133]
	v_add_u32_e32 v2, s18, v134
	ds_write_b64 v2, v[0:1]
	v_pk_add_f32 v[0:1], v[4:5], v[132:133] neg_lo:[0,1] neg_hi:[0,1]
	v_lshl_add_u32 v2, v135, 3, s18
	v_mov_b32_e32 v4, v180
	ds_write_b64 v2, v[0:1]
	s_waitcnt lgkmcnt(0)
	s_barrier
	s_nop 0
	v_cmp_gt_i32_e32 vcc, s16, v4
	s_and_saveexec_b64 s[2:3], vcc
	s_cbranch_execz .LBB0_495
	v_ashrrev_i32_e32 v5, 31, v4
	v_lshrrev_b32_e32 v5, 27, v5
	v_add_u32_e32 v5, v4, v5
	v_pk_mul_f32 v[132:133], v[100:101], s[34:35] op_sel_hi:[1,0]
	v_lshrrev_b32_e32 v100, 5, v5
	v_and_b32_e32 v5, 0xffffffe0, v5
	v_sub_u32_e32 v138, v4, v5
	v_mul_lo_u32 v139, v100, s17
	v_ashrrev_i32_e32 v5, 4, v138
	v_add_u32_e32 v4, s18, v139
	v_lshlrev_b32_e32 v140, 3, v138
	v_lshlrev_b32_e32 v5, 3, v5
	v_add3_u32 v141, v4, v140, v5
	v_pk_mul_f32 v[134:135], v[102:103], s[34:35] op_sel_hi:[1,0]
	v_pk_mul_f32 v[136:137], v[104:105], s[34:35] op_sel_hi:[1,0]
	ds_read2_b64 v[102:105], v141 offset1:34
	v_pk_mul_f32 v[6:7], v[126:127], s[34:35] op_sel_hi:[1,0]
	v_pk_mul_f32 v[106:107], v[106:107], s[34:35] op_sel_hi:[1,0]
	v_pk_mul_f32 v[2:3], v[128:129], s[34:35] op_sel_hi:[1,0]
	v_pk_mul_f32 v[108:109], v[108:109], s[34:35] op_sel_hi:[1,0]
	s_waitcnt lgkmcnt(0)
	v_pk_mul_f32 v[4:5], v[132:133], v[102:103] op_sel:[1,1] op_sel_hi:[0,1]
	v_pk_fma_f32 v[100:101], v[132:133], v[102:103], v[4:5] op_sel_hi:[1,0,1] neg_lo:[0,0,1]
	v_pk_mul_f32 v[102:103], v[134:135], v[104:105] op_sel:[1,1] op_sel_hi:[0,1]
	v_pk_fma_f32 v[4:5], v[134:135], v[104:105], v[102:103] op_sel_hi:[1,0,1] neg_lo:[0,0,1]
	v_pk_mul_f32 v[110:111], v[110:111], s[34:35] op_sel_hi:[1,0]
	ds_read2_b64 v[102:105], v141 offset0:68 offset1:102
	v_pk_mul_f32 v[0:1], v[130:131], s[34:35] op_sel_hi:[1,0]
	v_pk_mul_f32 v[112:113], v[112:113], s[34:35] op_sel_hi:[1,0]
	v_pk_mul_f32 v[114:115], v[114:115], s[34:35] op_sel_hi:[1,0]
	v_add_u32_e32 v132, 0x800, v141
	s_waitcnt lgkmcnt(0)
	v_pk_mul_f32 v[126:127], v[136:137], v[102:103] op_sel:[1,1] op_sel_hi:[0,1]
	v_pk_fma_f32 v[128:129], v[136:137], v[102:103], v[126:127] op_sel_hi:[1,0,1] neg_lo:[0,0,1]
	v_pk_mul_f32 v[116:117], v[116:117], s[34:35] op_sel_hi:[1,0]
	v_pk_mul_f32 v[102:103], v[106:107], v[104:105] op_sel:[1,1] op_sel_hi:[0,1]
	v_pk_fma_f32 v[126:127], v[106:107], v[104:105], v[102:103] op_sel_hi:[1,0,1] neg_lo:[0,0,1]
	v_pk_mul_f32 v[118:119], v[118:119], s[34:35] op_sel_hi:[1,0]
	ds_read2_b64 v[102:105], v141 offset0:136 offset1:170
	v_pk_mul_f32 v[120:121], v[120:121], s[34:35] op_sel_hi:[1,0]
	v_pk_mul_f32 v[122:123], v[122:123], s[34:35] op_sel_hi:[1,0]
	v_pk_mul_f32 v[124:125], v[124:125], s[34:35] op_sel_hi:[1,0]
	s_mov_b32 s29, s30
	s_waitcnt lgkmcnt(0)
	v_pk_mul_f32 v[106:107], v[108:109], v[102:103] op_sel:[1,1] op_sel_hi:[0,1]
	v_pk_fma_f32 v[130:131], v[108:109], v[102:103], v[106:107] op_sel_hi:[1,0,1] neg_lo:[0,0,1]
	s_nop 0
	v_pk_mul_f32 v[102:103], v[110:111], v[104:105] op_sel:[1,1] op_sel_hi:[0,1]
	v_pk_fma_f32 v[106:107], v[110:111], v[104:105], v[102:103] op_sel_hi:[1,0,1] neg_lo:[0,0,1]
	s_nop 0
	ds_read2_b64 v[102:105], v141 offset0:204 offset1:238
	s_waitcnt lgkmcnt(0)
	v_pk_mul_f32 v[108:109], v[112:113], v[102:103] op_sel:[1,1] op_sel_hi:[0,1]
	v_pk_fma_f32 v[110:111], v[112:113], v[102:103], v[108:109] op_sel_hi:[1,0,1] neg_lo:[0,0,1]
	s_nop 0
	v_pk_mul_f32 v[102:103], v[114:115], v[104:105] op_sel:[1,1] op_sel_hi:[0,1]
	v_pk_fma_f32 v[108:109], v[114:115], v[104:105], v[102:103] op_sel_hi:[1,0,1] neg_lo:[0,0,1]
	s_nop 0
	ds_read2_b64 v[102:105], v132 offset0:16 offset1:50
	s_waitcnt lgkmcnt(0)
	v_pk_mul_f32 v[112:113], v[116:117], v[102:103] op_sel:[1,1] op_sel_hi:[0,1]
	v_pk_fma_f32 v[114:115], v[116:117], v[102:103], v[112:113] op_sel_hi:[1,0,1] neg_lo:[0,0,1]
	s_nop 0
	v_pk_mul_f32 v[102:103], v[118:119], v[104:105] op_sel:[1,1] op_sel_hi:[0,1]
	v_pk_fma_f32 v[112:113], v[118:119], v[104:105], v[102:103] op_sel_hi:[1,0,1] neg_lo:[0,0,1]
	s_nop 0
	ds_read2_b64 v[102:105], v132 offset0:84 offset1:118
	s_waitcnt lgkmcnt(0)
	v_pk_mul_f32 v[116:117], v[120:121], v[102:103] op_sel:[1,1] op_sel_hi:[0,1]
	v_pk_fma_f32 v[118:119], v[120:121], v[102:103], v[116:117] op_sel_hi:[1,0,1] neg_lo:[0,0,1]
	s_nop 0
	v_pk_mul_f32 v[102:103], v[122:123], v[104:105] op_sel:[1,1] op_sel_hi:[0,1]
	v_pk_fma_f32 v[116:117], v[122:123], v[104:105], v[102:103] op_sel_hi:[1,0,1] neg_lo:[0,0,1]
	s_nop 0
	ds_read2_b64 v[102:105], v132 offset0:152 offset1:186
	s_waitcnt lgkmcnt(0)
	v_pk_mul_f32 v[120:121], v[124:125], v[102:103] op_sel:[1,1] op_sel_hi:[0,1]
	v_pk_fma_f32 v[122:123], v[124:125], v[102:103], v[120:121] op_sel_hi:[1,0,1] neg_lo:[0,0,1]
	s_nop 0
	v_pk_mul_f32 v[102:103], v[6:7], v[104:105] op_sel:[1,1] op_sel_hi:[0,1]
	v_pk_fma_f32 v[120:121], v[6:7], v[104:105], v[102:103] op_sel_hi:[1,0,1] neg_lo:[0,0,1]
	ds_read2_b64 v[102:105], v132 offset0:220 offset1:254
	s_waitcnt lgkmcnt(0)
	v_pk_mul_f32 v[6:7], v[2:3], v[102:103] op_sel:[1,1] op_sel_hi:[0,1]
	v_pk_fma_f32 v[124:125], v[2:3], v[102:103], v[6:7] op_sel_hi:[1,0,1] neg_lo:[0,0,1]
	v_pk_add_f32 v[102:103], v[130:131], v[122:123] neg_lo:[0,1] neg_hi:[0,1]
	v_pk_mul_f32 v[2:3], v[0:1], v[104:105] op_sel:[1,1] op_sel_hi:[0,1]
	v_pk_fma_f32 v[6:7], v[0:1], v[104:105], v[2:3] op_sel_hi:[1,0,1] neg_lo:[0,0,1]
	v_pk_add_f32 v[2:3], v[100:101], v[114:115] neg_lo:[0,1] neg_hi:[0,1]
	v_pk_add_f32 v[0:1], v[100:101], v[114:115]
	v_pk_add_f32 v[100:101], v[130:131], v[122:123]
	v_pk_add_f32 v[114:115], v[2:3], v[102:103] op_sel:[0,1] op_sel_hi:[1,0] neg_lo:[0,1]
	v_pk_add_f32 v[2:3], v[2:3], v[102:103] op_sel:[0,1] op_sel_hi:[1,0] neg_hi:[0,1]
	v_pk_add_f32 v[104:105], v[106:107], v[120:121]
	v_pk_add_f32 v[106:107], v[106:107], v[120:121] neg_lo:[0,1] neg_hi:[0,1]
	v_pk_add_f32 v[102:103], v[0:1], v[100:101]
	v_pk_add_f32 v[0:1], v[0:1], v[100:101] neg_lo:[0,1] neg_hi:[0,1]
	v_pk_add_f32 v[100:101], v[4:5], v[112:113]
	v_pk_add_f32 v[4:5], v[4:5], v[112:113] neg_lo:[0,1] neg_hi:[0,1]
	v_xor_b32_e32 v112, 0x80000000, v107
	v_mov_b32_e32 v113, v106
	v_pk_add_f32 v[106:107], v[100:101], v[104:105]
	v_pk_add_f32 v[120:121], v[4:5], v[112:113]
	v_pk_add_f32 v[100:101], v[100:101], v[104:105] neg_lo:[0,1] neg_hi:[0,1]
	v_pk_add_f32 v[4:5], v[4:5], v[112:113] neg_lo:[0,1] neg_hi:[0,1]
	v_pk_add_f32 v[104:105], v[128:129], v[118:119]
	v_pk_add_f32 v[112:113], v[128:129], v[118:119] neg_lo:[0,1] neg_hi:[0,1]
	v_pk_add_f32 v[118:119], v[110:111], v[124:125]
	v_pk_add_f32 v[110:111], v[110:111], v[124:125] neg_lo:[0,1] neg_hi:[0,1]
	s_nop 0
	v_pk_add_f32 v[124:125], v[112:113], v[110:111] op_sel:[0,1] op_sel_hi:[1,0] neg_lo:[0,1]
	v_pk_add_f32 v[112:113], v[112:113], v[110:111] op_sel:[0,1] op_sel_hi:[1,0] neg_hi:[0,1]
	v_pk_add_f32 v[122:123], v[108:109], v[6:7]
	v_pk_add_f32 v[6:7], v[108:109], v[6:7] neg_lo:[0,1] neg_hi:[0,1]
	v_pk_add_f32 v[110:111], v[104:105], v[118:119]
	v_pk_add_f32 v[104:105], v[104:105], v[118:119] neg_lo:[0,1] neg_hi:[0,1]
	v_pk_add_f32 v[118:119], v[126:127], v[116:117]
	v_pk_add_f32 v[116:117], v[126:127], v[116:117] neg_lo:[0,1] neg_hi:[0,1]
	v_pk_add_f32 v[126:127], v[116:117], v[6:7] op_sel:[0,1] op_sel_hi:[1,0] neg_lo:[0,1]
	v_pk_add_f32 v[108:109], v[116:117], v[6:7] op_sel:[0,1] op_sel_hi:[1,0] neg_hi:[0,1]
	v_pk_mul_f32 v[116:117], v[120:121], s[14:15] op_sel_hi:[1,0]
	v_pk_add_f32 v[6:7], v[118:119], v[122:123]
	v_pk_add_f32 v[118:119], v[118:119], v[122:123] neg_lo:[0,1] neg_hi:[0,1]
	v_pk_fma_f32 v[122:123], v[120:121], s[22:23], v[116:117] op_sel:[0,0,1] op_sel_hi:[1,0,0] neg_lo:[0,0,1]
	s_nop 0
	v_pk_mul_f32 v[116:117], v[100:101], s[24:25] op_sel_hi:[1,0]
	s_nop 0
	v_pk_fma_f32 v[120:121], v[100:101], s[24:25], v[116:117] op_sel:[0,0,1] op_sel_hi:[1,0,0] neg_lo:[0,0,1]
	v_pk_mul_f32 v[116:117], v[4:5], s[22:23] op_sel_hi:[1,0]
	v_pk_fma_f32 v[128:129], v[4:5], s[14:15], v[116:117] op_sel:[0,0,1] op_sel_hi:[1,0,0] neg_lo:[0,0,1]
	s_nop 0
	v_pk_mul_f32 v[4:5], v[124:125], s[24:25] op_sel_hi:[1,0]
	s_nop 0
	v_pk_fma_f32 v[116:117], v[124:125], s[24:25], v[4:5] op_sel:[0,0,1] op_sel_hi:[1,0,0] neg_lo:[0,0,1]
	s_nop 0
	v_pk_fma_f32 v[4:5], v[104:105], 0, v[104:105] op_sel:[0,0,1] op_sel_hi:[1,0,0] neg_lo:[0,0,1]
	s_nop 0
	v_pk_mul_f32 v[104:105], v[112:113], s[26:27] op_sel_hi:[1,0]
	s_nop 0
	v_pk_fma_f32 v[124:125], v[112:113], s[26:27], v[104:105] op_sel:[0,0,1] op_sel_hi:[1,0,0] neg_hi:[0,0,1]
	v_pk_mul_f32 v[112:113], v[126:127], s[22:23] op_sel_hi:[1,0]
	v_pk_fma_f32 v[130:131], v[126:127], s[14:15], v[112:113] op_sel:[0,0,1] op_sel_hi:[1,0,0] neg_lo:[0,0,1]
	s_mov_b32 s15, s28
	v_pk_mul_f32 v[112:113], v[118:119], s[26:27] op_sel_hi:[1,0]
	v_pk_add_f32 v[104:105], v[2:3], v[124:125]
	v_pk_fma_f32 v[126:127], v[118:119], s[26:27], v[112:113] op_sel:[0,0,1] op_sel_hi:[1,0,0] neg_hi:[0,0,1]
	v_pk_add_f32 v[2:3], v[2:3], v[124:125] neg_lo:[0,1] neg_hi:[0,1]
	v_pk_mul_f32 v[112:113], v[108:109], s[28:29] op_sel_hi:[0,1]
	v_pk_fma_f32 v[108:109], v[108:109], s[14:15], v[112:113] op_sel:[1,0,0]
	v_pk_add_f32 v[112:113], v[102:103], v[110:111]
	v_pk_add_f32 v[102:103], v[102:103], v[110:111] neg_lo:[0,1] neg_hi:[0,1]
	v_pk_add_f32 v[110:111], v[106:107], v[6:7]
	v_pk_add_f32 v[6:7], v[106:107], v[6:7] neg_lo:[0,1] neg_hi:[0,1]
	v_pk_add_f32 v[100:101], v[120:121], v[126:127] neg_lo:[0,1] neg_hi:[0,1]
	v_xor_b32_e32 v106, 0x80000000, v7
	v_mov_b32_e32 v107, v6
	v_pk_add_f32 v[6:7], v[112:113], v[110:111]
	v_pk_add_f32 v[118:119], v[102:103], v[106:107]
	v_pk_add_f32 v[110:111], v[112:113], v[110:111] neg_lo:[0,1] neg_hi:[0,1]
	v_pk_add_f32 v[102:103], v[102:103], v[106:107] neg_lo:[0,1] neg_hi:[0,1]
	v_pk_add_f32 v[106:107], v[114:115], v[116:117]
	v_pk_add_f32 v[112:113], v[114:115], v[116:117] neg_lo:[0,1] neg_hi:[0,1]
	v_pk_add_f32 v[114:115], v[122:123], v[130:131]
	v_pk_add_f32 v[116:117], v[122:123], v[130:131] neg_lo:[0,1] neg_hi:[0,1]
	s_nop 0
	v_xor_b32_e32 v122, 0x80000000, v117
	v_mov_b32_e32 v123, v116
	v_pk_add_f32 v[116:117], v[106:107], v[114:115]
	v_pk_add_f32 v[106:107], v[106:107], v[114:115] neg_lo:[0,1] neg_hi:[0,1]
	v_pk_add_f32 v[114:115], v[0:1], v[4:5]
	v_pk_add_f32 v[0:1], v[0:1], v[4:5] neg_lo:[0,1] neg_hi:[0,1]
	v_pk_add_f32 v[4:5], v[120:121], v[126:127]
	v_xor_b32_e32 v120, 0x80000000, v101
	v_mov_b32_e32 v121, v100
	v_pk_add_f32 v[100:101], v[114:115], v[4:5]
	v_pk_add_f32 v[4:5], v[114:115], v[4:5] neg_lo:[0,1] neg_hi:[0,1]
	v_pk_add_f32 v[114:115], v[128:129], v[108:109]
	v_pk_add_f32 v[108:109], v[128:129], v[108:109] neg_lo:[0,1] neg_hi:[0,1]
	v_pk_add_f32 v[130:131], v[112:113], v[122:123]
	v_pk_add_f32 v[112:113], v[112:113], v[122:123] neg_lo:[0,1] neg_hi:[0,1]
	v_pk_add_f32 v[122:123], v[0:1], v[120:121]
	v_pk_add_f32 v[0:1], v[0:1], v[120:121] neg_lo:[0,1] neg_hi:[0,1]
	v_xor_b32_e32 v120, 0x80000000, v109
	v_mov_b32_e32 v121, v108
	v_pk_add_f32 v[108:109], v[104:105], v[114:115]
	v_pk_add_f32 v[104:105], v[104:105], v[114:115] neg_lo:[0,1] neg_hi:[0,1]
	v_add_u32_e32 v114, 0, v139
	v_lshlrev_b32_e32 v115, 7, v138
	v_add3_u32 v114, v114, v115, v140
	v_add_u32_e32 v115, 0x1880, v114
	ds_write2_b64 v115, v[6:7], v[116:117] offset1:1
	v_add_u32_e32 v6, 0x1890, v114
	ds_write2_b64 v6, v[100:101], v[108:109] offset1:1
	v_add_u32_e32 v6, 0x18a0, v114
	v_pk_add_f32 v[124:125], v[2:3], v[120:121]
	ds_write2_b64 v6, v[118:119], v[130:131] offset1:1
	v_add_u32_e32 v6, 0x18b0, v114
	ds_write2_b64 v6, v[122:123], v[124:125] offset1:1
	v_add_u32_e32 v6, 0x18c0, v114
	ds_write2_b64 v6, v[110:111], v[106:107] offset1:1
	v_add_u32_e32 v6, 0x18d0, v114
	ds_write2_b64 v6, v[4:5], v[104:105] offset1:1
	v_add_u32_e32 v4, 0x18e0, v114
	v_pk_add_f32 v[2:3], v[2:3], v[120:121] neg_lo:[0,1] neg_hi:[0,1]
	ds_write2_b64 v4, v[102:103], v[112:113] offset1:1
	v_add_u32_e32 v4, 0x18f0, v114
	ds_write2_b64 v4, v[0:1], v[2:3] offset1:1

.LBB0_497:
	s_or_b64 exec, exec, s[2:3]
	s_waitcnt vmcnt(1)
	v_lshlrev_b32_e32 v0, 16, v82
	v_mul_f32_e32 v4, v185, v193
	v_and_b32_e32 v1, 0xffff0000, v82
	v_fmac_f32_e32 v4, v186, v0
	v_fmac_f32_e32 v4, v184, v1
	v_lshlrev_b32_e32 v2, 16, v83
	v_add_f32_e32 v5, v183, v4
	v_mul_f32_e32 v4, v186, v1
	v_fmac_f32_e32 v4, v185, v0
	v_mul_f32_e32 v0, v186, v2
	v_and_b32_e32 v3, 0xffff0000, v83
	v_fmac_f32_e32 v0, v185, v1
	v_fmac_f32_e32 v0, v184, v3
	v_add_f32_e32 v1, v183, v0
	v_mul_f32_e32 v0, v186, v3
	v_fmac_f32_e32 v0, v185, v2
	v_fmac_f32_e32 v4, v184, v2
	v_fmac_f32_e32 v0, v184, v194
	v_and_b32_e32 v2, 0xffff0000, v80
	v_add_f32_e32 v7, v183, v4
	v_add_f32_e32 v3, v183, v0
	v_lshlrev_b32_e32 v0, 16, v80
	v_lshlrev_b32_e32 v80, 16, v81
	v_mul_f32_e32 v4, v185, v191
	v_mul_f32_e32 v6, v186, v2
	v_and_b32_e32 v81, 0xffff0000, v81
	v_fmac_f32_e32 v4, v186, v0
	v_fmac_f32_e32 v6, v185, v0
	v_mul_f32_e32 v0, v186, v80
	v_fmac_f32_e32 v4, v184, v2
	v_fmac_f32_e32 v0, v185, v2
	v_mul_f32_e32 v2, v186, v81
	v_fmac_f32_e32 v6, v184, v80
	v_fmac_f32_e32 v2, v185, v80
	v_lshlrev_b32_e32 v80, 16, v78
	v_and_b32_e32 v78, 0xffff0000, v78
	v_fmac_f32_e32 v0, v184, v81
	v_lshlrev_b32_e32 v82, 16, v79
	v_and_b32_e32 v83, 0xffff0000, v79
	v_mul_f32_e32 v79, v182, v189
	v_mul_f32_e32 v81, v42, v78
	v_fmac_f32_e32 v79, v42, v80
	v_fmac_f32_e32 v81, v182, v80
	v_mul_f32_e32 v80, v42, v82
	v_fmac_f32_e32 v79, v38, v78
	v_fmac_f32_e32 v80, v182, v78
	v_mul_f32_e32 v78, v42, v83
	v_fmac_f32_e32 v81, v38, v82
	v_fmac_f32_e32 v80, v38, v83
	v_fmac_f32_e32 v78, v182, v82
	v_add_f32_e32 v101, v27, v81
	v_add_f32_e32 v81, v27, v80
	v_fmac_f32_e32 v78, v38, v190
	v_lshlrev_b32_e32 v80, 16, v68
	v_and_b32_e32 v68, 0xffff0000, v68
	v_add_f32_e32 v83, v27, v78
	v_lshlrev_b32_e32 v82, 16, v69
	v_and_b32_e32 v69, 0xffff0000, v69
	v_mul_f32_e32 v78, v182, v187
	v_mul_f32_e32 v100, v42, v68
	v_fmac_f32_e32 v78, v42, v80
	v_fmac_f32_e32 v100, v182, v80
	v_mul_f32_e32 v80, v42, v82
	v_mul_f32_e32 v42, v42, v69
	v_fmac_f32_e32 v80, v182, v68
	v_fmac_f32_e32 v42, v182, v82
	v_fmac_f32_e32 v78, v38, v68
	v_fmac_f32_e32 v100, v38, v82
	v_fmac_f32_e32 v80, v38, v69
	v_fmac_f32_e32 v42, v38, v188
	v_add_f32_e32 v79, v27, v79
	v_add_f32_e32 v78, v27, v78
	v_add_f32_e32 v100, v27, v100
	v_add_f32_e32 v80, v27, v80
	v_add_f32_e32 v82, v27, v42
	v_mov_b32_e32 v27, v180
	s_waitcnt lgkmcnt(0)
	s_barrier
	v_lshl_add_u32 v102, v197, 3, 0
	v_ashrrev_i32_e32 v38, 31, v27
	v_add_u32_sdwa v38, v27, v38 dst_sel:DWORD dst_unused:UNUSED_PAD src0_sel:DWORD src1_sel:BYTE_3
	v_ashrrev_i32_e32 v38, 8, v38
	v_mul_i32_i24_e32 v42, 0x100, v38
	v_sub_u32_e32 v42, v27, v42
	v_ashrrev_i32_e32 v68, 4, v42
	v_add_u32_e32 v104, 0x100, v42
	v_mul_i32_i24_e32 v38, 0x220, v38
	v_add_u32_e32 v68, v68, v42
	v_lshrrev_b32_e32 v112, 4, v104
	v_add_lshl_u32 v103, v68, v38, 3
	v_add3_u32 v104, v38, v104, v112
	v_add_u32_e32 v68, s18, v103
	v_lshl_add_u32 v104, v104, 3, s18
	v_lshl_add_u32 v106, v42, 3, 0
	ds_read_b64 v[68:69], v68
	ds_read_b64 v[104:105], v104
	ds_read_b64 v[106:107], v106 offset:4224
	v_add3_u32 v38, v38, v42, v112
	v_add_u32_e32 v103, 0, v103
	v_lshl_add_u32 v38, v38, 3, 0
	v_add_f32_e32 v4, v183, v4
	s_waitcnt lgkmcnt(0)
	v_pk_mul_f32 v[108:109], v[104:105], v[106:107] op_sel:[1,1] op_sel_hi:[0,1]
	v_pk_fma_f32 v[110:111], v[104:105], v[106:107], v[108:109] op_sel_hi:[1,0,1] neg_hi:[0,0,1]
	v_add_f32_e32 v6, v183, v6
	v_pk_add_f32 v[104:105], v[68:69], v[110:111]
	v_pk_add_f32 v[68:69], v[68:69], v[110:111] neg_lo:[0,1] neg_hi:[0,1]
	ds_write_b64 v103, v[104:105] offset:6272
	ds_write_b64 v38, v[68:69] offset:8320
	v_add_u32_e32 v38, 0x200, v27
	v_ashrrev_i32_e32 v42, 31, v38
	v_add_u32_sdwa v42, v38, v42 dst_sel:DWORD dst_unused:UNUSED_PAD src0_sel:DWORD src1_sel:BYTE_3
	v_ashrrev_i32_e32 v42, 8, v42
	v_mul_i32_i24_e32 v68, 0x100, v42
	v_sub_u32_e32 v38, v38, v68
	v_ashrrev_i32_e32 v68, 4, v38
	v_add_u32_e32 v104, 0x100, v38
	v_mul_i32_i24_e32 v42, 0x220, v42
	v_add_u32_e32 v68, v68, v38
	v_lshrrev_b32_e32 v112, 4, v104
	v_add_lshl_u32 v103, v68, v42, 3
	v_add3_u32 v104, v42, v104, v112
	v_add_u32_e32 v68, s18, v103
	v_lshl_add_u32 v104, v104, 3, s18
	v_lshl_add_u32 v106, v38, 3, 0
	ds_read_b64 v[68:69], v68
	ds_read_b64 v[104:105], v104
	ds_read_b64 v[106:107], v106 offset:4224
	v_add3_u32 v38, v42, v38, v112
	v_add_u32_e32 v103, 0, v103
	v_lshl_add_u32 v38, v38, 3, 0
	v_add_f32_e32 v0, v183, v0
	s_waitcnt lgkmcnt(0)
	v_pk_mul_f32 v[108:109], v[104:105], v[106:107] op_sel:[1,1] op_sel_hi:[0,1]
	v_pk_fma_f32 v[110:111], v[104:105], v[106:107], v[108:109] op_sel_hi:[1,0,1] neg_hi:[0,0,1]
	v_fmac_f32_e32 v2, v184, v192
	v_pk_add_f32 v[104:105], v[68:69], v[110:111]
	v_pk_add_f32 v[68:69], v[68:69], v[110:111] neg_lo:[0,1] neg_hi:[0,1]
	ds_write_b64 v103, v[104:105] offset:6272
	ds_write_b64 v38, v[68:69] offset:8320
	v_add_u32_e32 v38, 0x400, v27
	v_ashrrev_i32_e32 v42, 31, v38
	v_add_u32_sdwa v42, v38, v42 dst_sel:DWORD dst_unused:UNUSED_PAD src0_sel:DWORD src1_sel:BYTE_3
	v_ashrrev_i32_e32 v42, 8, v42
	v_mul_i32_i24_e32 v68, 0x100, v42
	v_sub_u32_e32 v38, v38, v68
	v_ashrrev_i32_e32 v68, 4, v38
	v_add_u32_e32 v104, 0x100, v38
	v_mul_i32_i24_e32 v42, 0x220, v42
	v_add_u32_e32 v68, v68, v38
	v_lshrrev_b32_e32 v112, 4, v104
	v_add_lshl_u32 v103, v68, v42, 3
	v_add3_u32 v104, v42, v104, v112
	v_add_u32_e32 v68, s18, v103
	v_lshl_add_u32 v104, v104, 3, s18
	v_lshl_add_u32 v106, v38, 3, 0
	ds_read_b64 v[68:69], v68
	ds_read_b64 v[104:105], v104
	ds_read_b64 v[106:107], v106 offset:4224
	v_add3_u32 v38, v42, v38, v112
	v_add_u32_e32 v103, 0, v103
	v_lshl_add_u32 v38, v38, 3, 0
	v_add_f32_e32 v2, v183, v2
	s_waitcnt lgkmcnt(0)
	v_pk_mul_f32 v[108:109], v[104:105], v[106:107] op_sel:[1,1] op_sel_hi:[0,1]
	v_pk_fma_f32 v[110:111], v[104:105], v[106:107], v[108:109] op_sel_hi:[1,0,1] neg_hi:[0,0,1]
	s_nop 0
	v_pk_add_f32 v[104:105], v[68:69], v[110:111]
	v_pk_add_f32 v[68:69], v[68:69], v[110:111] neg_lo:[0,1] neg_hi:[0,1]
	ds_write_b64 v103, v[104:105] offset:6272
	ds_write_b64 v38, v[68:69] offset:8320
	v_add_u32_e32 v38, 0x600, v27
	v_ashrrev_i32_e32 v42, 31, v38
	v_add_u32_sdwa v42, v38, v42 dst_sel:DWORD dst_unused:UNUSED_PAD src0_sel:DWORD src1_sel:BYTE_3
	v_ashrrev_i32_e32 v42, 8, v42
	v_mul_i32_i24_e32 v68, 0x100, v42
	v_sub_u32_e32 v38, v38, v68
	v_ashrrev_i32_e32 v68, 4, v38
	v_add_u32_e32 v104, 0x100, v38
	v_mul_i32_i24_e32 v42, 0x220, v42
	v_add_u32_e32 v68, v68, v38
	v_lshrrev_b32_e32 v112, 4, v104
	v_add_lshl_u32 v103, v68, v42, 3
	v_add3_u32 v104, v42, v104, v112
	v_add_u32_e32 v68, s18, v103
	v_lshl_add_u32 v104, v104, 3, s18
	v_lshl_add_u32 v106, v38, 3, 0
	ds_read_b64 v[68:69], v68
	ds_read_b64 v[104:105], v104
	ds_read_b64 v[106:107], v106 offset:4224
	v_add3_u32 v38, v42, v38, v112
	v_add_u32_e32 v103, 0, v103
	v_lshl_add_u32 v38, v38, 3, 0
	s_waitcnt lgkmcnt(0)
	v_pk_mul_f32 v[108:109], v[104:105], v[106:107] op_sel:[1,1] op_sel_hi:[0,1]
	v_pk_fma_f32 v[110:111], v[104:105], v[106:107], v[108:109] op_sel_hi:[1,0,1] neg_hi:[0,0,1]
	s_nop 0
	v_pk_add_f32 v[104:105], v[68:69], v[110:111]
	v_pk_add_f32 v[68:69], v[68:69], v[110:111] neg_lo:[0,1] neg_hi:[0,1]
	ds_write_b64 v103, v[104:105] offset:6272
	ds_write_b64 v38, v[68:69] offset:8320
	v_add_u32_e32 v38, 0x800, v27
	v_ashrrev_i32_e32 v42, 31, v38
	v_add_u32_sdwa v42, v38, v42 dst_sel:DWORD dst_unused:UNUSED_PAD src0_sel:DWORD src1_sel:BYTE_3
	v_ashrrev_i32_e32 v42, 8, v42
	v_mul_i32_i24_e32 v68, 0x100, v42
	v_sub_u32_e32 v38, v38, v68
	v_ashrrev_i32_e32 v68, 4, v38
	v_add_u32_e32 v104, 0x100, v38
	v_mul_i32_i24_e32 v42, 0x220, v42
	v_add_u32_e32 v68, v68, v38
	v_lshrrev_b32_e32 v112, 4, v104
	v_add_lshl_u32 v103, v68, v42, 3
	v_add3_u32 v104, v42, v104, v112
	v_add_u32_e32 v68, s18, v103
	v_lshl_add_u32 v104, v104, 3, s18
	v_lshl_add_u32 v106, v38, 3, 0
	ds_read_b64 v[68:69], v68
	ds_read_b64 v[104:105], v104
	ds_read_b64 v[106:107], v106 offset:4224
	v_add3_u32 v38, v42, v38, v112
	v_add_u32_e32 v103, 0, v103
	v_lshl_add_u32 v38, v38, 3, 0
	s_waitcnt lgkmcnt(0)
	v_pk_mul_f32 v[108:109], v[104:105], v[106:107] op_sel:[1,1] op_sel_hi:[0,1]
	v_pk_fma_f32 v[110:111], v[104:105], v[106:107], v[108:109] op_sel_hi:[1,0,1] neg_hi:[0,0,1]
	s_nop 0
	v_pk_add_f32 v[104:105], v[68:69], v[110:111]
	v_pk_add_f32 v[68:69], v[68:69], v[110:111] neg_lo:[0,1] neg_hi:[0,1]
	ds_write_b64 v103, v[104:105] offset:6272
	ds_write_b64 v38, v[68:69] offset:8320
	v_add_u32_e32 v38, 0xa00, v27
	v_ashrrev_i32_e32 v42, 31, v38
	v_add_u32_sdwa v42, v38, v42 dst_sel:DWORD dst_unused:UNUSED_PAD src0_sel:DWORD src1_sel:BYTE_3
	v_ashrrev_i32_e32 v42, 8, v42
	v_mul_i32_i24_e32 v68, 0x100, v42
	v_sub_u32_e32 v38, v38, v68
	v_ashrrev_i32_e32 v68, 4, v38
	v_add_u32_e32 v104, 0x100, v38
	v_mul_i32_i24_e32 v42, 0x220, v42
	v_add_u32_e32 v68, v68, v38
	v_lshrrev_b32_e32 v112, 4, v104
	v_add_lshl_u32 v103, v68, v42, 3
	v_add3_u32 v104, v42, v104, v112
	v_add_u32_e32 v68, s18, v103
	v_lshl_add_u32 v104, v104, 3, s18
	v_lshl_add_u32 v106, v38, 3, 0
	ds_read_b64 v[68:69], v68
	ds_read_b64 v[104:105], v104
	ds_read_b64 v[106:107], v106 offset:4224
	v_add3_u32 v38, v42, v38, v112
	v_add_u32_e32 v103, 0, v103
	v_lshl_add_u32 v38, v38, 3, 0
	s_waitcnt lgkmcnt(0)
	v_pk_mul_f32 v[108:109], v[104:105], v[106:107] op_sel:[1,1] op_sel_hi:[0,1]
	v_pk_fma_f32 v[110:111], v[104:105], v[106:107], v[108:109] op_sel_hi:[1,0,1] neg_hi:[0,0,1]
	s_nop 0
	v_pk_add_f32 v[104:105], v[68:69], v[110:111]
	v_pk_add_f32 v[68:69], v[68:69], v[110:111] neg_lo:[0,1] neg_hi:[0,1]
	ds_write_b64 v103, v[104:105] offset:6272
	ds_write_b64 v38, v[68:69] offset:8320
	v_add_u32_e32 v38, 0xc00, v27
	v_ashrrev_i32_e32 v42, 31, v38
	v_add_u32_sdwa v42, v38, v42 dst_sel:DWORD dst_unused:UNUSED_PAD src0_sel:DWORD src1_sel:BYTE_3
	v_ashrrev_i32_e32 v42, 8, v42
	v_mul_i32_i24_e32 v68, 0x100, v42
	v_sub_u32_e32 v38, v38, v68
	v_ashrrev_i32_e32 v68, 4, v38
	v_add_u32_e32 v104, 0x100, v38
	v_mul_i32_i24_e32 v42, 0x220, v42
	v_add_u32_e32 v68, v68, v38
	v_lshrrev_b32_e32 v112, 4, v104
	v_add_lshl_u32 v103, v68, v42, 3
	v_add3_u32 v104, v42, v104, v112
	v_add_u32_e32 v68, s18, v103
	v_lshl_add_u32 v104, v104, 3, s18
	v_lshl_add_u32 v106, v38, 3, 0
	ds_read_b64 v[68:69], v68
	ds_read_b64 v[104:105], v104
	ds_read_b64 v[106:107], v106 offset:4224
	v_add3_u32 v38, v42, v38, v112
	v_add_u32_e32 v103, 0, v103
	v_lshl_add_u32 v38, v38, 3, 0
	v_add_u32_e32 v27, 0xe00, v27
	s_waitcnt lgkmcnt(0)
	v_pk_mul_f32 v[108:109], v[104:105], v[106:107] op_sel:[1,1] op_sel_hi:[0,1]
	v_pk_fma_f32 v[110:111], v[104:105], v[106:107], v[108:109] op_sel_hi:[1,0,1] neg_hi:[0,0,1]
	s_nop 0
	v_pk_add_f32 v[104:105], v[68:69], v[110:111]
	v_pk_add_f32 v[68:69], v[68:69], v[110:111] neg_lo:[0,1] neg_hi:[0,1]
	ds_write_b64 v103, v[104:105] offset:6272
	ds_write_b64 v38, v[68:69] offset:8320
	v_ashrrev_i32_e32 v38, 31, v27
	v_add_u32_sdwa v38, v27, v38 dst_sel:DWORD dst_unused:UNUSED_PAD src0_sel:DWORD src1_sel:BYTE_3
	v_ashrrev_i32_e32 v38, 8, v38
	v_mul_i32_i24_e32 v42, 0x100, v38
	v_sub_u32_e32 v27, v27, v42
	v_ashrrev_i32_e32 v42, 4, v27
	v_add_u32_e32 v103, 0x100, v27
	v_mul_i32_i24_e32 v38, 0x220, v38
	v_add_u32_e32 v42, v42, v27
	v_lshrrev_b32_e32 v112, 4, v103
	v_add_lshl_u32 v42, v42, v38, 3
	v_add3_u32 v103, v38, v103, v112
	v_add_u32_e32 v68, s18, v42
	v_lshl_add_u32 v103, v103, 3, s18
	ds_read_b64 v[68:69], v68
	ds_read_b64 v[104:105], v103
	v_lshl_add_u32 v103, v27, 3, 0
	ds_read_b64 v[106:107], v103 offset:4224
	v_add_u32_e32 v42, 0, v42
	v_add3_u32 v27, v38, v27, v112
	v_lshl_add_u32 v27, v27, 3, 0
	s_waitcnt lgkmcnt(0)
	v_pk_mul_f32 v[108:109], v[104:105], v[106:107] op_sel:[1,1] op_sel_hi:[0,1]
	v_pk_fma_f32 v[110:111], v[104:105], v[106:107], v[108:109] op_sel_hi:[1,0,1] neg_hi:[0,0,1]
	s_nop 0
	v_pk_add_f32 v[104:105], v[68:69], v[110:111]
	ds_write_b64 v42, v[104:105] offset:6272
	v_pk_add_f32 v[68:69], v[68:69], v[110:111] neg_lo:[0,1] neg_hi:[0,1]
	v_add_u32_e32 v42, v102, v196
	ds_write_b64 v27, v[68:69] offset:8320
	v_add_u32_e32 v27, 0x1880, v42
	s_waitcnt lgkmcnt(0)
	s_barrier
	ds_read2_b64 v[102:105], v27 offset1:1
	v_add_u32_e32 v38, 0x1890, v42
	s_waitcnt lgkmcnt(0)
	v_pk_fma_f32 v[68:69], v[22:23], v[94:95], v[102:103] op_sel_hi:[0,1,1]
	v_pk_mul_f32 v[68:69], v[78:79], v[68:69]
	v_pk_fma_f32 v[78:79], v[22:23], v[96:97], v[104:105] op_sel_hi:[0,1,1]
	ds_read2_b64 v[94:97], v38 offset1:1
	v_pk_mul_f32 v[78:79], v[100:101], v[78:79]
	s_waitcnt lgkmcnt(0)
	v_pk_fma_f32 v[92:93], v[22:23], v[92:93], v[94:95] op_sel_hi:[0,1,1]
	v_pk_mul_f32 v[80:81], v[80:81], v[92:93]
	v_pk_fma_f32 v[92:93], v[22:23], v[98:99], v[96:97] op_sel_hi:[0,1,1]
	v_add_u32_e32 v22, 0xa080, v42
	v_pk_mul_f32 v[82:83], v[82:83], v[92:93]
	ds_read2_b64 v[92:95], v22 offset1:1
	v_add_u32_e32 v42, 0xa090, v42
	s_waitcnt lgkmcnt(0)
	v_pk_fma_f32 v[88:89], v[10:11], v[88:89], v[92:93] op_sel_hi:[0,1,1]
	v_pk_mul_f32 v[88:89], v[4:5], v[88:89]
	v_pk_fma_f32 v[4:5], v[10:11], v[90:91], v[94:95] op_sel_hi:[0,1,1]
	v_pk_mul_f32 v[90:91], v[6:7], v[4:5]
	ds_read2_b64 v[4:7], v42 offset1:1
	s_waitcnt lgkmcnt(0)
	s_barrier
	v_pk_fma_f32 v[4:5], v[10:11], v[84:85], v[4:5] op_sel_hi:[0,1,1]
	v_pk_mul_f32 v[84:85], v[0:1], v[4:5]
	v_pk_fma_f32 v[0:1], v[10:11], v[86:87], v[6:7] op_sel_hi:[0,1,1]
	v_pk_mul_f32 v[86:87], v[2:3], v[0:1]
	v_mov_b32_e32 v0, v180
	ds_write_b64 v8, v[68:69] offset:6272
	ds_write_b64 v195, v[202:203] offset:8320
	ds_write_b64 v8, v[78:79] offset:6280
	ds_write_b64 v195, v[202:203] offset:8328
	ds_write_b64 v8, v[80:81] offset:6288
	ds_write_b64 v195, v[202:203] offset:8336
	ds_write_b64 v8, v[82:83] offset:6296
	ds_write_b64 v195, v[202:203] offset:8344
	ds_write_b64 v8, v[88:89] offset:41088
	ds_write_b64 v195, v[202:203] offset:43136
	ds_write_b64 v8, v[90:91] offset:41096
	ds_write_b64 v195, v[202:203] offset:43144
	ds_write_b64 v8, v[84:85] offset:41104
	ds_write_b64 v195, v[202:203] offset:43152
	ds_write_b64 v8, v[86:87] offset:41112
	ds_write_b64 v195, v[202:203] offset:43160
	s_waitcnt lgkmcnt(0)
	s_barrier
	s_nop 0
	v_cmp_gt_i32_e32 vcc, s16, v0
	s_and_saveexec_b64 s[2:3], vcc
	s_cbranch_execz .LBB0_499
	v_ashrrev_i32_e32 v1, 31, v0
	v_lshrrev_b32_e32 v1, 27, v1
	v_add_u32_e32 v1, v0, v1
	v_lshrrev_b32_e32 v2, 5, v1
	v_and_b32_e32 v1, 0xffffffe0, v1
	v_sub_u32_e32 v8, v0, v1
	v_mul_lo_u32 v10, v2, s17
	v_ashrrev_i32_e32 v1, 4, v8
	v_add_u32_e32 v0, 0, v10
	v_lshlrev_b32_e32 v124, 3, v8
	v_lshlrev_b32_e32 v1, 3, v1
	v_add3_u32 v112, v0, v124, v1
	v_add_u32_e32 v96, 0x1800, v112
	v_add_u32_e32 v108, 0x2000, v112
	ds_read2_b64 v[0:3], v96 offset0:16 offset1:50
	ds_read2_b64 v[4:7], v96 offset0:84 offset1:118
	ds_read2_b64 v[92:95], v96 offset0:152 offset1:186
	ds_read2_b64 v[96:99], v96 offset0:220 offset1:254
	ds_read2_b64 v[100:103], v108 offset0:32 offset1:66
	ds_read2_b64 v[104:107], v108 offset0:100 offset1:134
	ds_read2_b64 v[108:111], v108 offset0:168 offset1:202
	v_add_u32_e32 v112, 0x2400, v112
	ds_read2_b64 v[112:115], v112 offset0:108 offset1:142
	s_waitcnt lgkmcnt(3)
	v_pk_add_f32 v[116:117], v[0:1], v[100:101]
	v_pk_add_f32 v[0:1], v[0:1], v[100:101] neg_lo:[0,1] neg_hi:[0,1]
	s_waitcnt lgkmcnt(1)
	v_pk_add_f32 v[100:101], v[92:93], v[108:109]
	v_pk_add_f32 v[92:93], v[92:93], v[108:109] neg_lo:[0,1] neg_hi:[0,1]
	s_mov_b32 s31, s28
	v_pk_add_f32 v[118:119], v[0:1], v[92:93] op_sel:[0,1] op_sel_hi:[1,0] neg_hi:[0,1]
	v_pk_add_f32 v[0:1], v[0:1], v[92:93] op_sel:[0,1] op_sel_hi:[1,0] neg_lo:[0,1]
	v_pk_add_f32 v[108:109], v[2:3], v[102:103]
	v_pk_add_f32 v[2:3], v[2:3], v[102:103] neg_lo:[0,1] neg_hi:[0,1]
	v_pk_add_f32 v[102:103], v[94:95], v[110:111]
	v_pk_add_f32 v[94:95], v[94:95], v[110:111] neg_lo:[0,1] neg_hi:[0,1]
	v_pk_add_f32 v[92:93], v[116:117], v[100:101]
	v_xor_b32_e32 v111, 0x80000000, v94
	v_mov_b32_e32 v110, v95
	v_pk_add_f32 v[94:95], v[108:109], v[102:103]
	v_pk_add_f32 v[102:103], v[108:109], v[102:103] neg_lo:[0,1] neg_hi:[0,1]
	v_pk_add_f32 v[108:109], v[4:5], v[104:105]
	v_pk_add_f32 v[4:5], v[4:5], v[104:105] neg_lo:[0,1] neg_hi:[0,1]
	s_waitcnt lgkmcnt(0)
	v_pk_add_f32 v[104:105], v[96:97], v[112:113]
	v_pk_add_f32 v[96:97], v[96:97], v[112:113] neg_lo:[0,1] neg_hi:[0,1]
	v_pk_add_f32 v[100:101], v[116:117], v[100:101] neg_lo:[0,1] neg_hi:[0,1]
	v_pk_add_f32 v[116:117], v[2:3], v[110:111]
	v_pk_add_f32 v[2:3], v[2:3], v[110:111] neg_lo:[0,1] neg_hi:[0,1]
	v_xor_b32_e32 v111, 0x80000000, v96
	v_mov_b32_e32 v110, v97
	v_pk_add_f32 v[96:97], v[108:109], v[104:105]
	v_pk_add_f32 v[104:105], v[108:109], v[104:105] neg_lo:[0,1] neg_hi:[0,1]
	v_pk_add_f32 v[108:109], v[6:7], v[106:107]
	v_pk_add_f32 v[6:7], v[6:7], v[106:107] neg_lo:[0,1] neg_hi:[0,1]
	v_pk_add_f32 v[106:107], v[98:99], v[114:115]
	v_pk_add_f32 v[98:99], v[98:99], v[114:115] neg_lo:[0,1] neg_hi:[0,1]
	v_pk_add_f32 v[112:113], v[4:5], v[110:111]
	v_pk_add_f32 v[4:5], v[4:5], v[110:111] neg_lo:[0,1] neg_hi:[0,1]
	v_xor_b32_e32 v111, 0x80000000, v98
	v_mov_b32_e32 v110, v99
	v_pk_add_f32 v[98:99], v[108:109], v[106:107]
	v_pk_add_f32 v[106:107], v[108:109], v[106:107] neg_lo:[0,1] neg_hi:[0,1]
	v_pk_mul_f32 v[108:109], v[116:117], s[14:15] op_sel_hi:[1,0]
	v_pk_add_f32 v[114:115], v[6:7], v[110:111]
	v_pk_add_f32 v[6:7], v[6:7], v[110:111] neg_lo:[0,1] neg_hi:[0,1]
	v_pk_fma_f32 v[110:111], v[116:117], s[22:23], v[108:109] op_sel:[0,0,1] op_sel_hi:[1,0,0] neg_hi:[0,0,1]
	s_mov_b32 s29, s14
	v_pk_mul_f32 v[108:109], v[102:103], s[24:25] op_sel_hi:[1,0]
	v_add_u32_e32 v10, s18, v10
	v_pk_fma_f32 v[116:117], v[102:103], s[24:25], v[108:109] op_sel:[0,0,1] op_sel_hi:[1,0,0] neg_hi:[0,0,1]
	v_pk_mul_f32 v[108:109], v[2:3], s[22:23] op_sel_hi:[1,0]
	v_pk_fma_f32 v[120:121], v[2:3], s[14:15], v[108:109] op_sel:[0,0,1] op_sel_hi:[1,0,0] neg_hi:[0,0,1]
	v_lshlrev_b32_e32 v8, 7, v8
	v_pk_mul_f32 v[2:3], v[112:113], s[24:25] op_sel_hi:[1,0]
	v_add3_u32 v8, v10, v8, v124
	v_pk_fma_f32 v[108:109], v[112:113], s[24:25], v[2:3] op_sel:[0,0,1] op_sel_hi:[1,0,0] neg_hi:[0,0,1]
	s_nop 0
	v_pk_fma_f32 v[2:3], v[104:105], 0, v[104:105] op_sel:[0,0,1] op_sel_hi:[1,0,0] neg_hi:[0,0,1]
	s_nop 0
	v_pk_mul_f32 v[104:105], v[4:5], s[26:27] op_sel_hi:[1,0]
	s_nop 0
	v_pk_fma_f32 v[112:113], v[4:5], s[26:27], v[104:105] op_sel:[0,0,1] op_sel_hi:[1,0,0] neg_lo:[0,0,1]
	v_pk_mul_f32 v[104:105], v[114:115], s[22:23] op_sel_hi:[1,0]
	v_pk_fma_f32 v[122:123], v[114:115], s[14:15], v[104:105] op_sel:[0,0,1] op_sel_hi:[1,0,0] neg_hi:[0,0,1]
	v_pk_add_f32 v[4:5], v[0:1], v[112:113]
	v_pk_mul_f32 v[104:105], v[106:107], s[26:27] op_sel_hi:[1,0]
	v_pk_add_f32 v[0:1], v[0:1], v[112:113] neg_lo:[0,1] neg_hi:[0,1]
	v_pk_fma_f32 v[114:115], v[106:107], s[26:27], v[104:105] op_sel:[0,0,1] op_sel_hi:[1,0,0] neg_lo:[0,0,1]
	s_nop 0
	v_pk_mul_f32 v[104:105], v[6:7], s[30:31] op_sel:[1,0]
	v_pk_add_f32 v[102:103], v[116:117], v[114:115] neg_lo:[0,1] neg_hi:[0,1]
	v_pk_fma_f32 v[6:7], v[6:7], s[28:29], v[104:105] op_sel_hi:[0,1,1]
	v_pk_add_f32 v[104:105], v[92:93], v[96:97]
	v_pk_add_f32 v[92:93], v[92:93], v[96:97] neg_lo:[0,1] neg_hi:[0,1]
	v_pk_add_f32 v[96:97], v[94:95], v[98:99]
	v_pk_add_f32 v[94:95], v[94:95], v[98:99] neg_lo:[0,1] neg_hi:[0,1]
	s_nop 0
	v_xor_b32_e32 v99, 0x80000000, v94
	v_mov_b32_e32 v98, v95
	v_pk_add_f32 v[94:95], v[104:105], v[96:97]
	v_pk_add_f32 v[106:107], v[92:93], v[98:99]
	v_pk_add_f32 v[96:97], v[104:105], v[96:97] neg_lo:[0,1] neg_hi:[0,1]
	v_pk_add_f32 v[92:93], v[92:93], v[98:99] neg_lo:[0,1] neg_hi:[0,1]
	v_pk_add_f32 v[98:99], v[118:119], v[108:109]
	v_pk_add_f32 v[104:105], v[118:119], v[108:109] neg_lo:[0,1] neg_hi:[0,1]
	v_pk_add_f32 v[108:109], v[110:111], v[122:123]
	v_pk_add_f32 v[110:111], v[110:111], v[122:123] neg_lo:[0,1] neg_hi:[0,1]
	s_nop 0
	v_xor_b32_e32 v119, 0x80000000, v110
	v_mov_b32_e32 v118, v111
	v_pk_add_f32 v[110:111], v[98:99], v[108:109]
	v_pk_add_f32 v[98:99], v[98:99], v[108:109] neg_lo:[0,1] neg_hi:[0,1]
	v_pk_add_f32 v[108:109], v[100:101], v[2:3]
	v_pk_add_f32 v[2:3], v[100:101], v[2:3] neg_lo:[0,1] neg_hi:[0,1]
	v_pk_add_f32 v[100:101], v[116:117], v[114:115]
	v_xor_b32_e32 v115, 0x80000000, v102
	v_mov_b32_e32 v114, v103
	v_pk_add_f32 v[102:103], v[108:109], v[100:101]
	v_pk_add_f32 v[100:101], v[108:109], v[100:101] neg_lo:[0,1] neg_hi:[0,1]
	v_pk_add_f32 v[108:109], v[120:121], v[6:7]
	v_pk_add_f32 v[6:7], v[120:121], v[6:7] neg_lo:[0,1] neg_hi:[0,1]
	v_pk_add_f32 v[122:123], v[104:105], v[118:119]
	v_xor_b32_e32 v113, 0x80000000, v6
	v_mov_b32_e32 v112, v7
	v_pk_add_f32 v[104:105], v[104:105], v[118:119] neg_lo:[0,1] neg_hi:[0,1]
	v_pk_add_f32 v[116:117], v[2:3], v[114:115]
	v_pk_add_f32 v[2:3], v[2:3], v[114:115] neg_lo:[0,1] neg_hi:[0,1]
	v_pk_add_f32 v[6:7], v[4:5], v[108:109]
	v_pk_add_f32 v[114:115], v[0:1], v[112:113]
	v_pk_add_f32 v[4:5], v[4:5], v[108:109] neg_lo:[0,1] neg_hi:[0,1]
	v_pk_add_f32 v[0:1], v[0:1], v[112:113] neg_lo:[0,1] neg_hi:[0,1]
	ds_write2_b64 v8, v[94:95], v[110:111] offset1:1
	ds_write2_b64 v8, v[102:103], v[6:7] offset0:2 offset1:3
	ds_write2_b64 v8, v[106:107], v[122:123] offset0:4 offset1:5
	ds_write2_b64 v8, v[116:117], v[114:115] offset0:6 offset1:7
	ds_write2_b64 v8, v[96:97], v[98:99] offset0:8 offset1:9
	ds_write2_b64 v8, v[100:101], v[4:5] offset0:10 offset1:11
	ds_write2_b64 v8, v[92:93], v[104:105] offset0:12 offset1:13
	ds_write2_b64 v8, v[2:3], v[0:1] offset0:14 offset1:15

.LBB0_501:
	s_or_b64 exec, exec, s[2:3]
	v_mov_b32_e32 v8, v180
	s_waitcnt lgkmcnt(0)
	s_barrier
	s_nop 0
	v_ashrrev_i32_e32 v0, 31, v8
	v_add_u32_sdwa v0, v8, v0 dst_sel:DWORD dst_unused:UNUSED_PAD src0_sel:DWORD src1_sel:BYTE_3
	v_ashrrev_i32_e32 v0, 8, v0
	v_mul_i32_i24_e32 v1, 0x100, v0
	v_sub_u32_e32 v1, v8, v1
	v_add_u32_e32 v7, 0x100, v1
	v_mul_i32_i24_e32 v6, 0x220, v0
	v_ashrrev_i32_e32 v0, 4, v1
	v_lshrrev_b32_e32 v10, 4, v7
	v_add_u32_e32 v4, v0, v1
	v_add3_u32 v0, v6, v1, v10
	v_lshl_add_u32 v0, v0, 3, 0
	v_lshl_add_u32 v2, v1, 3, 0
	ds_read_b64 v[0:1], v0 offset:8320
	ds_read_b64 v[2:3], v2 offset:4224
	v_add_lshl_u32 v94, v4, v6, 3
	v_add_u32_e32 v4, 0, v94
	ds_read_b64 v[4:5], v4 offset:6272
	v_add3_u32 v10, v6, v7, v10
	s_waitcnt lgkmcnt(1)
	v_pk_mul_f32 v[6:7], v[0:1], v[2:3] op_sel:[1,1] op_sel_hi:[1,0]
	s_nop 0
	v_pk_fma_f32 v[92:93], v[0:1], v[2:3], v[6:7] op_sel_hi:[0,1,1] neg_lo:[0,0,1]
	s_waitcnt lgkmcnt(0)
	v_pk_add_f32 v[0:1], v[4:5], v[92:93]
	v_add_u32_e32 v2, s18, v94
	ds_write_b64 v2, v[0:1]
	v_pk_add_f32 v[0:1], v[4:5], v[92:93] neg_lo:[0,1] neg_hi:[0,1]
	v_lshl_add_u32 v2, v10, 3, s18
	ds_write_b64 v2, v[0:1]
	v_add_u32_e32 v0, 0x200, v8
	v_ashrrev_i32_e32 v1, 31, v0
	v_add_u32_sdwa v1, v0, v1 dst_sel:DWORD dst_unused:UNUSED_PAD src0_sel:DWORD src1_sel:BYTE_3
	v_ashrrev_i32_e32 v1, 8, v1
	v_mul_i32_i24_e32 v2, 0x100, v1
	v_sub_u32_e32 v0, v0, v2
	v_add_u32_e32 v7, 0x100, v0
	v_mul_i32_i24_e32 v6, 0x220, v1
	v_ashrrev_i32_e32 v1, 4, v0
	v_lshrrev_b32_e32 v10, 4, v7
	v_add_u32_e32 v4, v1, v0
	v_add3_u32 v1, v6, v0, v10
	v_lshl_add_u32 v1, v1, 3, 0
	v_lshl_add_u32 v2, v0, 3, 0
	ds_read_b64 v[0:1], v1 offset:8320
	ds_read_b64 v[2:3], v2 offset:4224
	v_add_lshl_u32 v94, v4, v6, 3
	v_add_u32_e32 v4, 0, v94
	ds_read_b64 v[4:5], v4 offset:6272
	v_add3_u32 v10, v6, v7, v10
	s_waitcnt lgkmcnt(1)
	v_pk_mul_f32 v[6:7], v[0:1], v[2:3] op_sel:[1,1] op_sel_hi:[1,0]
	s_nop 0
	v_pk_fma_f32 v[92:93], v[0:1], v[2:3], v[6:7] op_sel_hi:[0,1,1] neg_lo:[0,0,1]
	s_waitcnt lgkmcnt(0)
	v_pk_add_f32 v[0:1], v[4:5], v[92:93]
	v_add_u32_e32 v2, s18, v94
	ds_write_b64 v2, v[0:1]
	v_pk_add_f32 v[0:1], v[4:5], v[92:93] neg_lo:[0,1] neg_hi:[0,1]
	v_lshl_add_u32 v2, v10, 3, s18
	ds_write_b64 v2, v[0:1]
	v_add_u32_e32 v0, 0x400, v8
	v_ashrrev_i32_e32 v1, 31, v0
	v_add_u32_sdwa v1, v0, v1 dst_sel:DWORD dst_unused:UNUSED_PAD src0_sel:DWORD src1_sel:BYTE_3
	v_ashrrev_i32_e32 v1, 8, v1
	v_mul_i32_i24_e32 v2, 0x100, v1
	v_sub_u32_e32 v0, v0, v2
	v_add_u32_e32 v7, 0x100, v0
	v_mul_i32_i24_e32 v6, 0x220, v1
	v_ashrrev_i32_e32 v1, 4, v0
	v_lshrrev_b32_e32 v10, 4, v7
	v_add_u32_e32 v4, v1, v0
	v_add3_u32 v1, v6, v0, v10
	v_lshl_add_u32 v1, v1, 3, 0
	v_lshl_add_u32 v2, v0, 3, 0
	ds_read_b64 v[0:1], v1 offset:8320
	ds_read_b64 v[2:3], v2 offset:4224
	v_add_lshl_u32 v94, v4, v6, 3
	v_add_u32_e32 v4, 0, v94
	ds_read_b64 v[4:5], v4 offset:6272
	v_add3_u32 v10, v6, v7, v10
	s_waitcnt lgkmcnt(1)
	v_pk_mul_f32 v[6:7], v[0:1], v[2:3] op_sel:[1,1] op_sel_hi:[1,0]
	s_nop 0
	v_pk_fma_f32 v[92:93], v[0:1], v[2:3], v[6:7] op_sel_hi:[0,1,1] neg_lo:[0,0,1]
	s_waitcnt lgkmcnt(0)
	v_pk_add_f32 v[0:1], v[4:5], v[92:93]
	v_add_u32_e32 v2, s18, v94
	ds_write_b64 v2, v[0:1]
	v_pk_add_f32 v[0:1], v[4:5], v[92:93] neg_lo:[0,1] neg_hi:[0,1]
	v_lshl_add_u32 v2, v10, 3, s18
	ds_write_b64 v2, v[0:1]
	v_add_u32_e32 v0, 0x600, v8
	v_ashrrev_i32_e32 v1, 31, v0
	v_add_u32_sdwa v1, v0, v1 dst_sel:DWORD dst_unused:UNUSED_PAD src0_sel:DWORD src1_sel:BYTE_3
	v_ashrrev_i32_e32 v1, 8, v1
	v_mul_i32_i24_e32 v2, 0x100, v1
	v_sub_u32_e32 v0, v0, v2
	v_add_u32_e32 v7, 0x100, v0
	v_mul_i32_i24_e32 v6, 0x220, v1
	v_ashrrev_i32_e32 v1, 4, v0
	v_lshrrev_b32_e32 v10, 4, v7
	v_add_u32_e32 v4, v1, v0
	v_add3_u32 v1, v6, v0, v10
	v_lshl_add_u32 v1, v1, 3, 0
	v_lshl_add_u32 v2, v0, 3, 0
	ds_read_b64 v[0:1], v1 offset:8320
	ds_read_b64 v[2:3], v2 offset:4224
	v_add_lshl_u32 v94, v4, v6, 3
	v_add_u32_e32 v4, 0, v94
	ds_read_b64 v[4:5], v4 offset:6272
	v_add3_u32 v10, v6, v7, v10
	s_waitcnt lgkmcnt(1)
	v_pk_mul_f32 v[6:7], v[0:1], v[2:3] op_sel:[1,1] op_sel_hi:[1,0]
	s_nop 0
	v_pk_fma_f32 v[92:93], v[0:1], v[2:3], v[6:7] op_sel_hi:[0,1,1] neg_lo:[0,0,1]
	s_waitcnt lgkmcnt(0)
	v_pk_add_f32 v[0:1], v[4:5], v[92:93]
	v_add_u32_e32 v2, s18, v94
	ds_write_b64 v2, v[0:1]
	v_pk_add_f32 v[0:1], v[4:5], v[92:93] neg_lo:[0,1] neg_hi:[0,1]
	v_lshl_add_u32 v2, v10, 3, s18
	ds_write_b64 v2, v[0:1]
	v_add_u32_e32 v0, 0x800, v8
	v_ashrrev_i32_e32 v1, 31, v0
	v_add_u32_sdwa v1, v0, v1 dst_sel:DWORD dst_unused:UNUSED_PAD src0_sel:DWORD src1_sel:BYTE_3
	v_ashrrev_i32_e32 v1, 8, v1
	v_mul_i32_i24_e32 v2, 0x100, v1
	v_sub_u32_e32 v0, v0, v2
	v_add_u32_e32 v7, 0x100, v0
	v_mul_i32_i24_e32 v6, 0x220, v1
	v_ashrrev_i32_e32 v1, 4, v0
	v_lshrrev_b32_e32 v10, 4, v7
	v_add_u32_e32 v4, v1, v0
	v_add3_u32 v1, v6, v0, v10
	v_lshl_add_u32 v1, v1, 3, 0
	v_lshl_add_u32 v2, v0, 3, 0
	ds_read_b64 v[0:1], v1 offset:8320
	ds_read_b64 v[2:3], v2 offset:4224
	v_add_lshl_u32 v94, v4, v6, 3
	v_add_u32_e32 v4, 0, v94
	ds_read_b64 v[4:5], v4 offset:6272
	v_add3_u32 v10, v6, v7, v10
	s_waitcnt lgkmcnt(1)
	v_pk_mul_f32 v[6:7], v[0:1], v[2:3] op_sel:[1,1] op_sel_hi:[1,0]
	s_nop 0
	v_pk_fma_f32 v[92:93], v[0:1], v[2:3], v[6:7] op_sel_hi:[0,1,1] neg_lo:[0,0,1]
	s_waitcnt lgkmcnt(0)
	v_pk_add_f32 v[0:1], v[4:5], v[92:93]
	v_add_u32_e32 v2, s18, v94
	ds_write_b64 v2, v[0:1]
	v_pk_add_f32 v[0:1], v[4:5], v[92:93] neg_lo:[0,1] neg_hi:[0,1]
	v_lshl_add_u32 v2, v10, 3, s18
	ds_write_b64 v2, v[0:1]
	v_add_u32_e32 v0, 0xa00, v8
	v_ashrrev_i32_e32 v1, 31, v0
	v_add_u32_sdwa v1, v0, v1 dst_sel:DWORD dst_unused:UNUSED_PAD src0_sel:DWORD src1_sel:BYTE_3
	v_ashrrev_i32_e32 v1, 8, v1
	v_mul_i32_i24_e32 v2, 0x100, v1
	v_sub_u32_e32 v0, v0, v2
	v_add_u32_e32 v7, 0x100, v0
	v_mul_i32_i24_e32 v6, 0x220, v1
	v_ashrrev_i32_e32 v1, 4, v0
	v_lshrrev_b32_e32 v10, 4, v7
	v_add_u32_e32 v4, v1, v0
	v_add3_u32 v1, v6, v0, v10
	v_lshl_add_u32 v1, v1, 3, 0
	v_lshl_add_u32 v2, v0, 3, 0
	ds_read_b64 v[0:1], v1 offset:8320
	ds_read_b64 v[2:3], v2 offset:4224
	v_add_lshl_u32 v94, v4, v6, 3
	v_add_u32_e32 v4, 0, v94
	ds_read_b64 v[4:5], v4 offset:6272
	v_add3_u32 v10, v6, v7, v10
	s_waitcnt lgkmcnt(1)
	v_pk_mul_f32 v[6:7], v[0:1], v[2:3] op_sel:[1,1] op_sel_hi:[1,0]
	s_nop 0
	v_pk_fma_f32 v[92:93], v[0:1], v[2:3], v[6:7] op_sel_hi:[0,1,1] neg_lo:[0,0,1]
	s_waitcnt lgkmcnt(0)
	v_pk_add_f32 v[0:1], v[4:5], v[92:93]
	v_add_u32_e32 v2, s18, v94
	ds_write_b64 v2, v[0:1]
	v_pk_add_f32 v[0:1], v[4:5], v[92:93] neg_lo:[0,1] neg_hi:[0,1]
	v_lshl_add_u32 v2, v10, 3, s18
	ds_write_b64 v2, v[0:1]
	v_add_u32_e32 v0, 0xc00, v8
	v_ashrrev_i32_e32 v1, 31, v0
	v_add_u32_sdwa v1, v0, v1 dst_sel:DWORD dst_unused:UNUSED_PAD src0_sel:DWORD src1_sel:BYTE_3
	v_ashrrev_i32_e32 v1, 8, v1
	v_mul_i32_i24_e32 v2, 0x100, v1
	v_sub_u32_e32 v0, v0, v2
	v_add_u32_e32 v7, 0x100, v0
	v_mul_i32_i24_e32 v6, 0x220, v1
	v_ashrrev_i32_e32 v1, 4, v0
	v_lshrrev_b32_e32 v10, 4, v7
	v_add_u32_e32 v4, v1, v0
	v_add3_u32 v1, v6, v0, v10
	v_lshl_add_u32 v1, v1, 3, 0
	v_lshl_add_u32 v2, v0, 3, 0
	ds_read_b64 v[0:1], v1 offset:8320
	ds_read_b64 v[2:3], v2 offset:4224
	v_add_lshl_u32 v94, v4, v6, 3
	v_add_u32_e32 v4, 0, v94
	ds_read_b64 v[4:5], v4 offset:6272
	v_add3_u32 v10, v6, v7, v10
	s_waitcnt lgkmcnt(1)
	v_pk_mul_f32 v[6:7], v[0:1], v[2:3] op_sel:[1,1] op_sel_hi:[1,0]
	s_nop 0
	v_pk_fma_f32 v[92:93], v[0:1], v[2:3], v[6:7] op_sel_hi:[0,1,1] neg_lo:[0,0,1]
	s_waitcnt lgkmcnt(0)
	v_pk_add_f32 v[0:1], v[4:5], v[92:93]
	v_add_u32_e32 v2, s18, v94
	ds_write_b64 v2, v[0:1]
	v_pk_add_f32 v[0:1], v[4:5], v[92:93] neg_lo:[0,1] neg_hi:[0,1]
	v_lshl_add_u32 v2, v10, 3, s18
	ds_write_b64 v2, v[0:1]
	v_add_u32_e32 v0, 0xe00, v8
	v_ashrrev_i32_e32 v1, 31, v0
	v_add_u32_sdwa v1, v0, v1 dst_sel:DWORD dst_unused:UNUSED_PAD src0_sel:DWORD src1_sel:BYTE_3
	v_ashrrev_i32_e32 v1, 8, v1
	v_mul_i32_i24_e32 v2, 0x100, v1
	v_sub_u32_e32 v0, v0, v2
	v_add_u32_e32 v7, 0x100, v0
	v_mul_i32_i24_e32 v6, 0x220, v1
	v_ashrrev_i32_e32 v1, 4, v0
	v_lshrrev_b32_e32 v8, 4, v7
	v_add_u32_e32 v4, v1, v0
	v_add3_u32 v1, v6, v0, v8
	v_lshl_add_u32 v1, v1, 3, 0
	v_lshl_add_u32 v2, v0, 3, 0
	ds_read_b64 v[0:1], v1 offset:8320
	ds_read_b64 v[2:3], v2 offset:4224
	v_add_lshl_u32 v10, v4, v6, 3
	v_add_u32_e32 v4, 0, v10
	ds_read_b64 v[4:5], v4 offset:6272
	v_add3_u32 v8, v6, v7, v8
	s_waitcnt lgkmcnt(1)
	v_pk_mul_f32 v[6:7], v[0:1], v[2:3] op_sel:[1,1] op_sel_hi:[1,0]
	s_nop 0
	v_pk_fma_f32 v[92:93], v[0:1], v[2:3], v[6:7] op_sel_hi:[0,1,1] neg_lo:[0,0,1]
	s_waitcnt lgkmcnt(0)
	v_pk_add_f32 v[0:1], v[4:5], v[92:93]
	v_add_u32_e32 v2, s18, v10
	ds_write_b64 v2, v[0:1]
	v_pk_add_f32 v[0:1], v[4:5], v[92:93] neg_lo:[0,1] neg_hi:[0,1]
	v_lshl_add_u32 v2, v8, 3, s18
	v_mov_b32_e32 v4, v180
	ds_write_b64 v2, v[0:1]
	s_waitcnt lgkmcnt(0)
	s_barrier
	s_nop 0
	v_cmp_gt_i32_e32 vcc, s16, v4
	s_and_saveexec_b64 s[2:3], vcc
	s_cbranch_execz .LBB0_503
	v_ashrrev_i32_e32 v5, 31, v4
	v_lshrrev_b32_e32 v5, 27, v5
	v_add_u32_e32 v5, v4, v5
	v_lshrrev_b32_e32 v8, 5, v5
	v_and_b32_e32 v5, 0xffffffe0, v5
	v_sub_u32_e32 v10, v4, v5
	v_mul_lo_u32 v8, v8, s17
	v_ashrrev_i32_e32 v5, 4, v10
	v_add_u32_e32 v4, s18, v8
	v_lshlrev_b32_e32 v98, 3, v10
	v_lshlrev_b32_e32 v5, 3, v5
	v_add3_u32 v99, v4, v98, v5
	v_pk_mul_f32 v[94:95], v[46:47], s[34:35] op_sel_hi:[1,0]
	v_pk_mul_f32 v[96:97], v[48:49], s[34:35] op_sel_hi:[1,0]
	ds_read2_b64 v[46:49], v99 offset1:34
	v_pk_mul_f32 v[92:93], v[44:45], s[34:35] op_sel_hi:[1,0]
	v_pk_mul_f32 v[6:7], v[72:73], s[34:35] op_sel_hi:[1,0]
	v_pk_mul_f32 v[50:51], v[50:51], s[34:35] op_sel_hi:[1,0]
	v_pk_mul_f32 v[2:3], v[74:75], s[34:35] op_sel_hi:[1,0]
	s_waitcnt lgkmcnt(0)
	v_pk_mul_f32 v[4:5], v[92:93], v[46:47] op_sel:[1,1] op_sel_hi:[0,1]
	v_pk_fma_f32 v[44:45], v[92:93], v[46:47], v[4:5] op_sel_hi:[1,0,1] neg_lo:[0,0,1]
	v_pk_mul_f32 v[46:47], v[94:95], v[48:49] op_sel:[1,1] op_sel_hi:[0,1]
	v_pk_fma_f32 v[4:5], v[94:95], v[48:49], v[46:47] op_sel_hi:[1,0,1] neg_lo:[0,0,1]
	v_pk_mul_f32 v[52:53], v[52:53], s[34:35] op_sel_hi:[1,0]
	ds_read2_b64 v[46:49], v99 offset0:68 offset1:102
	v_pk_mul_f32 v[54:55], v[54:55], s[34:35] op_sel_hi:[1,0]
	v_pk_mul_f32 v[0:1], v[76:77], s[34:35] op_sel_hi:[1,0]
	v_pk_mul_f32 v[56:57], v[56:57], s[34:35] op_sel_hi:[1,0]
	v_pk_mul_f32 v[58:59], v[58:59], s[34:35] op_sel_hi:[1,0]
	s_waitcnt lgkmcnt(0)
	v_pk_mul_f32 v[72:73], v[96:97], v[46:47] op_sel:[1,1] op_sel_hi:[0,1]
	v_pk_fma_f32 v[74:75], v[96:97], v[46:47], v[72:73] op_sel_hi:[1,0,1] neg_lo:[0,0,1]
	v_add_u32_e32 v92, 0x800, v99
	v_pk_mul_f32 v[46:47], v[50:51], v[48:49] op_sel:[1,1] op_sel_hi:[0,1]
	v_pk_fma_f32 v[72:73], v[50:51], v[48:49], v[46:47] op_sel_hi:[1,0,1] neg_lo:[0,0,1]
	v_pk_mul_f32 v[60:61], v[60:61], s[34:35] op_sel_hi:[1,0]
	ds_read2_b64 v[46:49], v99 offset0:136 offset1:170
	v_pk_mul_f32 v[62:63], v[62:63], s[34:35] op_sel_hi:[1,0]
	v_pk_mul_f32 v[64:65], v[64:65], s[34:35] op_sel_hi:[1,0]
	v_pk_mul_f32 v[66:67], v[66:67], s[34:35] op_sel_hi:[1,0]
	v_pk_mul_f32 v[70:71], v[70:71], s[34:35] op_sel_hi:[1,0]
	s_waitcnt lgkmcnt(0)
	v_pk_mul_f32 v[50:51], v[52:53], v[46:47] op_sel:[1,1] op_sel_hi:[0,1]
	v_pk_fma_f32 v[76:77], v[52:53], v[46:47], v[50:51] op_sel_hi:[1,0,1] neg_lo:[0,0,1]
	s_mov_b32 s29, s30
	v_pk_mul_f32 v[46:47], v[54:55], v[48:49] op_sel:[1,1] op_sel_hi:[0,1]
	v_pk_fma_f32 v[50:51], v[54:55], v[48:49], v[46:47] op_sel_hi:[1,0,1] neg_lo:[0,0,1]
	v_add_u32_e32 v8, 0, v8
	ds_read2_b64 v[46:49], v99 offset0:204 offset1:238
	v_lshlrev_b32_e32 v10, 7, v10
	v_add3_u32 v8, v8, v10, v98
	v_add_u32_e32 v10, 0x1880, v8
	s_waitcnt lgkmcnt(0)
	v_pk_mul_f32 v[52:53], v[56:57], v[46:47] op_sel:[1,1] op_sel_hi:[0,1]
	v_pk_fma_f32 v[54:55], v[56:57], v[46:47], v[52:53] op_sel_hi:[1,0,1] neg_lo:[0,0,1]
	s_nop 0
	v_pk_mul_f32 v[46:47], v[58:59], v[48:49] op_sel:[1,1] op_sel_hi:[0,1]
	v_pk_fma_f32 v[52:53], v[58:59], v[48:49], v[46:47] op_sel_hi:[1,0,1] neg_lo:[0,0,1]
	s_nop 0
	ds_read2_b64 v[46:49], v92 offset0:16 offset1:50
	s_waitcnt lgkmcnt(0)
	v_pk_mul_f32 v[56:57], v[60:61], v[46:47] op_sel:[1,1] op_sel_hi:[0,1]
	v_pk_fma_f32 v[58:59], v[60:61], v[46:47], v[56:57] op_sel_hi:[1,0,1] neg_lo:[0,0,1]
	s_nop 0
	v_pk_mul_f32 v[46:47], v[62:63], v[48:49] op_sel:[1,1] op_sel_hi:[0,1]
	v_pk_fma_f32 v[56:57], v[62:63], v[48:49], v[46:47] op_sel_hi:[1,0,1] neg_lo:[0,0,1]
	s_nop 0
	ds_read2_b64 v[46:49], v92 offset0:84 offset1:118
	s_waitcnt lgkmcnt(0)
	v_pk_mul_f32 v[60:61], v[64:65], v[46:47] op_sel:[1,1] op_sel_hi:[0,1]
	v_pk_fma_f32 v[62:63], v[64:65], v[46:47], v[60:61] op_sel_hi:[1,0,1] neg_lo:[0,0,1]
	s_nop 0
	v_pk_mul_f32 v[46:47], v[66:67], v[48:49] op_sel:[1,1] op_sel_hi:[0,1]
	v_pk_fma_f32 v[60:61], v[66:67], v[48:49], v[46:47] op_sel_hi:[1,0,1] neg_lo:[0,0,1]
	s_nop 0
	ds_read2_b64 v[46:49], v92 offset0:152 offset1:186
	s_waitcnt lgkmcnt(0)
	v_pk_mul_f32 v[64:65], v[70:71], v[46:47] op_sel:[1,1] op_sel_hi:[0,1]
	v_pk_fma_f32 v[66:67], v[70:71], v[46:47], v[64:65] op_sel_hi:[1,0,1] neg_lo:[0,0,1]
	s_nop 0
	v_pk_mul_f32 v[46:47], v[6:7], v[48:49] op_sel:[1,1] op_sel_hi:[0,1]
	v_pk_fma_f32 v[64:65], v[6:7], v[48:49], v[46:47] op_sel_hi:[1,0,1] neg_lo:[0,0,1]
	ds_read2_b64 v[46:49], v92 offset0:220 offset1:254
	s_waitcnt lgkmcnt(0)
	v_pk_mul_f32 v[6:7], v[2:3], v[46:47] op_sel:[1,1] op_sel_hi:[0,1]
	v_pk_fma_f32 v[70:71], v[2:3], v[46:47], v[6:7] op_sel_hi:[1,0,1] neg_lo:[0,0,1]
	v_pk_add_f32 v[46:47], v[76:77], v[66:67] neg_lo:[0,1] neg_hi:[0,1]
	v_pk_mul_f32 v[2:3], v[0:1], v[48:49] op_sel:[1,1] op_sel_hi:[0,1]
	v_pk_fma_f32 v[6:7], v[0:1], v[48:49], v[2:3] op_sel_hi:[1,0,1] neg_lo:[0,0,1]
	v_pk_add_f32 v[2:3], v[44:45], v[58:59] neg_lo:[0,1] neg_hi:[0,1]
	v_pk_add_f32 v[0:1], v[44:45], v[58:59]
	v_pk_add_f32 v[44:45], v[76:77], v[66:67]
	v_pk_add_f32 v[58:59], v[2:3], v[46:47] op_sel:[0,1] op_sel_hi:[1,0] neg_lo:[0,1]
	v_pk_add_f32 v[2:3], v[2:3], v[46:47] op_sel:[0,1] op_sel_hi:[1,0] neg_hi:[0,1]
	v_pk_add_f32 v[48:49], v[50:51], v[64:65]
	v_pk_add_f32 v[50:51], v[50:51], v[64:65] neg_lo:[0,1] neg_hi:[0,1]
	v_pk_add_f32 v[46:47], v[0:1], v[44:45]
	v_pk_add_f32 v[0:1], v[0:1], v[44:45] neg_lo:[0,1] neg_hi:[0,1]
	v_pk_add_f32 v[44:45], v[4:5], v[56:57]
	v_pk_add_f32 v[4:5], v[4:5], v[56:57] neg_lo:[0,1] neg_hi:[0,1]
	v_xor_b32_e32 v56, 0x80000000, v51
	v_mov_b32_e32 v57, v50
	v_pk_add_f32 v[50:51], v[44:45], v[48:49]
	v_pk_add_f32 v[64:65], v[4:5], v[56:57]
	v_pk_add_f32 v[44:45], v[44:45], v[48:49] neg_lo:[0,1] neg_hi:[0,1]
	v_pk_add_f32 v[4:5], v[4:5], v[56:57] neg_lo:[0,1] neg_hi:[0,1]
	v_pk_add_f32 v[48:49], v[74:75], v[62:63]
	v_pk_add_f32 v[56:57], v[74:75], v[62:63] neg_lo:[0,1] neg_hi:[0,1]
	v_pk_add_f32 v[62:63], v[54:55], v[70:71]
	v_pk_add_f32 v[54:55], v[54:55], v[70:71] neg_lo:[0,1] neg_hi:[0,1]
	s_nop 0
	v_pk_add_f32 v[70:71], v[56:57], v[54:55] op_sel:[0,1] op_sel_hi:[1,0] neg_lo:[0,1]
	v_pk_add_f32 v[56:57], v[56:57], v[54:55] op_sel:[0,1] op_sel_hi:[1,0] neg_hi:[0,1]
	v_pk_add_f32 v[66:67], v[52:53], v[6:7]
	v_pk_add_f32 v[6:7], v[52:53], v[6:7] neg_lo:[0,1] neg_hi:[0,1]
	v_pk_add_f32 v[54:55], v[48:49], v[62:63]
	v_pk_add_f32 v[48:49], v[48:49], v[62:63] neg_lo:[0,1] neg_hi:[0,1]
	v_pk_add_f32 v[62:63], v[72:73], v[60:61]
	v_pk_add_f32 v[60:61], v[72:73], v[60:61] neg_lo:[0,1] neg_hi:[0,1]
	v_pk_add_f32 v[72:73], v[60:61], v[6:7] op_sel:[0,1] op_sel_hi:[1,0] neg_lo:[0,1]
	v_pk_add_f32 v[52:53], v[60:61], v[6:7] op_sel:[0,1] op_sel_hi:[1,0] neg_hi:[0,1]
	v_pk_mul_f32 v[60:61], v[64:65], s[14:15] op_sel_hi:[1,0]
	v_pk_add_f32 v[6:7], v[62:63], v[66:67]
	v_pk_add_f32 v[62:63], v[62:63], v[66:67] neg_lo:[0,1] neg_hi:[0,1]
	v_pk_fma_f32 v[66:67], v[64:65], s[22:23], v[60:61] op_sel:[0,0,1] op_sel_hi:[1,0,0] neg_lo:[0,0,1]
	s_nop 0
	v_pk_mul_f32 v[60:61], v[44:45], s[24:25] op_sel_hi:[1,0]
	s_nop 0
	v_pk_fma_f32 v[64:65], v[44:45], s[24:25], v[60:61] op_sel:[0,0,1] op_sel_hi:[1,0,0] neg_lo:[0,0,1]
	v_pk_mul_f32 v[60:61], v[4:5], s[22:23] op_sel_hi:[1,0]
	v_pk_fma_f32 v[74:75], v[4:5], s[14:15], v[60:61] op_sel:[0,0,1] op_sel_hi:[1,0,0] neg_lo:[0,0,1]
	s_nop 0
	v_pk_mul_f32 v[4:5], v[70:71], s[24:25] op_sel_hi:[1,0]
	s_nop 0
	v_pk_fma_f32 v[60:61], v[70:71], s[24:25], v[4:5] op_sel:[0,0,1] op_sel_hi:[1,0,0] neg_lo:[0,0,1]
	s_nop 0
	v_pk_fma_f32 v[4:5], v[48:49], 0, v[48:49] op_sel:[0,0,1] op_sel_hi:[1,0,0] neg_lo:[0,0,1]
	s_nop 0
	v_pk_mul_f32 v[48:49], v[56:57], s[26:27] op_sel_hi:[1,0]
	s_nop 0
	v_pk_fma_f32 v[70:71], v[56:57], s[26:27], v[48:49] op_sel:[0,0,1] op_sel_hi:[1,0,0] neg_hi:[0,0,1]
	v_pk_mul_f32 v[56:57], v[72:73], s[22:23] op_sel_hi:[1,0]
	v_pk_fma_f32 v[76:77], v[72:73], s[14:15], v[56:57] op_sel:[0,0,1] op_sel_hi:[1,0,0] neg_lo:[0,0,1]
	s_mov_b32 s15, s28
	v_pk_mul_f32 v[56:57], v[62:63], s[26:27] op_sel_hi:[1,0]
	v_pk_add_f32 v[48:49], v[2:3], v[70:71]
	v_pk_fma_f32 v[72:73], v[62:63], s[26:27], v[56:57] op_sel:[0,0,1] op_sel_hi:[1,0,0] neg_hi:[0,0,1]
	v_pk_add_f32 v[2:3], v[2:3], v[70:71] neg_lo:[0,1] neg_hi:[0,1]
	v_pk_mul_f32 v[56:57], v[52:53], s[28:29] op_sel_hi:[0,1]
	v_pk_fma_f32 v[52:53], v[52:53], s[14:15], v[56:57] op_sel:[1,0,0]
	v_pk_add_f32 v[56:57], v[46:47], v[54:55]
	v_pk_add_f32 v[46:47], v[46:47], v[54:55] neg_lo:[0,1] neg_hi:[0,1]
	v_pk_add_f32 v[54:55], v[50:51], v[6:7]
	v_pk_add_f32 v[6:7], v[50:51], v[6:7] neg_lo:[0,1] neg_hi:[0,1]
	v_pk_add_f32 v[44:45], v[64:65], v[72:73] neg_lo:[0,1] neg_hi:[0,1]
	v_xor_b32_e32 v50, 0x80000000, v7
	v_mov_b32_e32 v51, v6
	v_pk_add_f32 v[6:7], v[56:57], v[54:55]
	v_pk_add_f32 v[62:63], v[46:47], v[50:51]
	v_pk_add_f32 v[54:55], v[56:57], v[54:55] neg_lo:[0,1] neg_hi:[0,1]
	v_pk_add_f32 v[46:47], v[46:47], v[50:51] neg_lo:[0,1] neg_hi:[0,1]
	v_pk_add_f32 v[50:51], v[58:59], v[60:61]
	v_pk_add_f32 v[56:57], v[58:59], v[60:61] neg_lo:[0,1] neg_hi:[0,1]
	v_pk_add_f32 v[58:59], v[66:67], v[76:77]
	v_pk_add_f32 v[60:61], v[66:67], v[76:77] neg_lo:[0,1] neg_hi:[0,1]
	s_nop 0
	v_xor_b32_e32 v66, 0x80000000, v61
	v_mov_b32_e32 v67, v60
	v_pk_add_f32 v[60:61], v[50:51], v[58:59]
	v_pk_add_f32 v[50:51], v[50:51], v[58:59] neg_lo:[0,1] neg_hi:[0,1]
	v_pk_add_f32 v[58:59], v[0:1], v[4:5]
	v_pk_add_f32 v[0:1], v[0:1], v[4:5] neg_lo:[0,1] neg_hi:[0,1]
	v_pk_add_f32 v[4:5], v[64:65], v[72:73]
	v_xor_b32_e32 v64, 0x80000000, v45
	v_mov_b32_e32 v65, v44
	v_pk_add_f32 v[44:45], v[58:59], v[4:5]
	v_pk_add_f32 v[4:5], v[58:59], v[4:5] neg_lo:[0,1] neg_hi:[0,1]
	v_pk_add_f32 v[58:59], v[74:75], v[52:53]
	v_pk_add_f32 v[52:53], v[74:75], v[52:53] neg_lo:[0,1] neg_hi:[0,1]
	v_pk_add_f32 v[76:77], v[56:57], v[66:67]
	v_pk_add_f32 v[56:57], v[56:57], v[66:67] neg_lo:[0,1] neg_hi:[0,1]
	v_pk_add_f32 v[66:67], v[0:1], v[64:65]
	v_pk_add_f32 v[0:1], v[0:1], v[64:65] neg_lo:[0,1] neg_hi:[0,1]
	v_xor_b32_e32 v64, 0x80000000, v53
	v_mov_b32_e32 v65, v52
	v_pk_add_f32 v[52:53], v[48:49], v[58:59]
	ds_write2_b64 v10, v[6:7], v[60:61] offset1:1
	v_add_u32_e32 v6, 0x1890, v8
	ds_write2_b64 v6, v[44:45], v[52:53] offset1:1
	v_add_u32_e32 v6, 0x18a0, v8
	v_pk_add_f32 v[70:71], v[2:3], v[64:65]
	ds_write2_b64 v6, v[62:63], v[76:77] offset1:1
	v_add_u32_e32 v6, 0x18b0, v8
	ds_write2_b64 v6, v[66:67], v[70:71] offset1:1
	v_add_u32_e32 v6, 0x18c0, v8
	v_pk_add_f32 v[48:49], v[48:49], v[58:59] neg_lo:[0,1] neg_hi:[0,1]
	ds_write2_b64 v6, v[54:55], v[50:51] offset1:1
	v_add_u32_e32 v6, 0x18d0, v8
	ds_write2_b64 v6, v[4:5], v[48:49] offset1:1
	v_add_u32_e32 v4, 0x18e0, v8
	v_pk_add_f32 v[2:3], v[2:3], v[64:65] neg_lo:[0,1] neg_hi:[0,1]
	ds_write2_b64 v4, v[46:47], v[56:57] offset1:1
	v_add_u32_e32 v4, 0x18f0, v8
	ds_write2_b64 v4, v[0:1], v[2:3] offset1:1
